# row passes P0/P5/P8: norm-weight loads hoisted out of the per-piece loops (VGPR copy in P0/P8, per-wave LDS copy in P5); nt policy on f32 k/v/G output stores of the in-proj epilogue
# speedup vs baseline: 1.0106x; 1.0106x over previous
.LBB0_17:
	s_cmpk_gt_i32 s9, 0x20ff
	v_mov_b32_e32 v73, 0
	v_lshlrev_b32_e32 v70, 3, v237
	s_cbranch_scc1 .LBB0_77
	v_mbcnt_lo_u32_b32 v1, -1, 0
	v_mbcnt_hi_u32_b32 v2, -1, v1
	v_and_b32_e32 v1, 64, v2
	v_add_u32_e32 v3, 64, v1
	v_xor_b32_e32 v1, 1, v2
	v_cmp_lt_i32_e32 vcc, v1, v3
	v_xor_b32_e32 v4, 2, v2
	s_load_dwordx16 s[12:27], s[0:1], 0x30
	v_cndmask_b32_e32 v1, v2, v1, vcc
	v_cmp_lt_i32_e32 vcc, v4, v3
	v_lshlrev_b32_e32 v72, 4, v237
	s_mov_b64 s[2:3], 0x1000
	v_cndmask_b32_e32 v4, v2, v4, vcc
	v_lshlrev_b32_e32 v92, 2, v4
	v_xor_b32_e32 v4, 4, v2
	v_cmp_lt_i32_e32 vcc, v4, v3
	s_waitcnt lgkmcnt(0)
	v_lshl_add_u64 v[74:75], s[12:13], 0, v[72:73]
	v_lshl_add_u64 v[76:77], v[74:75], 0, s[2:3]
	v_cndmask_b32_e32 v4, v2, v4, vcc
	v_lshlrev_b32_e32 v93, 2, v4
	v_xor_b32_e32 v4, 8, v2
	v_cmp_lt_i32_e32 vcc, v4, v3
	s_mov_b64 s[2:3], 0x1400
	v_lshl_add_u64 v[78:79], v[74:75], 0, s[2:3]
	v_cndmask_b32_e32 v4, v2, v4, vcc
	v_lshlrev_b32_e32 v94, 2, v4
	v_xor_b32_e32 v4, 16, v2
	v_cmp_lt_i32_e32 vcc, v4, v3
	s_mov_b64 s[2:3], 0x1800
	v_lshl_add_u64 v[80:81], v[74:75], 0, s[2:3]
	v_cndmask_b32_e32 v4, v2, v4, vcc
	v_lshlrev_b32_e32 v95, 2, v4
	v_xor_b32_e32 v4, 32, v2
	v_cmp_lt_i32_e32 vcc, v4, v3
	s_mov_b64 s[2:3], 0x1c00
	v_mov_b32_e32 v71, v73
	v_cndmask_b32_e32 v2, v2, v4, vcc
	v_lshl_add_u64 v[82:83], v[74:75], 0, s[2:3]
	v_lshlrev_b32_e32 v96, 2, v2
	v_lshl_add_u64 v[2:3], s[68:69], 0, v[70:71]
	s_mov_b64 s[2:3], 0x8c00000
	s_mov_b32 s7, 0
	v_lshlrev_b32_e32 v1, 2, v1
	v_lshl_add_u64 v[84:85], v[2:3], 0, s[2:3]
	v_mov_b32_e32 v71, 0x358637bd
	s_mov_b32 s20, 0xf800000
	v_mov_b32_e32 v97, 0x260
	s_movk_i32 s21, 0x7fff
	s_mov_b32 s22, 0xffff0000
	v_mov_b32_e32 v98, 1
	s_mov_b32 s12, s9
	global_load_dwordx4 v[150:153], v[74:75], off
	global_load_dwordx4 v[154:157], v[74:75], off offset:1024
	global_load_dwordx4 v[158:161], v[74:75], off offset:2048
	global_load_dwordx4 v[162:165], v[74:75], off offset:3072
	global_load_dwordx4 v[166:169], v[76:77], off
	global_load_dwordx4 v[170:173], v[78:79], off
	global_load_dwordx4 v[174:177], v[80:81], off
	global_load_dwordx4 v[178:181], v[82:83], off
	s_branch .LBB0_20

.LBB0_61:
	s_waitcnt vmcnt(0)
	v_mov_b32_e32 v58, v63
	v_mov_b32_e32 v60, v65
	v_mov_b32_e32 v88, v62
	v_pk_mul_f32 v[66:67], v[58:59], v[58:59]
	v_mov_b32_e32 v86, v64
	v_pk_mul_f32 v[68:69], v[60:61], v[60:61]
	v_mul_f32_e32 v58, v51, v51
	v_mul_f32_e32 v60, v53, v53
	v_fmac_f32_e32 v58, v50, v50
	v_fmac_f32_e32 v60, v52, v52
	v_pk_fma_f32 v[66:67], v[88:89], v[88:89], v[66:67]
	v_pk_fma_f32 v[68:69], v[86:87], v[86:87], v[68:69]
	v_add_f32_e32 v58, v58, v60
	v_pk_add_f32 v[66:67], v[66:67], v[68:69]
	v_mul_f32_e32 v60, v43, v43
	v_mul_f32_e32 v68, v45, v45
	v_fmac_f32_e32 v60, v42, v42
	v_fmac_f32_e32 v68, v44, v44
	v_add_f32_e32 v60, v60, v68
	v_add_f32_e32 v58, v58, v60
	v_mul_f32_e32 v60, v31, v31
	v_mul_f32_e32 v86, v33, v33
	v_fmac_f32_e32 v60, v30, v30
	v_fmac_f32_e32 v86, v32, v32
	v_add_f32_e32 v60, v60, v86
	v_pk_mul_f32 v[68:69], v[54:55], v[54:55]
	v_pk_mul_f32 v[90:91], v[56:57], v[56:57]
	v_add_f32_e32 v58, v58, v60
	v_mul_f32_e32 v60, v19, v19
	v_mul_f32_e32 v86, v21, v21
	v_mov_b32_e32 v100, v68
	v_mov_b32_e32 v101, v91
	v_pk_mov_b32 v[68:69], v[68:69], v[90:91] op_sel:[1,0]
	v_fmac_f32_e32 v60, v18, v18
	v_fmac_f32_e32 v86, v20, v20
	v_pk_add_f32 v[68:69], v[68:69], v[100:101]
	v_add_f32_e32 v60, v60, v86
	v_add_f32_e32 v60, v58, v60
	v_mul_f32_e32 v58, v38, v38
	v_mul_f32_e32 v86, v39, v39
	v_pk_add_f32 v[66:67], v[66:67], v[66:67] op_sel:[0,1] op_sel_hi:[1,0]
	v_pk_add_f32 v[68:69], v[68:69], v[68:69] op_sel:[0,1] op_sel_hi:[1,0]
	v_mov_b32_e32 v67, v58
	v_mov_b32_e32 v69, v86
	v_mul_f32_e32 v58, v47, v47
	v_pk_add_f32 v[66:67], v[66:67], v[68:69]
	v_pk_fma_f32 v[68:69], v[46:47], v[46:47], v[58:59] op_sel_hi:[1,1,0]
	v_mul_f32_e32 v58, v49, v49
	v_mul_f32_e32 v88, v40, v40
	v_mul_f32_e32 v99, v41, v41
	v_pk_fma_f32 v[90:91], v[48:49], v[48:49], v[58:59] op_sel_hi:[1,1,0]
	v_mov_b32_e32 v69, v88
	v_mov_b32_e32 v91, v99
	v_pk_add_f32 v[68:69], v[68:69], v[90:91]
	v_pk_mul_f32 v[90:91], v[36:37], v[36:37]
	v_pk_add_f32 v[66:67], v[66:67], v[68:69]
	v_pk_mul_f32 v[68:69], v[34:35], v[34:35]
	v_mov_b32_e32 v101, v91
	v_mov_b32_e32 v100, v68
	v_pk_mov_b32 v[68:69], v[68:69], v[90:91] op_sel:[1,0]
	v_mul_f32_e32 v58, v22, v22
	v_pk_add_f32 v[68:69], v[68:69], v[100:101]
	v_mul_f32_e32 v86, v23, v23
	v_pk_add_f32 v[66:67], v[66:67], v[66:67] op_sel:[0,1] op_sel_hi:[1,0]
	v_pk_add_f32 v[68:69], v[68:69], v[68:69] op_sel:[0,1] op_sel_hi:[1,0]
	v_mov_b32_e32 v67, v58
	v_mov_b32_e32 v69, v86
	v_mul_f32_e32 v58, v27, v27
	v_pk_add_f32 v[66:67], v[66:67], v[68:69]
	v_pk_fma_f32 v[68:69], v[26:27], v[26:27], v[58:59] op_sel_hi:[1,1,0]
	v_mul_f32_e32 v58, v29, v29
	v_mul_f32_e32 v88, v24, v24
	v_mul_f32_e32 v99, v25, v25
	v_pk_fma_f32 v[90:91], v[28:29], v[28:29], v[58:59] op_sel_hi:[1,1,0]
	v_mov_b32_e32 v69, v88
	v_mov_b32_e32 v91, v99
	v_pk_add_f32 v[68:69], v[68:69], v[90:91]
	v_mul_f32_e32 v86, v3, v3
	v_pk_add_f32 v[66:67], v[66:67], v[68:69]
	v_mul_f32_e32 v68, v17, v17
	v_add_f32_e32 v58, v66, v67
	ds_bpermute_b32 v66, v1, v58
	v_mul_f32_e32 v67, v15, v15
	v_fmac_f32_e32 v67, v14, v14
	v_fmac_f32_e32 v68, v16, v16
	v_add_f32_e32 v67, v67, v68
	s_waitcnt lgkmcnt(0)
	v_add_f32_e32 v58, v58, v66
	ds_bpermute_b32 v66, v92, v58
	v_add_f32_e32 v60, v60, v67
	v_mul_f32_e32 v67, v11, v11
	v_mul_f32_e32 v68, v13, v13
	v_fmac_f32_e32 v67, v10, v10
	s_waitcnt lgkmcnt(0)
	v_add_f32_e32 v58, v58, v66
	ds_bpermute_b32 v66, v93, v58
	v_fmac_f32_e32 v68, v12, v12
	v_add_f32_e32 v67, v67, v68
	v_add_f32_e32 v60, v60, v67
	v_mul_f32_e32 v67, v7, v7
	s_waitcnt lgkmcnt(0)
	v_add_f32_e32 v58, v58, v66
	ds_bpermute_b32 v66, v94, v58
	v_mul_f32_e32 v68, v9, v9
	v_fmac_f32_e32 v67, v6, v6
	v_fmac_f32_e32 v68, v8, v8
	v_add_f32_e32 v67, v67, v68
	s_waitcnt lgkmcnt(0)
	v_add_f32_e32 v58, v58, v66
	ds_bpermute_b32 v66, v95, v58
	v_add_f32_e32 v60, v60, v67
	v_mul_f32_e32 v90, v5, v5
	v_fmac_f32_e32 v86, v2, v2
	v_fmac_f32_e32 v90, v4, v4
	s_waitcnt lgkmcnt(0)
	v_add_f32_e32 v58, v58, v66
	v_mov_b32_e32 v66, v150
	v_mov_b32_e32 v67, v151
	v_mov_b32_e32 v68, v152
	v_mov_b32_e32 v69, v153
	ds_bpermute_b32 v88, v96, v58
	v_add_f32_e32 v86, v86, v90
	v_add_f32_e32 v60, v60, v86
	s_ashr_i32 s13, s12, 31
	s_ashr_i32 s11, s10, 31
	s_waitcnt lgkmcnt(0)
	v_add_f32_e32 v58, v58, v88
	ds_bpermute_b32 v88, v1, v60
	v_fmamk_f32 v58, v58, 0x3a000000, v71
	v_mul_f32_e32 v86, 0x4f800000, v58
	v_cmp_gt_f32_e32 vcc, s20, v58
	s_waitcnt lgkmcnt(0)
	v_add_f32_e32 v60, v60, v88
	ds_bpermute_b32 v88, v92, v60
	v_cndmask_b32_e32 v58, v58, v86, vcc
	v_sqrt_f32_e32 v86, v58
	s_waitcnt lgkmcnt(0)
	v_add_f32_e32 v60, v60, v88
	ds_bpermute_b32 v88, v93, v60
	v_add_u32_e32 v90, -1, v86
	v_fma_f32 v91, -v90, v86, v58
	v_cmp_ge_f32_e64 s[2:3], 0, v91
	v_add_u32_e32 v91, 1, v86
	s_waitcnt lgkmcnt(0)
	v_add_f32_e32 v60, v60, v88
	ds_bpermute_b32 v88, v94, v60
	v_cndmask_b32_e64 v90, v86, v90, s[2:3]
	v_fma_f32 v86, -v91, v86, v58
	v_cmp_lt_f32_e64 s[2:3], 0, v86
	s_waitcnt lgkmcnt(0)
	v_add_f32_e32 v60, v60, v88
	v_cndmask_b32_e64 v86, v90, v91, s[2:3]
	v_mul_f32_e32 v90, 0x37800000, v86
	v_cndmask_b32_e32 v86, v86, v90, vcc
	v_cmp_class_f32_e32 vcc, v58, v97
	s_nop 1
	v_cndmask_b32_e32 v58, v86, v58, vcc
	ds_bpermute_b32 v86, v95, v60
	v_div_scale_f32 v88, s[2:3], v58, v58, 1.0
	v_rcp_f32_e32 v90, v88
	s_waitcnt lgkmcnt(0)
	v_add_f32_e32 v60, v60, v86
	ds_bpermute_b32 v86, v96, v60
	v_fma_f32 v91, -v88, v90, 1.0
	v_fmac_f32_e32 v90, v91, v90
	v_div_scale_f32 v91, vcc, 1.0, v58, 1.0
	s_waitcnt lgkmcnt(0)
	v_add_f32_e32 v60, v60, v86
	v_fmamk_f32 v60, v60, 0x3a000000, v71
	v_mul_f32_e32 v86, 0x4f800000, v60
	v_cmp_gt_f32_e64 s[2:3], s20, v60
	v_mul_f32_e32 v99, v91, v90
	v_fma_f32 v100, -v88, v99, v91
	v_cndmask_b32_e64 v60, v60, v86, s[2:3]
	v_sqrt_f32_e32 v86, v60
	v_fmac_f32_e32 v99, v100, v90
	v_fma_f32 v88, -v88, v99, v91
	v_div_fmas_f32 v88, v88, v90, v99
	v_add_u32_e32 v100, -1, v86
	v_fma_f32 v101, -v100, v86, v60
	v_cmp_ge_f32_e64 s[4:5], 0, v101
	v_add_u32_e32 v101, 1, v86
	v_div_fixup_f32 v88, v88, v58, 1.0
	v_cndmask_b32_e64 v100, v86, v100, s[4:5]
	v_fma_f32 v86, -v101, v86, v60
	v_cmp_lt_f32_e64 s[4:5], 0, v86
	v_pk_mul_f32 v[62:63], v[62:63], v[88:89] op_sel_hi:[1,0]
	v_pk_mul_f32 v[64:65], v[64:65], v[88:89] op_sel_hi:[1,0]
	v_cndmask_b32_e64 v86, v100, v101, s[4:5]
	v_mul_f32_e32 v100, 0x37800000, v86
	v_cndmask_b32_e64 v86, v86, v100, s[2:3]
	v_cmp_class_f32_e64 s[2:3], v60, v97
	s_lshl_b64 s[4:5], s[10:11], 12
	v_pk_mul_f32 v[62:63], v[62:63], v[66:67]
	v_cndmask_b32_e64 v60, v86, v60, s[2:3]
	v_div_scale_f32 v86, s[2:3], v60, v60, 1.0
	v_rcp_f32_e32 v100, v86
	v_pk_mul_f32 v[64:65], v[64:65], v[68:69]
	s_lshl_b64 s[2:3], s[12:13], 12
	v_fma_f32 v90, -v86, v100, 1.0
	v_fmac_f32_e32 v100, v90, v100
	v_div_scale_f32 v90, vcc, 1.0, v60, 1.0
	v_mul_f32_e32 v91, v90, v100
	v_fma_f32 v99, -v86, v91, v90
	v_fmac_f32_e32 v91, v99, v100
	v_fma_f32 v58, -v86, v91, v90
	v_and_b32_sdwa v86, v63, v98 dst_sel:DWORD dst_unused:UNUSED_PAD src0_sel:WORD_1 src1_sel:DWORD
	v_div_fmas_f32 v58, v58, v100, v91
	v_add3_u32 v63, v63, v86, s21
	v_and_b32_sdwa v86, v62, v98 dst_sel:DWORD dst_unused:UNUSED_PAD src0_sel:WORD_1 src1_sel:DWORD
	v_add3_u32 v86, v62, v86, s21
	v_div_fixup_f32 v62, v58, v60, 1.0
	v_and_b32_sdwa v60, v64, v98 dst_sel:DWORD dst_unused:UNUSED_PAD src0_sel:WORD_1 src1_sel:DWORD
	v_and_b32_sdwa v58, v65, v98 dst_sel:DWORD dst_unused:UNUSED_PAD src0_sel:WORD_1 src1_sel:DWORD
	v_add3_u32 v60, v64, v60, s21
	v_add3_u32 v58, v65, v58, s21
	v_lshrrev_b32_e32 v60, 16, v60
	v_lshrrev_b32_e32 v64, 16, v86
	v_and_or_b32 v101, v58, s22, v60
	v_cndmask_b32_e64 v58, 0, 1, s[14:15]
	v_lshl_add_u64 v[90:91], v[84:85], 0, s[2:3]
	v_and_or_b32 v100, v63, s22, v64
	v_lshl_add_u64 v[64:65], v[84:85], 0, s[4:5]
	v_cmp_ne_u32_e64 s[2:3], 1, v58
	s_andn2_b64 vcc, exec, s[14:15]
	global_store_dwordx2 v[90:91], v[100:101], off
	s_cbranch_vccnz .LBB0_63
	v_pk_mul_f32 v[50:51], v[50:51], v[62:63] op_sel_hi:[1,0]
	v_pk_mul_f32 v[52:53], v[52:53], v[62:63] op_sel_hi:[1,0]
	v_pk_mul_f32 v[50:51], v[66:67], v[50:51]
	v_pk_mul_f32 v[52:53], v[68:69], v[52:53]
	v_and_b32_sdwa v60, v50, v98 dst_sel:DWORD dst_unused:UNUSED_PAD src0_sel:WORD_1 src1_sel:DWORD
	v_and_b32_sdwa v58, v51, v98 dst_sel:DWORD dst_unused:UNUSED_PAD src0_sel:WORD_1 src1_sel:DWORD
	v_add3_u32 v50, v50, v60, s21
	v_add3_u32 v51, v51, v58, s21
	v_lshrrev_b32_e32 v50, 16, v50
	v_and_b32_sdwa v58, v52, v98 dst_sel:DWORD dst_unused:UNUSED_PAD src0_sel:WORD_1 src1_sel:DWORD
	v_and_or_b32 v50, v51, s22, v50
	v_and_b32_sdwa v51, v53, v98 dst_sel:DWORD dst_unused:UNUSED_PAD src0_sel:WORD_1 src1_sel:DWORD
	v_add3_u32 v52, v52, v58, s21
	v_add3_u32 v51, v53, v51, s21
	v_lshrrev_b32_e32 v52, 16, v52
	v_and_or_b32 v51, v51, s22, v52
	global_store_dwordx2 v[64:65], v[50:51], off
.LBB0_63:
	v_mov_b32_e32 v50, v154
	v_mov_b32_e32 v51, v155
	v_mov_b32_e32 v52, v156
	v_mov_b32_e32 v53, v157
	v_mov_b32_e32 v58, v89
	v_mov_b32_e32 v89, v88
	v_mov_b32_e32 v60, v87
	v_pk_mul_f32 v[58:59], v[58:59], v[88:89]
	v_pk_mul_f32 v[60:61], v[60:61], v[88:89]
	s_and_b64 vcc, exec, s[2:3]
	v_pk_mul_f32 v[58:59], v[58:59], v[50:51]
	v_pk_mul_f32 v[60:61], v[60:61], v[52:53]
	v_and_b32_sdwa v66, v58, v98 dst_sel:DWORD dst_unused:UNUSED_PAD src0_sel:WORD_1 src1_sel:DWORD
	v_and_b32_sdwa v68, v60, v98 dst_sel:DWORD dst_unused:UNUSED_PAD src0_sel:WORD_1 src1_sel:DWORD
	v_and_b32_sdwa v63, v59, v98 dst_sel:DWORD dst_unused:UNUSED_PAD src0_sel:WORD_1 src1_sel:DWORD
	v_and_b32_sdwa v67, v61, v98 dst_sel:DWORD dst_unused:UNUSED_PAD src0_sel:WORD_1 src1_sel:DWORD
	v_add3_u32 v58, v58, v66, s21
	v_add3_u32 v60, v60, v68, s21
	v_add3_u32 v59, v59, v63, s21
	v_add3_u32 v61, v61, v67, s21
	v_lshrrev_b32_e32 v58, 16, v58
	v_lshrrev_b32_e32 v60, 16, v60
	v_and_or_b32 v58, v59, s22, v58
	v_and_or_b32 v59, v61, s22, v60
	global_store_dwordx2 v[90:91], v[58:59], off offset:512
	s_cbranch_vccnz .LBB0_65
	v_pk_mul_f32 v[42:43], v[42:43], v[62:63] op_sel_hi:[1,0]
	v_pk_mul_f32 v[44:45], v[44:45], v[62:63] op_sel_hi:[1,0]
	v_pk_mul_f32 v[42:43], v[42:43], v[50:51]
	v_pk_mul_f32 v[44:45], v[44:45], v[52:53]
	v_and_b32_sdwa v51, v42, v98 dst_sel:DWORD dst_unused:UNUSED_PAD src0_sel:WORD_1 src1_sel:DWORD
	v_and_b32_sdwa v50, v43, v98 dst_sel:DWORD dst_unused:UNUSED_PAD src0_sel:WORD_1 src1_sel:DWORD
	v_add3_u32 v42, v42, v51, s21
	v_add3_u32 v43, v43, v50, s21
	v_lshrrev_b32_e32 v42, 16, v42
	v_and_b32_sdwa v50, v44, v98 dst_sel:DWORD dst_unused:UNUSED_PAD src0_sel:WORD_1 src1_sel:DWORD
	v_and_or_b32 v42, v43, s22, v42
	v_and_b32_sdwa v43, v45, v98 dst_sel:DWORD dst_unused:UNUSED_PAD src0_sel:WORD_1 src1_sel:DWORD
	v_add3_u32 v44, v44, v50, s21
	v_add3_u32 v43, v45, v43, s21
	v_lshrrev_b32_e32 v44, 16, v44
	v_and_or_b32 v43, v43, s22, v44
	global_store_dwordx2 v[64:65], v[42:43], off offset:512
.LBB0_65:
	v_mov_b32_e32 v42, v158
	v_mov_b32_e32 v43, v159
	v_mov_b32_e32 v44, v160
	v_mov_b32_e32 v45, v161
	v_pk_mul_f32 v[50:51], v[54:55], v[88:89]
	v_pk_mul_f32 v[52:53], v[56:57], v[88:89]
	s_and_b64 vcc, exec, s[2:3]
	v_pk_mul_f32 v[50:51], v[50:51], v[42:43]
	v_pk_mul_f32 v[52:53], v[52:53], v[44:45]
	v_and_b32_sdwa v55, v50, v98 dst_sel:DWORD dst_unused:UNUSED_PAD src0_sel:WORD_1 src1_sel:DWORD
	v_and_b32_sdwa v57, v52, v98 dst_sel:DWORD dst_unused:UNUSED_PAD src0_sel:WORD_1 src1_sel:DWORD
	v_and_b32_sdwa v54, v51, v98 dst_sel:DWORD dst_unused:UNUSED_PAD src0_sel:WORD_1 src1_sel:DWORD
	v_and_b32_sdwa v56, v53, v98 dst_sel:DWORD dst_unused:UNUSED_PAD src0_sel:WORD_1 src1_sel:DWORD
	v_add3_u32 v50, v50, v55, s21
	v_add3_u32 v52, v52, v57, s21
	v_add3_u32 v51, v51, v54, s21
	v_add3_u32 v53, v53, v56, s21
	v_lshrrev_b32_e32 v50, 16, v50
	v_lshrrev_b32_e32 v52, 16, v52
	v_and_or_b32 v50, v51, s22, v50
	v_and_or_b32 v51, v53, s22, v52
	global_store_dwordx2 v[90:91], v[50:51], off offset:1024
	s_cbranch_vccnz .LBB0_67
	v_pk_mul_f32 v[30:31], v[30:31], v[62:63] op_sel_hi:[1,0]
	v_pk_mul_f32 v[32:33], v[32:33], v[62:63] op_sel_hi:[1,0]
	v_pk_mul_f32 v[30:31], v[30:31], v[42:43]
	v_pk_mul_f32 v[32:33], v[32:33], v[44:45]
	v_and_b32_sdwa v43, v30, v98 dst_sel:DWORD dst_unused:UNUSED_PAD src0_sel:WORD_1 src1_sel:DWORD
	v_and_b32_sdwa v42, v31, v98 dst_sel:DWORD dst_unused:UNUSED_PAD src0_sel:WORD_1 src1_sel:DWORD
	v_add3_u32 v30, v30, v43, s21
	v_add3_u32 v31, v31, v42, s21
	v_lshrrev_b32_e32 v30, 16, v30
	v_and_b32_sdwa v42, v32, v98 dst_sel:DWORD dst_unused:UNUSED_PAD src0_sel:WORD_1 src1_sel:DWORD
	v_and_or_b32 v30, v31, s22, v30
	v_and_b32_sdwa v31, v33, v98 dst_sel:DWORD dst_unused:UNUSED_PAD src0_sel:WORD_1 src1_sel:DWORD
	v_add3_u32 v32, v32, v42, s21
	v_add3_u32 v31, v33, v31, s21
	v_lshrrev_b32_e32 v32, 16, v32
	v_and_or_b32 v31, v31, s22, v32
	global_store_dwordx2 v[64:65], v[30:31], off offset:1024
.LBB0_67:
	v_mov_b32_e32 v30, v162
	v_mov_b32_e32 v31, v163
	v_mov_b32_e32 v32, v164
	v_mov_b32_e32 v33, v165
	v_pk_mul_f32 v[42:43], v[46:47], v[88:89]
	v_pk_mul_f32 v[44:45], v[48:49], v[88:89]
	s_and_b64 vcc, exec, s[2:3]
	v_pk_mul_f32 v[42:43], v[42:43], v[30:31]
	v_pk_mul_f32 v[44:45], v[44:45], v[32:33]
	v_and_b32_sdwa v47, v42, v98 dst_sel:DWORD dst_unused:UNUSED_PAD src0_sel:WORD_1 src1_sel:DWORD
	v_and_b32_sdwa v49, v44, v98 dst_sel:DWORD dst_unused:UNUSED_PAD src0_sel:WORD_1 src1_sel:DWORD
	v_and_b32_sdwa v46, v43, v98 dst_sel:DWORD dst_unused:UNUSED_PAD src0_sel:WORD_1 src1_sel:DWORD
	v_and_b32_sdwa v48, v45, v98 dst_sel:DWORD dst_unused:UNUSED_PAD src0_sel:WORD_1 src1_sel:DWORD
	v_add3_u32 v42, v42, v47, s21
	v_add3_u32 v44, v44, v49, s21
	v_add3_u32 v43, v43, v46, s21
	v_add3_u32 v45, v45, v48, s21
	v_lshrrev_b32_e32 v42, 16, v42
	v_lshrrev_b32_e32 v44, 16, v44
	v_and_or_b32 v42, v43, s22, v42
	v_and_or_b32 v43, v45, s22, v44
	global_store_dwordx2 v[90:91], v[42:43], off offset:1536
	s_cbranch_vccnz .LBB0_69
	v_pk_mul_f32 v[18:19], v[18:19], v[62:63] op_sel_hi:[1,0]
	v_pk_mul_f32 v[20:21], v[20:21], v[62:63] op_sel_hi:[1,0]
	v_pk_mul_f32 v[18:19], v[18:19], v[30:31]
	v_pk_mul_f32 v[20:21], v[20:21], v[32:33]
	v_and_b32_sdwa v31, v18, v98 dst_sel:DWORD dst_unused:UNUSED_PAD src0_sel:WORD_1 src1_sel:DWORD
	v_and_b32_sdwa v30, v19, v98 dst_sel:DWORD dst_unused:UNUSED_PAD src0_sel:WORD_1 src1_sel:DWORD
	v_add3_u32 v18, v18, v31, s21
	v_add3_u32 v19, v19, v30, s21
	v_lshrrev_b32_e32 v18, 16, v18
	v_and_b32_sdwa v30, v20, v98 dst_sel:DWORD dst_unused:UNUSED_PAD src0_sel:WORD_1 src1_sel:DWORD
	v_and_or_b32 v18, v19, s22, v18
	v_and_b32_sdwa v19, v21, v98 dst_sel:DWORD dst_unused:UNUSED_PAD src0_sel:WORD_1 src1_sel:DWORD
	v_add3_u32 v20, v20, v30, s21
	v_add3_u32 v19, v21, v19, s21
	v_lshrrev_b32_e32 v20, 16, v20
	v_and_or_b32 v19, v19, s22, v20
	global_store_dwordx2 v[64:65], v[18:19], off offset:1536
.LBB0_69:
	v_mov_b32_e32 v18, v166
	v_mov_b32_e32 v19, v167
	v_mov_b32_e32 v20, v168
	v_mov_b32_e32 v21, v169
	v_pk_mul_f32 v[30:31], v[38:39], v[88:89]
	v_pk_mul_f32 v[32:33], v[40:41], v[88:89]
	s_and_b64 vcc, exec, s[2:3]
	v_pk_mul_f32 v[30:31], v[30:31], v[18:19]
	v_pk_mul_f32 v[32:33], v[32:33], v[20:21]
	v_and_b32_sdwa v39, v30, v98 dst_sel:DWORD dst_unused:UNUSED_PAD src0_sel:WORD_1 src1_sel:DWORD
	v_and_b32_sdwa v41, v32, v98 dst_sel:DWORD dst_unused:UNUSED_PAD src0_sel:WORD_1 src1_sel:DWORD
	v_and_b32_sdwa v38, v31, v98 dst_sel:DWORD dst_unused:UNUSED_PAD src0_sel:WORD_1 src1_sel:DWORD
	v_and_b32_sdwa v40, v33, v98 dst_sel:DWORD dst_unused:UNUSED_PAD src0_sel:WORD_1 src1_sel:DWORD
	v_add3_u32 v30, v30, v39, s21
	v_add3_u32 v32, v32, v41, s21
	v_add3_u32 v31, v31, v38, s21
	v_add3_u32 v33, v33, v40, s21
	v_lshrrev_b32_e32 v30, 16, v30
	v_lshrrev_b32_e32 v32, 16, v32
	v_and_or_b32 v30, v31, s22, v30
	v_and_or_b32 v31, v33, s22, v32
	global_store_dwordx2 v[90:91], v[30:31], off offset:2048
	s_cbranch_vccnz .LBB0_71
	v_pk_mul_f32 v[14:15], v[14:15], v[62:63] op_sel_hi:[1,0]
	v_pk_mul_f32 v[16:17], v[16:17], v[62:63] op_sel_hi:[1,0]
	v_pk_mul_f32 v[14:15], v[14:15], v[18:19]
	v_pk_mul_f32 v[16:17], v[16:17], v[20:21]
	v_and_b32_sdwa v19, v14, v98 dst_sel:DWORD dst_unused:UNUSED_PAD src0_sel:WORD_1 src1_sel:DWORD
	v_and_b32_sdwa v18, v15, v98 dst_sel:DWORD dst_unused:UNUSED_PAD src0_sel:WORD_1 src1_sel:DWORD
	v_add3_u32 v14, v14, v19, s21
	v_add3_u32 v15, v15, v18, s21
	v_lshrrev_b32_e32 v14, 16, v14
	v_and_b32_sdwa v18, v16, v98 dst_sel:DWORD dst_unused:UNUSED_PAD src0_sel:WORD_1 src1_sel:DWORD
	v_and_or_b32 v14, v15, s22, v14
	v_and_b32_sdwa v15, v17, v98 dst_sel:DWORD dst_unused:UNUSED_PAD src0_sel:WORD_1 src1_sel:DWORD
	v_add3_u32 v16, v16, v18, s21
	v_add3_u32 v15, v17, v15, s21
	v_lshrrev_b32_e32 v16, 16, v16
	v_and_or_b32 v15, v15, s22, v16
	global_store_dwordx2 v[64:65], v[14:15], off offset:2048
.LBB0_71:
	v_mov_b32_e32 v14, v170
	v_mov_b32_e32 v15, v171
	v_mov_b32_e32 v16, v172
	v_mov_b32_e32 v17, v173
	v_pk_mul_f32 v[18:19], v[34:35], v[88:89]
	v_pk_mul_f32 v[20:21], v[36:37], v[88:89]
	s_and_b64 vcc, exec, s[2:3]
	v_pk_mul_f32 v[18:19], v[18:19], v[14:15]
	v_pk_mul_f32 v[20:21], v[20:21], v[16:17]
	v_and_b32_sdwa v31, v18, v98 dst_sel:DWORD dst_unused:UNUSED_PAD src0_sel:WORD_1 src1_sel:DWORD
	v_and_b32_sdwa v33, v20, v98 dst_sel:DWORD dst_unused:UNUSED_PAD src0_sel:WORD_1 src1_sel:DWORD
	v_and_b32_sdwa v30, v19, v98 dst_sel:DWORD dst_unused:UNUSED_PAD src0_sel:WORD_1 src1_sel:DWORD
	v_and_b32_sdwa v32, v21, v98 dst_sel:DWORD dst_unused:UNUSED_PAD src0_sel:WORD_1 src1_sel:DWORD
	v_add3_u32 v18, v18, v31, s21
	v_add3_u32 v20, v20, v33, s21
	v_add3_u32 v19, v19, v30, s21
	v_add3_u32 v21, v21, v32, s21
	v_lshrrev_b32_e32 v18, 16, v18
	v_lshrrev_b32_e32 v20, 16, v20
	v_and_or_b32 v18, v19, s22, v18
	v_and_or_b32 v19, v21, s22, v20
	global_store_dwordx2 v[90:91], v[18:19], off offset:2560
	s_cbranch_vccnz .LBB0_73
	v_pk_mul_f32 v[10:11], v[10:11], v[62:63] op_sel_hi:[1,0]
	v_pk_mul_f32 v[12:13], v[12:13], v[62:63] op_sel_hi:[1,0]
	v_pk_mul_f32 v[10:11], v[10:11], v[14:15]
	v_pk_mul_f32 v[12:13], v[12:13], v[16:17]
	v_and_b32_sdwa v15, v10, v98 dst_sel:DWORD dst_unused:UNUSED_PAD src0_sel:WORD_1 src1_sel:DWORD
	v_and_b32_sdwa v14, v11, v98 dst_sel:DWORD dst_unused:UNUSED_PAD src0_sel:WORD_1 src1_sel:DWORD
	v_add3_u32 v10, v10, v15, s21
	v_add3_u32 v11, v11, v14, s21
	v_lshrrev_b32_e32 v10, 16, v10
	v_and_b32_sdwa v14, v12, v98 dst_sel:DWORD dst_unused:UNUSED_PAD src0_sel:WORD_1 src1_sel:DWORD
	v_and_or_b32 v10, v11, s22, v10
	v_and_b32_sdwa v11, v13, v98 dst_sel:DWORD dst_unused:UNUSED_PAD src0_sel:WORD_1 src1_sel:DWORD
	v_add3_u32 v12, v12, v14, s21
	v_add3_u32 v11, v13, v11, s21
	v_lshrrev_b32_e32 v12, 16, v12
	v_and_or_b32 v11, v11, s22, v12
	global_store_dwordx2 v[64:65], v[10:11], off offset:2560
.LBB0_73:
	v_mov_b32_e32 v10, v174
	v_mov_b32_e32 v11, v175
	v_mov_b32_e32 v12, v176
	v_mov_b32_e32 v13, v177
	v_pk_mul_f32 v[14:15], v[26:27], v[88:89]
	v_pk_mul_f32 v[16:17], v[28:29], v[88:89]
	s_and_b64 vcc, exec, s[2:3]
	v_pk_mul_f32 v[14:15], v[14:15], v[10:11]
	v_pk_mul_f32 v[16:17], v[16:17], v[12:13]
	v_and_b32_sdwa v19, v14, v98 dst_sel:DWORD dst_unused:UNUSED_PAD src0_sel:WORD_1 src1_sel:DWORD
	v_and_b32_sdwa v21, v16, v98 dst_sel:DWORD dst_unused:UNUSED_PAD src0_sel:WORD_1 src1_sel:DWORD
	v_and_b32_sdwa v18, v15, v98 dst_sel:DWORD dst_unused:UNUSED_PAD src0_sel:WORD_1 src1_sel:DWORD
	v_and_b32_sdwa v20, v17, v98 dst_sel:DWORD dst_unused:UNUSED_PAD src0_sel:WORD_1 src1_sel:DWORD
	v_add3_u32 v14, v14, v19, s21
	v_add3_u32 v16, v16, v21, s21
	v_add3_u32 v15, v15, v18, s21
	v_add3_u32 v17, v17, v20, s21
	v_lshrrev_b32_e32 v14, 16, v14
	v_lshrrev_b32_e32 v16, 16, v16
	v_and_or_b32 v14, v15, s22, v14
	v_and_or_b32 v15, v17, s22, v16
	global_store_dwordx2 v[90:91], v[14:15], off offset:3072
	s_cbranch_vccnz .LBB0_75
	v_pk_mul_f32 v[6:7], v[6:7], v[62:63] op_sel_hi:[1,0]
	v_pk_mul_f32 v[8:9], v[8:9], v[62:63] op_sel_hi:[1,0]
	v_pk_mul_f32 v[6:7], v[6:7], v[10:11]
	v_pk_mul_f32 v[8:9], v[8:9], v[12:13]
	v_and_b32_sdwa v11, v6, v98 dst_sel:DWORD dst_unused:UNUSED_PAD src0_sel:WORD_1 src1_sel:DWORD
	v_and_b32_sdwa v10, v7, v98 dst_sel:DWORD dst_unused:UNUSED_PAD src0_sel:WORD_1 src1_sel:DWORD
	v_add3_u32 v6, v6, v11, s21
	v_add3_u32 v7, v7, v10, s21
	v_lshrrev_b32_e32 v6, 16, v6
	v_and_b32_sdwa v10, v8, v98 dst_sel:DWORD dst_unused:UNUSED_PAD src0_sel:WORD_1 src1_sel:DWORD
	v_and_or_b32 v6, v7, s22, v6
	v_and_b32_sdwa v7, v9, v98 dst_sel:DWORD dst_unused:UNUSED_PAD src0_sel:WORD_1 src1_sel:DWORD
	v_add3_u32 v8, v8, v10, s21
	v_add3_u32 v7, v9, v7, s21
	v_lshrrev_b32_e32 v8, 16, v8
	v_and_or_b32 v7, v7, s22, v8
	global_store_dwordx2 v[64:65], v[6:7], off offset:3072
.LBB0_75:
	v_mov_b32_e32 v6, v178
	v_mov_b32_e32 v7, v179
	v_mov_b32_e32 v8, v180
	v_mov_b32_e32 v9, v181
	v_pk_mul_f32 v[10:11], v[22:23], v[88:89]
	v_pk_mul_f32 v[12:13], v[24:25], v[88:89]
	s_and_b64 vcc, exec, s[2:3]
	v_pk_mul_f32 v[10:11], v[10:11], v[6:7]
	v_pk_mul_f32 v[12:13], v[12:13], v[8:9]
	v_and_b32_sdwa v15, v10, v98 dst_sel:DWORD dst_unused:UNUSED_PAD src0_sel:WORD_1 src1_sel:DWORD
	v_and_b32_sdwa v17, v12, v98 dst_sel:DWORD dst_unused:UNUSED_PAD src0_sel:WORD_1 src1_sel:DWORD
	v_and_b32_sdwa v14, v11, v98 dst_sel:DWORD dst_unused:UNUSED_PAD src0_sel:WORD_1 src1_sel:DWORD
	v_and_b32_sdwa v16, v13, v98 dst_sel:DWORD dst_unused:UNUSED_PAD src0_sel:WORD_1 src1_sel:DWORD
	v_add3_u32 v10, v10, v15, s21
	v_add3_u32 v12, v12, v17, s21
	v_add3_u32 v11, v11, v14, s21
	v_add3_u32 v13, v13, v16, s21
	v_lshrrev_b32_e32 v10, 16, v10
	v_lshrrev_b32_e32 v12, 16, v12
	v_and_or_b32 v10, v11, s22, v10
	v_and_or_b32 v11, v13, s22, v12
	global_store_dwordx2 v[90:91], v[10:11], off offset:3584
	s_cbranch_vccnz .LBB0_19
	v_pk_mul_f32 v[2:3], v[2:3], v[62:63] op_sel_hi:[1,0]
	v_pk_mul_f32 v[4:5], v[4:5], v[62:63] op_sel_hi:[1,0]
	v_pk_mul_f32 v[2:3], v[2:3], v[6:7]
	v_pk_mul_f32 v[4:5], v[4:5], v[8:9]
	v_and_b32_sdwa v7, v2, v98 dst_sel:DWORD dst_unused:UNUSED_PAD src0_sel:WORD_1 src1_sel:DWORD
	v_and_b32_sdwa v6, v3, v98 dst_sel:DWORD dst_unused:UNUSED_PAD src0_sel:WORD_1 src1_sel:DWORD
	v_add3_u32 v2, v2, v7, s21
	v_add3_u32 v3, v3, v6, s21
	v_lshrrev_b32_e32 v2, 16, v2
	v_and_b32_sdwa v6, v4, v98 dst_sel:DWORD dst_unused:UNUSED_PAD src0_sel:WORD_1 src1_sel:DWORD
	v_and_or_b32 v2, v3, s22, v2
	v_and_b32_sdwa v3, v5, v98 dst_sel:DWORD dst_unused:UNUSED_PAD src0_sel:WORD_1 src1_sel:DWORD
	v_add3_u32 v4, v4, v6, s21
	v_add3_u32 v3, v5, v3, s21
	v_lshrrev_b32_e32 v4, 16, v4
	v_and_or_b32 v3, v3, s22, v4
	global_store_dwordx2 v[64:65], v[2:3], off offset:3584
	s_branch .LBB0_19

.LBB0_167:
	v_add_u32_e32 v134, s21, v166
	v_ashrrev_i32_e32 v135, 31, v134
	v_lshl_add_u64 v[132:133], v[134:135], 2, v[132:133]
	global_store_dwordx4 v[132:133], v[126:129], off nt
	global_store_dwordx4 v[132:133], v[122:125], off offset:16 nt

.LBB0_180:
	v_add_u32_e32 v130, s21, v144
	v_ashrrev_i32_e32 v131, 31, v130
	v_lshl_add_u64 v[130:131], v[130:131], 2, v[134:135]
	global_store_dwordx4 v[130:131], v[118:121], off nt
	global_store_dwordx4 v[130:131], v[114:117], off offset:16 nt

.LBB0_193:
	v_add_u32_e32 v136, s21, v166
	v_ashrrev_i32_e32 v137, 31, v136
	v_lshl_add_u64 v[134:135], v[136:137], 2, v[134:135]
	global_store_dwordx4 v[134:135], v[110:113], off nt
	global_store_dwordx4 v[134:135], v[106:109], off offset:16 nt

.LBB0_206:
	v_add_u32_e32 v130, s21, v144
	v_ashrrev_i32_e32 v131, 31, v130
	v_lshl_add_u64 v[130:131], v[130:131], 2, v[132:133]
	global_store_dwordx4 v[130:131], v[102:105], off nt
	global_store_dwordx4 v[130:131], v[98:101], off offset:16 nt

.LBB0_219:
	v_add_u32_e32 v136, s21, v166
	v_ashrrev_i32_e32 v137, 31, v136
	v_lshl_add_u64 v[134:135], v[136:137], 2, v[134:135]
	global_store_dwordx4 v[134:135], v[94:97], off nt
	global_store_dwordx4 v[134:135], v[90:93], off offset:16 nt

.LBB0_232:
	v_add_u32_e32 v130, s21, v144
	v_ashrrev_i32_e32 v131, 31, v130
	v_lshl_add_u64 v[130:131], v[130:131], 2, v[132:133]
	global_store_dwordx4 v[130:131], v[86:89], off nt
	global_store_dwordx4 v[130:131], v[82:85], off offset:16 nt

.LBB0_245:
	v_add_u32_e32 v136, s21, v166
	v_ashrrev_i32_e32 v137, 31, v136
	v_lshl_add_u64 v[134:135], v[136:137], 2, v[134:135]
	global_store_dwordx4 v[134:135], v[78:81], off nt
	global_store_dwordx4 v[134:135], v[74:77], off offset:16 nt

.LBB0_258:
	v_add_u32_e32 v130, s21, v144
	v_ashrrev_i32_e32 v131, 31, v130
	v_lshl_add_u64 v[130:131], v[130:131], 2, v[132:133]
	global_store_dwordx4 v[130:131], v[70:73], off nt
	global_store_dwordx4 v[130:131], v[66:69], off offset:16 nt

.LBB0_271:
	v_add_u32_e32 v136, s21, v166
	v_ashrrev_i32_e32 v137, 31, v136
	v_lshl_add_u64 v[134:135], v[136:137], 2, v[134:135]
	global_store_dwordx4 v[134:135], v[62:65], off nt
	global_store_dwordx4 v[134:135], v[58:61], off offset:16 nt

.LBB0_284:
	v_add_u32_e32 v130, s21, v144
	v_ashrrev_i32_e32 v131, 31, v130
	v_lshl_add_u64 v[130:131], v[130:131], 2, v[136:137]
	global_store_dwordx4 v[130:131], v[54:57], off nt
	global_store_dwordx4 v[130:131], v[50:53], off offset:16 nt

.LBB0_297:
	v_add_u32_e32 v136, s21, v166
	v_ashrrev_i32_e32 v137, 31, v136
	v_lshl_add_u64 v[134:135], v[136:137], 2, v[134:135]
	global_store_dwordx4 v[134:135], v[46:49], off nt
	global_store_dwordx4 v[134:135], v[42:45], off offset:16 nt

.LBB0_310:
	v_add_u32_e32 v130, s21, v144
	v_ashrrev_i32_e32 v131, 31, v130
	v_lshl_add_u64 v[130:131], v[130:131], 2, v[136:137]
	global_store_dwordx4 v[130:131], v[38:41], off nt
	global_store_dwordx4 v[130:131], v[34:37], off offset:16 nt

.LBB0_323:
	v_add_u32_e32 v136, s21, v166
	v_ashrrev_i32_e32 v137, 31, v136
	v_lshl_add_u64 v[134:135], v[136:137], 2, v[134:135]
	global_store_dwordx4 v[134:135], v[30:33], off nt
	global_store_dwordx4 v[134:135], v[26:29], off offset:16 nt

.LBB0_336:
	v_add_u32_e32 v130, s21, v144
	v_ashrrev_i32_e32 v131, 31, v130
	v_lshl_add_u64 v[130:131], v[130:131], 2, v[136:137]
	global_store_dwordx4 v[130:131], v[22:25], off nt
	global_store_dwordx4 v[130:131], v[18:21], off offset:16 nt

.LBB0_349:
	v_add_u32_e32 v136, s21, v166
	v_ashrrev_i32_e32 v137, 31, v136
	v_lshl_add_u64 v[134:135], v[136:137], 2, v[134:135]
	global_store_dwordx4 v[134:135], v[14:17], off nt
	global_store_dwordx4 v[134:135], v[10:13], off offset:16 nt

.LBB0_362:
	v_add_u32_e32 v130, s21, v144
	v_ashrrev_i32_e32 v131, 31, v130
	v_lshl_add_u64 v[130:131], v[130:131], 2, v[136:137]
	global_store_dwordx4 v[130:131], v[6:9], off nt
	global_store_dwordx4 v[130:131], v[2:5], off offset:16 nt

.LBB0_365:
	v_mov_b32_e32 v167, v155
	v_readlane_b32 s52, v254, 11
	v_lshlrev_b64 v[168:169], 2, v[166:167]
	v_readlane_b32 s62, v254, 21
	v_readlane_b32 s63, v254, 22
	v_mul_f32_e32 v126, 0xbfb8aa3b, v126
	v_exp_f32_e32 v126, v126
	v_lshl_add_u64 v[186:187], s[62:63], 0, v[168:169]
	global_load_dwordx4 v[130:133], v[186:187], off offset:-4080
	global_load_dwordx4 v[138:141], v[186:187], off offset:-4096
	global_load_dwordx4 v[134:137], v[186:187], off offset:16
	global_load_dwordx4 v[142:145], v[186:187], off
	v_mul_f32_e32 v122, 0xbfb8aa3b, v122
	v_add_f32_e32 v126, 1.0, v126
	v_exp_f32_e32 v122, v122
	v_mul_f32_e32 v127, 0xbfb8aa3b, v127
	v_exp_f32_e32 v127, v127
	v_mul_f32_e32 v123, 0xbfb8aa3b, v123
	v_add_f32_e32 v122, 1.0, v122
	v_rcp_f32_e32 v184, v122
	v_add_f32_e32 v127, 1.0, v127
	v_exp_f32_e32 v123, v123
	v_mul_f32_e32 v128, 0xbfb8aa3b, v128
	v_exp_f32_e32 v128, v128
	v_mul_f32_e32 v124, 0xbfb8aa3b, v124
	v_add_f32_e32 v123, 1.0, v123
	v_rcp_f32_e32 v182, v123
	v_add_f32_e32 v128, 1.0, v128
	v_exp_f32_e32 v124, v124
	v_mul_f32_e32 v129, 0xbfb8aa3b, v129
	v_exp_f32_e32 v129, v129
	v_mul_f32_e32 v125, 0xbfb8aa3b, v125
	v_add_f32_e32 v124, 1.0, v124
	v_rcp_f32_e32 v180, v124
	v_add_f32_e32 v129, 1.0, v129
	v_rcp_f32_e32 v176, v129
	v_exp_f32_e32 v125, v125
	v_mul_f32_e32 v118, 0xbfb8aa3b, v118
	v_exp_f32_e32 v118, v118
	v_mul_f32_e32 v114, 0xbfb8aa3b, v114
	v_add_f32_e32 v125, 1.0, v125
	v_rcp_f32_e32 v178, v125
	v_add_f32_e32 v118, 1.0, v118
	v_rcp_f32_e32 v188, v118
	v_exp_f32_e32 v114, v114
	v_lshlrev_b64 v[194:195], 12, v[164:165]
	v_lshl_add_u64 v[194:195], s[12:13], 0, v[194:195]
	v_lshl_add_u64 v[212:213], v[194:195], 0, v[168:169]
	v_add_f32_e32 v114, 1.0, v114
	v_mov_b64_e32 v[208:209], s[10:11]
	v_lshlrev_b64 v[210:211], 1, v[166:167]
	v_mul_f32_e32 v119, 0xbfb8aa3b, v119
	v_exp_f32_e32 v119, v119
	v_mul_f32_e32 v115, 0xbfb8aa3b, v115
	v_exp_f32_e32 v115, v115
	v_mul_f32_e32 v120, 0xbfb8aa3b, v120
	v_add_f32_e32 v119, 1.0, v119
	v_exp_f32_e32 v120, v120
	v_add_f32_e32 v115, 1.0, v115
	v_mul_f32_e32 v116, 0xbfb8aa3b, v116
	v_exp_f32_e32 v116, v116
	v_add_f32_e32 v120, 1.0, v120
	v_mul_f32_e32 v121, 0xbfb8aa3b, v121
	v_exp_f32_e32 v121, v121
	v_add_f32_e32 v116, 1.0, v116
	v_mul_f32_e32 v117, 0xbfb8aa3b, v117
	v_exp_f32_e32 v117, v117
	v_add_f32_e32 v121, 1.0, v121
	v_mul_f32_e32 v110, 0xbfb8aa3b, v110
	v_exp_f32_e32 v110, v110
	v_add_f32_e32 v117, 1.0, v117
	v_mul_f32_e32 v106, 0xbfb8aa3b, v106
	v_exp_f32_e32 v106, v106
	v_add_f32_e32 v110, 1.0, v110
	v_mul_f32_e32 v111, 0xbfb8aa3b, v111
	v_exp_f32_e32 v111, v111
	v_add_f32_e32 v106, 1.0, v106
	v_mul_f32_e32 v107, 0xbfb8aa3b, v107
	v_exp_f32_e32 v107, v107
	v_add_f32_e32 v111, 1.0, v111
	v_mul_f32_e32 v112, 0xbfb8aa3b, v112
	v_exp_f32_e32 v112, v112
	v_add_f32_e32 v107, 1.0, v107
	v_mul_f32_e32 v108, 0xbfb8aa3b, v108
	v_exp_f32_e32 v108, v108
	v_add_f32_e32 v112, 1.0, v112
	v_mul_f32_e32 v113, 0xbfb8aa3b, v113
	v_exp_f32_e32 v113, v113
	v_add_f32_e32 v108, 1.0, v108
	v_mul_f32_e32 v109, 0xbfb8aa3b, v109
	s_waitcnt vmcnt(0)
	v_sub_f32_e32 v130, v134, v130
	v_sub_f32_e32 v138, v142, v138
	v_mul_f32_e32 v142, 0x3fb8aa3b, v138
	v_fma_f32 v154, v138, s9, -v142
	v_rndne_f32_e32 v170, v142
	v_fmac_f32_e32 v154, 0x32a5705f, v138
	v_sub_f32_e32 v142, v142, v170
	v_add_f32_e32 v142, v142, v154
	v_exp_f32_e32 v142, v142
	v_cvt_i32_f32_e32 v154, v170
	v_cmp_ngt_f32_e32 vcc, s95, v138
	v_mul_f32_e32 v134, 0x3fb8aa3b, v130
	v_add_f32_e32 v113, 1.0, v113
	v_ldexp_f32 v142, v142, v154
	v_cndmask_b32_e32 v142, 0, v142, vcc
	v_cmp_nlt_f32_e32 vcc, s85, v138
	v_exp_f32_e32 v109, v109
	v_mul_f32_e32 v102, 0xbfb8aa3b, v102
	v_cndmask_b32_e32 v138, v223, v142, vcc
	v_add_f32_e32 v138, 1.0, v138
	v_div_scale_f32 v142, s[0:1], v138, v138, 1.0
	v_rcp_f32_e32 v154, v142
	v_add_f32_e32 v109, 1.0, v109
	v_exp_f32_e32 v102, v102
	v_mul_f32_e32 v98, 0xbfb8aa3b, v98
	v_fma_f32 v170, -v142, v154, 1.0
	v_fmac_f32_e32 v154, v170, v154
	v_div_scale_f32 v170, vcc, 1.0, v138, 1.0
	v_mul_f32_e32 v171, v170, v154
	v_fma_f32 v172, -v142, v171, v170
	v_fmac_f32_e32 v171, v172, v154
	v_fma_f32 v142, -v142, v171, v170
	v_div_fmas_f32 v142, v142, v154, v171
	v_div_fixup_f32 v171, v142, v138, 1.0
	v_sub_f32_e32 v138, v143, v139
	v_mul_f32_e32 v139, 0x3fb8aa3b, v138
	v_fma_f32 v142, v138, s9, -v139
	v_rndne_f32_e32 v143, v139
	v_fmac_f32_e32 v142, 0x32a5705f, v138
	v_sub_f32_e32 v139, v139, v143
	v_add_f32_e32 v139, v139, v142
	v_exp_f32_e32 v139, v139
	v_cvt_i32_f32_e32 v142, v143
	v_cmp_ngt_f32_e32 vcc, s95, v138
	v_add_f32_e32 v102, 1.0, v102
	v_exp_f32_e32 v98, v98
	v_ldexp_f32 v139, v139, v142
	v_cndmask_b32_e32 v139, 0, v139, vcc
	v_cmp_nlt_f32_e32 vcc, s85, v138
	v_add_f32_e32 v98, 1.0, v98
	v_mul_f32_e32 v103, 0xbfb8aa3b, v103
	v_cndmask_b32_e32 v138, v223, v139, vcc
	v_add_f32_e32 v138, 1.0, v138
	v_div_scale_f32 v139, s[0:1], v138, v138, 1.0
	v_rcp_f32_e32 v142, v139
	v_exp_f32_e32 v103, v103
	v_mul_f32_e32 v99, 0xbfb8aa3b, v99
	v_exp_f32_e32 v99, v99
	v_fma_f32 v143, -v139, v142, 1.0
	v_fmac_f32_e32 v142, v143, v142
	v_div_scale_f32 v143, vcc, 1.0, v138, 1.0
	v_mul_f32_e32 v154, v143, v142
	v_fma_f32 v170, -v139, v154, v143
	v_fmac_f32_e32 v154, v170, v142
	v_fma_f32 v139, -v139, v154, v143
	v_div_fmas_f32 v139, v139, v142, v154
	v_div_fixup_f32 v173, v139, v138, 1.0
	v_sub_f32_e32 v138, v144, v140
	v_mul_f32_e32 v139, 0x3fb8aa3b, v138
	v_fma_f32 v140, v138, s9, -v139
	v_rndne_f32_e32 v142, v139
	v_fmac_f32_e32 v140, 0x32a5705f, v138
	v_sub_f32_e32 v139, v139, v142
	v_add_f32_e32 v139, v139, v140
	v_exp_f32_e32 v139, v139
	v_cvt_i32_f32_e32 v140, v142
	v_cmp_ngt_f32_e32 vcc, s95, v138
	v_add_f32_e32 v103, 1.0, v103
	v_add_f32_e32 v99, 1.0, v99
	v_ldexp_f32 v139, v139, v140
	v_cndmask_b32_e32 v139, 0, v139, vcc
	v_cmp_nlt_f32_e32 vcc, s85, v138
	v_mul_f32_e32 v104, 0xbfb8aa3b, v104
	v_exp_f32_e32 v104, v104
	v_cndmask_b32_e32 v138, v223, v139, vcc
	v_add_f32_e32 v138, 1.0, v138
	v_div_scale_f32 v139, s[0:1], v138, v138, 1.0
	v_rcp_f32_e32 v140, v139
	v_mul_f32_e32 v100, 0xbfb8aa3b, v100
	v_add_f32_e32 v104, 1.0, v104
	v_exp_f32_e32 v100, v100
	v_fma_f32 v142, -v139, v140, 1.0
	v_fmac_f32_e32 v140, v142, v140
	v_div_scale_f32 v142, vcc, 1.0, v138, 1.0
	v_mul_f32_e32 v143, v142, v140
	v_fma_f32 v144, -v139, v143, v142
	v_fmac_f32_e32 v143, v144, v140
	v_fma_f32 v139, -v139, v143, v142
	v_div_fmas_f32 v139, v139, v140, v143
	v_div_fixup_f32 v175, v139, v138, 1.0
	v_sub_f32_e32 v138, v145, v141
	v_mul_f32_e32 v139, 0x3fb8aa3b, v138
	v_fma_f32 v140, v138, s9, -v139
	v_rndne_f32_e32 v141, v139
	v_fmac_f32_e32 v140, 0x32a5705f, v138
	v_sub_f32_e32 v139, v139, v141
	v_add_f32_e32 v139, v139, v140
	v_exp_f32_e32 v139, v139
	v_cvt_i32_f32_e32 v140, v141
	v_cmp_ngt_f32_e32 vcc, s95, v138
	v_add_f32_e32 v100, 1.0, v100
	v_mul_f32_e32 v105, 0xbfb8aa3b, v105
	v_ldexp_f32 v139, v139, v140
	v_cndmask_b32_e32 v139, 0, v139, vcc
	v_cmp_nlt_f32_e32 vcc, s85, v138
	v_exp_f32_e32 v105, v105
	v_mul_f32_e32 v101, 0xbfb8aa3b, v101
	v_cndmask_b32_e32 v138, v223, v139, vcc
	v_add_f32_e32 v138, 1.0, v138
	v_div_scale_f32 v139, s[0:1], v138, v138, 1.0
	v_rcp_f32_e32 v140, v139
	v_add_f32_e32 v105, 1.0, v105
	v_exp_f32_e32 v101, v101
	v_mul_f32_e32 v94, 0xbfb8aa3b, v94
	v_fma_f32 v141, -v139, v140, 1.0
	v_fmac_f32_e32 v140, v141, v140
	v_div_scale_f32 v141, vcc, 1.0, v138, 1.0
	v_mul_f32_e32 v142, v141, v140
	v_fma_f32 v143, -v139, v142, v141
	v_fmac_f32_e32 v142, v143, v140
	v_fma_f32 v139, -v139, v142, v141
	v_div_fmas_f32 v139, v139, v140, v142
	v_div_fixup_f32 v177, v139, v138, 1.0
	v_fma_f32 v138, v130, s9, -v134
	v_rndne_f32_e32 v139, v134
	v_fmac_f32_e32 v138, 0x32a5705f, v130
	v_sub_f32_e32 v134, v134, v139
	v_add_f32_e32 v134, v134, v138
	v_exp_f32_e32 v134, v134
	v_cvt_i32_f32_e32 v138, v139
	v_cmp_ngt_f32_e32 vcc, s95, v130
	v_add_f32_e32 v101, 1.0, v101
	v_exp_f32_e32 v94, v94
	v_ldexp_f32 v134, v134, v138
	v_cndmask_b32_e32 v134, 0, v134, vcc
	v_cmp_nlt_f32_e32 vcc, s85, v130
	v_mul_f32_e32 v90, 0xbfb8aa3b, v90
	v_add_f32_e32 v94, 1.0, v94
	v_cndmask_b32_e32 v130, v223, v134, vcc
	v_add_f32_e32 v130, 1.0, v130
	v_div_scale_f32 v134, s[0:1], v130, v130, 1.0
	v_rcp_f32_e32 v138, v134
	v_exp_f32_e32 v90, v90
	v_mul_f32_e32 v95, 0xbfb8aa3b, v95
	v_exp_f32_e32 v95, v95
	v_fma_f32 v139, -v134, v138, 1.0
	v_fmac_f32_e32 v138, v139, v138
	v_div_scale_f32 v139, vcc, 1.0, v130, 1.0
	v_mul_f32_e32 v140, v139, v138
	v_fma_f32 v141, -v134, v140, v139
	v_fmac_f32_e32 v140, v141, v138
	v_fma_f32 v134, -v134, v140, v139
	v_div_fmas_f32 v134, v134, v138, v140
	v_div_fixup_f32 v185, v134, v130, 1.0
	v_sub_f32_e32 v130, v135, v131
	v_mul_f32_e32 v131, 0x3fb8aa3b, v130
	v_fma_f32 v134, v130, s9, -v131
	v_rndne_f32_e32 v135, v131
	v_fmac_f32_e32 v134, 0x32a5705f, v130
	v_sub_f32_e32 v131, v131, v135
	v_add_f32_e32 v131, v131, v134
	v_exp_f32_e32 v131, v131
	v_cvt_i32_f32_e32 v134, v135
	v_cmp_ngt_f32_e32 vcc, s95, v130
	v_pk_add_f32 v[206:207], v[184:185], 1.0 op_sel_hi:[1,0] neg_lo:[1,0] neg_hi:[1,0]
	v_add_f32_e32 v90, 1.0, v90
	v_ldexp_f32 v131, v131, v134
	v_cndmask_b32_e32 v131, 0, v131, vcc
	v_cmp_nlt_f32_e32 vcc, s85, v130
	v_mul_f32_e32 v91, 0xbfb8aa3b, v91
	v_add_f32_e32 v95, 1.0, v95
	v_cndmask_b32_e32 v130, v223, v131, vcc
	v_add_f32_e32 v130, 1.0, v130
	v_div_scale_f32 v131, s[0:1], v130, v130, 1.0
	v_rcp_f32_e32 v134, v131
	v_exp_f32_e32 v91, v91
	v_mul_f32_e32 v96, 0xbfb8aa3b, v96
	v_exp_f32_e32 v96, v96
	v_fma_f32 v135, -v131, v134, 1.0
	v_fmac_f32_e32 v134, v135, v134
	v_div_scale_f32 v135, vcc, 1.0, v130, 1.0
	v_mul_f32_e32 v138, v135, v134
	v_fma_f32 v139, -v131, v138, v135
	v_fmac_f32_e32 v138, v139, v134
	v_fma_f32 v131, -v131, v138, v135
	v_div_fmas_f32 v131, v131, v134, v138
	v_div_fixup_f32 v183, v131, v130, 1.0
	v_sub_f32_e32 v130, v136, v132
	v_mul_f32_e32 v131, 0x3fb8aa3b, v130
	v_fma_f32 v132, v130, s9, -v131
	v_rndne_f32_e32 v134, v131
	v_fmac_f32_e32 v132, 0x32a5705f, v130
	v_sub_f32_e32 v131, v131, v134
	v_add_f32_e32 v131, v131, v132
	v_exp_f32_e32 v131, v131
	v_cvt_i32_f32_e32 v132, v134
	v_cmp_ngt_f32_e32 vcc, s95, v130
	v_pk_add_f32 v[204:205], v[182:183], 1.0 op_sel_hi:[1,0] neg_lo:[1,0] neg_hi:[1,0]
	v_add_f32_e32 v91, 1.0, v91
	v_ldexp_f32 v131, v131, v132
	v_cndmask_b32_e32 v131, 0, v131, vcc
	v_cmp_nlt_f32_e32 vcc, s85, v130
	v_mul_f32_e32 v92, 0xbfb8aa3b, v92
	v_add_f32_e32 v96, 1.0, v96
	v_cndmask_b32_e32 v130, v223, v131, vcc
	v_add_f32_e32 v130, 1.0, v130
	v_div_scale_f32 v131, s[0:1], v130, v130, 1.0
	v_rcp_f32_e32 v132, v131
	v_exp_f32_e32 v92, v92
	v_mul_f32_e32 v97, 0xbfb8aa3b, v97
	v_exp_f32_e32 v97, v97
	v_fma_f32 v134, -v131, v132, 1.0
	v_fmac_f32_e32 v132, v134, v132
	v_div_scale_f32 v134, vcc, 1.0, v130, 1.0
	v_mul_f32_e32 v135, v134, v132
	v_fma_f32 v136, -v131, v135, v134
	v_fmac_f32_e32 v135, v136, v132
	v_fma_f32 v131, -v131, v135, v134
	v_div_fmas_f32 v131, v131, v132, v135
	v_div_fixup_f32 v181, v131, v130, 1.0
	v_sub_f32_e32 v130, v137, v133
	v_mul_f32_e32 v131, 0x3fb8aa3b, v130
	v_fma_f32 v132, v130, s9, -v131
	v_rndne_f32_e32 v133, v131
	v_fmac_f32_e32 v132, 0x32a5705f, v130
	v_sub_f32_e32 v131, v131, v133
	v_add_f32_e32 v131, v131, v132
	v_exp_f32_e32 v131, v131
	v_cvt_i32_f32_e32 v132, v133
	v_cmp_ngt_f32_e32 vcc, s95, v130
	v_pk_add_f32 v[202:203], v[180:181], 1.0 op_sel_hi:[1,0] neg_lo:[1,0] neg_hi:[1,0]
	v_add_f32_e32 v92, 1.0, v92
	v_ldexp_f32 v131, v131, v132
	v_cndmask_b32_e32 v131, 0, v131, vcc
	v_cmp_nlt_f32_e32 vcc, s85, v130
	v_mul_f32_e32 v93, 0xbfb8aa3b, v93
	v_add_f32_e32 v97, 1.0, v97
	v_cndmask_b32_e32 v130, v223, v131, vcc
	v_add_f32_e32 v130, 1.0, v130
	v_div_scale_f32 v131, s[0:1], v130, v130, 1.0
	v_rcp_f32_e32 v132, v131
	v_exp_f32_e32 v93, v93
	v_mul_f32_e32 v86, 0xbfb8aa3b, v86
	v_exp_f32_e32 v86, v86
	v_fma_f32 v133, -v131, v132, 1.0
	v_fmac_f32_e32 v132, v133, v132
	v_div_scale_f32 v133, vcc, 1.0, v130, 1.0
	v_mul_f32_e32 v134, v133, v132
	v_fma_f32 v135, -v131, v134, v133
	v_fmac_f32_e32 v134, v135, v132
	v_fma_f32 v131, -v131, v134, v133
	v_div_fmas_f32 v131, v131, v132, v134
	v_div_fixup_f32 v179, v131, v130, 1.0
	global_load_dwordx4 v[130:133], v[186:187], off offset:-3568
	global_load_dwordx4 v[138:141], v[186:187], off offset:-3584
	global_load_dwordx4 v[134:137], v[186:187], off offset:528
	global_load_dwordx4 v[142:145], v[186:187], off offset:512
	v_pk_add_f32 v[200:201], v[178:179], 1.0 op_sel_hi:[1,0] neg_lo:[1,0] neg_hi:[1,0]
	v_rcp_f32_e32 v186, v119
	v_add_f32_e32 v93, 1.0, v93
	v_mul_f32_e32 v82, 0xbfb8aa3b, v82
	v_add_f32_e32 v86, 1.0, v86
	v_exp_f32_e32 v82, v82
	v_mul_f32_e32 v87, 0xbfb8aa3b, v87
	v_exp_f32_e32 v87, v87
	v_mul_f32_e32 v83, 0xbfb8aa3b, v83
	v_add_f32_e32 v82, 1.0, v82
	v_exp_f32_e32 v83, v83
	v_add_f32_e32 v87, 1.0, v87
	v_mul_f32_e32 v88, 0xbfb8aa3b, v88
	v_exp_f32_e32 v88, v88
	v_add_f32_e32 v83, 1.0, v83
	v_mul_f32_e32 v84, 0xbfb8aa3b, v84
	v_exp_f32_e32 v84, v84
	v_add_f32_e32 v88, 1.0, v88
	v_mul_f32_e32 v89, 0xbfb8aa3b, v89
	v_exp_f32_e32 v89, v89
	v_add_f32_e32 v84, 1.0, v84
	v_mul_f32_e32 v85, 0xbfb8aa3b, v85
	v_exp_f32_e32 v85, v85
	v_add_f32_e32 v89, 1.0, v89
	v_mul_f32_e32 v78, 0xbfb8aa3b, v78
	v_exp_f32_e32 v78, v78
	v_add_f32_e32 v85, 1.0, v85
	v_mul_f32_e32 v74, 0xbfb8aa3b, v74
	v_exp_f32_e32 v74, v74
	v_add_f32_e32 v78, 1.0, v78
	v_mul_f32_e32 v79, 0xbfb8aa3b, v79
	v_exp_f32_e32 v79, v79
	v_add_f32_e32 v74, 1.0, v74
	v_mul_f32_e32 v75, 0xbfb8aa3b, v75
	v_exp_f32_e32 v75, v75
	v_add_f32_e32 v79, 1.0, v79
	v_mul_f32_e32 v80, 0xbfb8aa3b, v80
	v_exp_f32_e32 v80, v80
	v_add_f32_e32 v75, 1.0, v75
	v_mul_f32_e32 v76, 0xbfb8aa3b, v76
	v_exp_f32_e32 v76, v76
	v_add_f32_e32 v80, 1.0, v80
	v_mul_f32_e32 v81, 0xbfb8aa3b, v81
	v_exp_f32_e32 v81, v81
	v_add_f32_e32 v76, 1.0, v76
	v_mul_f32_e32 v77, 0xbfb8aa3b, v77
	v_exp_f32_e32 v77, v77
	v_add_f32_e32 v81, 1.0, v81
	v_mul_f32_e32 v70, 0xbfb8aa3b, v70
	v_exp_f32_e32 v70, v70
	v_add_f32_e32 v77, 1.0, v77
	v_mul_f32_e32 v66, 0xbfb8aa3b, v66
	v_exp_f32_e32 v66, v66
	v_add_f32_e32 v70, 1.0, v70
	v_mul_f32_e32 v71, 0xbfb8aa3b, v71
	v_exp_f32_e32 v71, v71
	v_add_f32_e32 v66, 1.0, v66
	v_mul_f32_e32 v67, 0xbfb8aa3b, v67
	v_exp_f32_e32 v67, v67
	v_add_f32_e32 v71, 1.0, v71
	v_mul_f32_e32 v72, 0xbfb8aa3b, v72
	v_exp_f32_e32 v72, v72
	v_add_f32_e32 v67, 1.0, v67
	v_mul_f32_e32 v68, 0xbfb8aa3b, v68
	v_exp_f32_e32 v68, v68
	v_add_f32_e32 v72, 1.0, v72
	v_mul_f32_e32 v73, 0xbfb8aa3b, v73
	v_exp_f32_e32 v73, v73
	v_add_f32_e32 v68, 1.0, v68
	v_mul_f32_e32 v69, 0xbfb8aa3b, v69
	v_exp_f32_e32 v69, v69
	v_add_f32_e32 v73, 1.0, v73
	v_mul_f32_e32 v62, 0xbfb8aa3b, v62
	v_exp_f32_e32 v62, v62
	v_add_f32_e32 v69, 1.0, v69
	v_mul_f32_e32 v58, 0xbfb8aa3b, v58
	v_exp_f32_e32 v58, v58
	v_add_f32_e32 v62, 1.0, v62
	s_waitcnt vmcnt(1)
	v_sub_f32_e32 v130, v134, v130
	s_waitcnt vmcnt(0)
	v_sub_f32_e32 v138, v142, v138
	v_mul_f32_e32 v142, 0x3fb8aa3b, v138
	v_fma_f32 v154, v138, s9, -v142
	v_rndne_f32_e32 v170, v142
	v_fmac_f32_e32 v154, 0x32a5705f, v138
	v_sub_f32_e32 v142, v142, v170
	v_add_f32_e32 v142, v142, v154
	v_exp_f32_e32 v142, v142
	v_cvt_i32_f32_e32 v154, v170
	v_cmp_ngt_f32_e32 vcc, s95, v138
	v_mul_f32_e32 v134, 0x3fb8aa3b, v130
	v_add_f32_e32 v58, 1.0, v58
	v_ldexp_f32 v142, v142, v154
	v_cndmask_b32_e32 v142, 0, v142, vcc
	v_cmp_nlt_f32_e32 vcc, s85, v138
	v_mul_f32_e32 v63, 0xbfb8aa3b, v63
	v_exp_f32_e32 v63, v63
	v_cndmask_b32_e32 v138, v223, v142, vcc
	v_add_f32_e32 v138, 1.0, v138
	v_div_scale_f32 v142, s[0:1], v138, v138, 1.0
	v_rcp_f32_e32 v154, v142
	v_mul_f32_e32 v59, 0xbfb8aa3b, v59
	v_add_f32_e32 v63, 1.0, v63
	v_exp_f32_e32 v59, v59
	v_fma_f32 v170, -v142, v154, 1.0
	v_fmac_f32_e32 v154, v170, v154
	v_div_scale_f32 v170, vcc, 1.0, v138, 1.0
	v_mul_f32_e32 v172, v170, v154
	v_fma_f32 v174, -v142, v172, v170
	v_fmac_f32_e32 v172, v174, v154
	v_fma_f32 v142, -v142, v172, v170
	v_div_fmas_f32 v142, v142, v154, v172
	v_div_fixup_f32 v189, v142, v138, 1.0
	v_sub_f32_e32 v138, v143, v139
	v_mul_f32_e32 v139, 0x3fb8aa3b, v138
	v_fma_f32 v142, v138, s9, -v139
	v_rndne_f32_e32 v143, v139
	v_fmac_f32_e32 v142, 0x32a5705f, v138
	v_sub_f32_e32 v139, v139, v143
	v_add_f32_e32 v139, v139, v142
	v_exp_f32_e32 v139, v139
	v_cvt_i32_f32_e32 v142, v143
	v_cmp_ngt_f32_e32 vcc, s95, v138
	v_rcp_f32_e32 v172, v127
	v_rcp_f32_e32 v174, v128
	v_ldexp_f32 v139, v139, v142
	v_cndmask_b32_e32 v139, 0, v139, vcc
	v_cmp_nlt_f32_e32 vcc, s85, v138
	v_pk_add_f32 v[190:191], v[172:173], 1.0 op_sel_hi:[1,0] neg_lo:[1,0] neg_hi:[1,0]
	v_add_f32_e32 v59, 1.0, v59
	v_cndmask_b32_e32 v138, v223, v139, vcc
	v_add_f32_e32 v138, 1.0, v138
	v_div_scale_f32 v139, s[0:1], v138, v138, 1.0
	v_rcp_f32_e32 v142, v139
	v_fma_f32 v123, v172, v191, v173
	v_mul_f32_e32 v64, 0xbfb8aa3b, v64
	v_exp_f32_e32 v64, v64
	v_fma_f32 v143, -v139, v142, 1.0
	v_fmac_f32_e32 v142, v143, v142
	v_div_scale_f32 v143, vcc, 1.0, v138, 1.0
	v_mul_f32_e32 v154, v143, v142
	v_fma_f32 v170, -v139, v154, v143
	v_fmac_f32_e32 v154, v170, v142
	v_fma_f32 v139, -v139, v154, v143
	v_div_fmas_f32 v139, v139, v142, v154
	v_div_fixup_f32 v187, v139, v138, 1.0
	v_sub_f32_e32 v138, v144, v140
	v_mul_f32_e32 v139, 0x3fb8aa3b, v138
	v_fma_f32 v140, v138, s9, -v139
	v_rndne_f32_e32 v142, v139
	v_fmac_f32_e32 v140, 0x32a5705f, v138
	v_sub_f32_e32 v139, v139, v142
	v_add_f32_e32 v139, v139, v140
	v_exp_f32_e32 v139, v139
	v_cvt_i32_f32_e32 v140, v142
	v_cmp_ngt_f32_e32 vcc, s95, v138
	v_rcp_f32_e32 v170, v126
	v_mul_f32_e32 v60, 0xbfb8aa3b, v60
	v_ldexp_f32 v139, v139, v140
	v_cndmask_b32_e32 v139, 0, v139, vcc
	v_cmp_nlt_f32_e32 vcc, s85, v138
	v_pk_add_f32 v[192:193], v[170:171], 1.0 op_sel_hi:[1,0] neg_lo:[1,0] neg_hi:[1,0]
	v_add_f32_e32 v64, 1.0, v64
	v_cndmask_b32_e32 v138, v223, v139, vcc
	v_add_f32_e32 v138, 1.0, v138
	v_div_scale_f32 v139, s[0:1], v138, v138, 1.0
	v_rcp_f32_e32 v140, v139
	v_fma_f32 v122, v170, v193, v171
	v_exp_f32_e32 v60, v60
	v_mul_f32_e32 v65, 0xbfb8aa3b, v65
	v_fma_f32 v142, -v139, v140, 1.0
	v_fmac_f32_e32 v140, v142, v140
	v_div_scale_f32 v142, vcc, 1.0, v138, 1.0
	v_mul_f32_e32 v143, v142, v140
	v_fma_f32 v144, -v139, v143, v142
	v_fmac_f32_e32 v143, v144, v140
	v_fma_f32 v139, -v139, v143, v142
	v_div_fmas_f32 v139, v139, v140, v143
	v_div_fixup_f32 v143, v139, v138, 1.0
	v_sub_f32_e32 v138, v145, v141
	v_mul_f32_e32 v139, 0x3fb8aa3b, v138
	v_fma_f32 v140, v138, s9, -v139
	v_rndne_f32_e32 v141, v139
	v_fmac_f32_e32 v140, 0x32a5705f, v138
	v_sub_f32_e32 v139, v139, v141
	v_add_f32_e32 v139, v139, v140
	v_exp_f32_e32 v139, v139
	v_cvt_i32_f32_e32 v140, v141
	v_cmp_ngt_f32_e32 vcc, s95, v138
	v_add_f32_e32 v60, 1.0, v60
	v_exp_f32_e32 v65, v65
	v_ldexp_f32 v139, v139, v140
	v_cndmask_b32_e32 v139, 0, v139, vcc
	v_cmp_nlt_f32_e32 vcc, s85, v138
	v_mul_f32_e32 v61, 0xbfb8aa3b, v61
	v_add_f32_e32 v65, 1.0, v65
	v_cndmask_b32_e32 v138, v223, v139, vcc
	v_add_f32_e32 v138, 1.0, v138
	v_div_scale_f32 v139, s[0:1], v138, v138, 1.0
	v_rcp_f32_e32 v140, v139
	v_exp_f32_e32 v61, v61
	v_mul_f32_e32 v54, 0xbfb8aa3b, v54
	v_exp_f32_e32 v54, v54
	v_fma_f32 v141, -v139, v140, 1.0
	v_fmac_f32_e32 v140, v141, v140
	v_div_scale_f32 v141, vcc, 1.0, v138, 1.0
	v_mul_f32_e32 v142, v141, v140
	v_fma_f32 v144, -v139, v142, v141
	v_fmac_f32_e32 v142, v144, v140
	v_fma_f32 v139, -v139, v142, v141
	v_div_fmas_f32 v139, v139, v140, v142
	v_div_fixup_f32 v139, v139, v138, 1.0
	v_fma_f32 v138, v130, s9, -v134
	v_rndne_f32_e32 v140, v134
	v_fmac_f32_e32 v138, 0x32a5705f, v130
	v_sub_f32_e32 v134, v134, v140
	v_add_f32_e32 v134, v134, v138
	v_exp_f32_e32 v134, v134
	v_cvt_i32_f32_e32 v138, v140
	v_cmp_ngt_f32_e32 vcc, s95, v130
	v_add_f32_e32 v61, 1.0, v61
	v_mul_f32_e32 v50, 0xbfb8aa3b, v50
	v_ldexp_f32 v134, v134, v138
	v_cndmask_b32_e32 v134, 0, v134, vcc
	v_cmp_nlt_f32_e32 vcc, s85, v130
	v_add_f32_e32 v54, 1.0, v54
	v_exp_f32_e32 v50, v50
	v_cndmask_b32_e32 v130, v223, v134, vcc
	v_add_f32_e32 v130, 1.0, v130
	v_div_scale_f32 v134, s[0:1], v130, v130, 1.0
	v_rcp_f32_e32 v138, v134
	v_add_f32_e32 v50, 1.0, v50
	v_mul_f32_e32 v55, 0xbfb8aa3b, v55
	v_exp_f32_e32 v55, v55
	v_fma_f32 v140, -v134, v138, 1.0
	v_fmac_f32_e32 v138, v140, v138
	v_div_scale_f32 v140, vcc, 1.0, v130, 1.0
	v_mul_f32_e32 v141, v140, v138
	v_fma_f32 v142, -v134, v141, v140
	v_fmac_f32_e32 v141, v142, v138
	v_fma_f32 v134, -v134, v141, v140
	v_div_fmas_f32 v134, v134, v138, v141
	v_div_fixup_f32 v145, v134, v130, 1.0
	v_sub_f32_e32 v130, v135, v131
	v_mul_f32_e32 v131, 0x3fb8aa3b, v130
	v_fma_f32 v134, v130, s9, -v131
	v_rndne_f32_e32 v135, v131
	v_fmac_f32_e32 v134, 0x32a5705f, v130
	v_sub_f32_e32 v131, v131, v135
	v_add_f32_e32 v131, v131, v134
	v_exp_f32_e32 v131, v131
	v_cvt_i32_f32_e32 v134, v135
	v_cmp_ngt_f32_e32 vcc, s95, v130
	v_mul_f32_e32 v142, v202, v203
	v_mul_f32_e32 v51, 0xbfb8aa3b, v51
	v_ldexp_f32 v131, v131, v134
	v_cndmask_b32_e32 v131, 0, v131, vcc
	v_cmp_nlt_f32_e32 vcc, s85, v130
	v_add_f32_e32 v55, 1.0, v55
	v_exp_f32_e32 v51, v51
	v_cndmask_b32_e32 v130, v223, v131, vcc
	v_add_f32_e32 v130, 1.0, v130
	v_div_scale_f32 v131, s[0:1], v130, v130, 1.0
	v_rcp_f32_e32 v134, v131
	v_add_f32_e32 v51, 1.0, v51
	v_mul_f32_e32 v56, 0xbfb8aa3b, v56
	v_exp_f32_e32 v56, v56
	v_fma_f32 v135, -v131, v134, 1.0
	v_fmac_f32_e32 v134, v135, v134
	v_div_scale_f32 v135, vcc, 1.0, v130, 1.0
	v_mul_f32_e32 v138, v135, v134
	v_fma_f32 v140, -v131, v138, v135
	v_fmac_f32_e32 v138, v140, v134
	v_fma_f32 v131, -v131, v138, v135
	v_div_fmas_f32 v131, v131, v134, v138
	v_div_fixup_f32 v141, v131, v130, 1.0
	v_sub_f32_e32 v130, v136, v132
	v_mul_f32_e32 v131, 0x3fb8aa3b, v130
	v_fma_f32 v132, v130, s9, -v131
	v_rndne_f32_e32 v134, v131
	v_fmac_f32_e32 v132, 0x32a5705f, v130
	v_sub_f32_e32 v131, v131, v134
	v_add_f32_e32 v131, v131, v132
	v_exp_f32_e32 v131, v131
	v_cvt_i32_f32_e32 v132, v134
	v_cmp_ngt_f32_e32 vcc, s95, v130
	v_mul_f32_e32 v138, v190, v191
	v_mul_f32_e32 v140, v204, v205
	v_ldexp_f32 v131, v131, v132
	v_cndmask_b32_e32 v131, 0, v131, vcc
	v_cmp_nlt_f32_e32 vcc, s85, v130
	v_mul_f32_e32 v52, 0xbfb8aa3b, v52
	v_add_f32_e32 v56, 1.0, v56
	v_cndmask_b32_e32 v130, v223, v131, vcc
	v_add_f32_e32 v130, 1.0, v130
	v_div_scale_f32 v131, s[0:1], v130, v130, 1.0
	v_rcp_f32_e32 v132, v131
	v_exp_f32_e32 v52, v52
	v_mul_f32_e32 v57, 0xbfb8aa3b, v57
	v_exp_f32_e32 v57, v57
	v_fma_f32 v134, -v131, v132, 1.0
	v_fmac_f32_e32 v132, v134, v132
	v_div_scale_f32 v134, vcc, 1.0, v130, 1.0
	v_mul_f32_e32 v135, v134, v132
	v_fma_f32 v136, -v131, v135, v134
	v_fmac_f32_e32 v135, v136, v132
	v_fma_f32 v131, -v131, v135, v134
	v_div_fmas_f32 v131, v131, v132, v135
	v_div_fixup_f32 v135, v131, v130, 1.0
	v_sub_f32_e32 v130, v137, v133
	v_mul_f32_e32 v131, 0x3fb8aa3b, v130
	v_fma_f32 v132, v130, s9, -v131
	v_rndne_f32_e32 v133, v131
	v_fmac_f32_e32 v132, 0x32a5705f, v130
	v_sub_f32_e32 v131, v131, v133
	v_add_f32_e32 v131, v131, v132
	v_exp_f32_e32 v131, v131
	v_cvt_i32_f32_e32 v132, v133
	v_cmp_ngt_f32_e32 vcc, s95, v130
	v_add_f32_e32 v52, 1.0, v52
	v_mul_f32_e32 v53, 0xbfb8aa3b, v53
	v_ldexp_f32 v131, v131, v132
	v_cndmask_b32_e32 v131, 0, v131, vcc
	v_cmp_nlt_f32_e32 vcc, s85, v130
	v_add_f32_e32 v57, 1.0, v57
	v_exp_f32_e32 v53, v53
	v_cndmask_b32_e32 v130, v223, v131, vcc
	v_add_f32_e32 v130, 1.0, v130
	v_div_scale_f32 v131, s[0:1], v130, v130, 1.0
	v_rcp_f32_e32 v132, v131
	v_add_f32_e32 v53, 1.0, v53
	v_mul_f32_e32 v46, 0xbfb8aa3b, v46
	v_exp_f32_e32 v46, v46
	v_fma_f32 v133, -v131, v132, 1.0
	v_fmac_f32_e32 v132, v133, v132
	v_div_scale_f32 v133, vcc, 1.0, v130, 1.0
	v_mul_f32_e32 v134, v133, v132
	v_fma_f32 v136, -v131, v134, v133
	v_fmac_f32_e32 v134, v136, v132
	v_fma_f32 v131, -v131, v134, v133
	v_div_fmas_f32 v131, v131, v132, v134
	v_cmp_gt_f32_e32 vcc, s16, v122
	v_pk_add_f32 v[136:137], v[174:175], 1.0 op_sel_hi:[1,0] neg_lo:[1,0] neg_hi:[1,0]
	v_div_fixup_f32 v131, v131, v130, 1.0
	v_cndmask_b32_e64 v126, 0, 32, vcc
	v_ldexp_f32 v122, v122, v126
	v_log_f32_e32 v122, v122
	v_fma_f32 v124, v174, v137, v175
	v_mul_f32_e32 v130, v192, v193
	v_mul_f32_e32 v134, v206, v207
	v_mul_f32_e32 v126, 0x3f317217, v122
	v_fma_f32 v126, v122, s17, -v126
	v_fmac_f32_e32 v126, 0x3377d1cf, v122
	v_fmac_f32_e32 v126, 0x3f317217, v122
	v_cmp_lt_f32_e64 s[0:1], |v122|, s86
	v_mul_f32_e32 v136, v136, v137
	v_mul_f32_e32 v42, 0xbfb8aa3b, v42
	v_cndmask_b32_e64 v122, v122, v126, s[0:1]
	v_cndmask_b32_e32 v126, 0, v224, vcc
	v_sub_f32_e32 v122, v122, v126
	v_fma_f32 v126, v184, v207, v185
	v_cmp_gt_f32_e32 vcc, s16, v126
	v_add_f32_e32 v46, 1.0, v46
	v_exp_f32_e32 v42, v42
	v_cndmask_b32_e64 v132, 0, 32, vcc
	v_ldexp_f32 v126, v126, v132
	v_log_f32_e32 v126, v126
	v_add_f32_e32 v42, 1.0, v42
	v_mul_f32_e32 v47, 0xbfb8aa3b, v47
	v_exp_f32_e32 v47, v47
	v_mul_f32_e32 v132, 0x3f317217, v126
	v_fma_f32 v132, v126, s17, -v132
	v_fmac_f32_e32 v132, 0x3377d1cf, v126
	v_fmac_f32_e32 v132, 0x3f317217, v126
	v_cmp_lt_f32_e64 s[0:1], |v126|, s86
	v_mul_f32_e32 v43, 0xbfb8aa3b, v43
	v_add_f32_e32 v47, 1.0, v47
	v_cndmask_b32_e64 v126, v126, v132, s[0:1]
	v_cndmask_b32_e32 v132, 0, v224, vcc
	v_cmp_gt_f32_e32 vcc, s16, v123
	v_sub_f32_e32 v126, v126, v132
	v_exp_f32_e32 v43, v43
	v_cndmask_b32_e64 v127, 0, 32, vcc
	v_ldexp_f32 v123, v123, v127
	v_log_f32_e32 v123, v123
	v_add_f32_e32 v43, 1.0, v43
	v_mul_f32_e32 v48, 0xbfb8aa3b, v48
	v_exp_f32_e32 v48, v48
	v_mul_f32_e32 v127, 0x3f317217, v123
	v_fma_f32 v127, v123, s17, -v127
	v_fmac_f32_e32 v127, 0x3377d1cf, v123
	v_fmac_f32_e32 v127, 0x3f317217, v123
	v_cmp_lt_f32_e64 s[0:1], |v123|, s86
	v_mul_f32_e32 v44, 0xbfb8aa3b, v44
	v_add_f32_e32 v48, 1.0, v48
	v_cndmask_b32_e64 v123, v123, v127, s[0:1]
	v_cndmask_b32_e32 v127, 0, v224, vcc
	v_sub_f32_e32 v123, v123, v127
	v_fma_f32 v127, v182, v205, v183
	v_cmp_gt_f32_e32 vcc, s16, v127
	v_exp_f32_e32 v44, v44
	v_mul_f32_e32 v49, 0xbfb8aa3b, v49
	v_cndmask_b32_e64 v132, 0, 32, vcc
	v_ldexp_f32 v127, v127, v132
	v_log_f32_e32 v127, v127
	v_add_f32_e32 v44, 1.0, v44
	v_exp_f32_e32 v49, v49
	v_mul_f32_e32 v45, 0xbfb8aa3b, v45
	v_mul_f32_e32 v132, 0x3f317217, v127
	v_fma_f32 v132, v127, s17, -v132
	v_fmac_f32_e32 v132, 0x3377d1cf, v127
	v_fmac_f32_e32 v132, 0x3f317217, v127
	v_cmp_lt_f32_e64 s[0:1], |v127|, s86
	v_add_f32_e32 v49, 1.0, v49
	v_exp_f32_e32 v45, v45
	v_cndmask_b32_e64 v127, v127, v132, s[0:1]
	v_cndmask_b32_e32 v132, 0, v224, vcc
	v_cmp_gt_f32_e32 vcc, s16, v124
	v_sub_f32_e32 v127, v127, v132
	v_add_f32_e32 v45, 1.0, v45
	v_cndmask_b32_e64 v128, 0, 32, vcc
	v_ldexp_f32 v124, v124, v128
	v_log_f32_e32 v124, v124
	v_mul_f32_e32 v38, 0xbfb8aa3b, v38
	v_exp_f32_e32 v38, v38
	v_mul_f32_e32 v34, 0xbfb8aa3b, v34
	v_mul_f32_e32 v128, 0x3f317217, v124
	v_fma_f32 v128, v124, s17, -v128
	v_fmac_f32_e32 v128, 0x3377d1cf, v124
	v_fmac_f32_e32 v128, 0x3f317217, v124
	v_cmp_lt_f32_e64 s[0:1], |v124|, s86
	v_add_f32_e32 v38, 1.0, v38
	v_exp_f32_e32 v34, v34
	v_cndmask_b32_e64 v124, v124, v128, s[0:1]
	v_cndmask_b32_e32 v128, 0, v224, vcc
	v_sub_f32_e32 v124, v124, v128
	v_fma_f32 v128, v180, v203, v181
	v_cmp_gt_f32_e32 vcc, s16, v128
	v_add_f32_e32 v34, 1.0, v34
	v_mul_f32_e32 v39, 0xbfb8aa3b, v39
	v_cndmask_b32_e64 v132, 0, 32, vcc
	v_ldexp_f32 v128, v128, v132
	v_log_f32_e32 v128, v128
	v_exp_f32_e32 v39, v39
	v_mul_f32_e32 v35, 0xbfb8aa3b, v35
	v_exp_f32_e32 v35, v35
	v_mul_f32_e32 v132, 0x3f317217, v128
	v_fma_f32 v132, v128, s17, -v132
	v_fmac_f32_e32 v132, 0x3377d1cf, v128
	v_fmac_f32_e32 v132, 0x3f317217, v128
	v_cmp_lt_f32_e64 s[0:1], |v128|, s86
	v_add_f32_e32 v39, 1.0, v39
	v_add_f32_e32 v35, 1.0, v35
	v_cndmask_b32_e64 v128, v128, v132, s[0:1]
	v_cndmask_b32_e32 v132, 0, v224, vcc
	v_sub_f32_e32 v128, v128, v132
	v_pk_add_f32 v[132:133], v[176:177], 1.0 op_sel_hi:[1,0] neg_lo:[1,0] neg_hi:[1,0]
	v_mul_f32_e32 v40, 0xbfb8aa3b, v40
	v_fma_f32 v125, v176, v133, v177
	v_cmp_gt_f32_e32 vcc, s16, v125
	v_mul_f32_e32 v132, v132, v133
	v_exp_f32_e32 v40, v40
	v_cndmask_b32_e64 v129, 0, 32, vcc
	v_ldexp_f32 v125, v125, v129
	v_log_f32_e32 v125, v125
	v_mul_f32_e32 v36, 0xbfb8aa3b, v36
	v_add_f32_e32 v40, 1.0, v40
	v_exp_f32_e32 v36, v36
	v_mul_f32_e32 v129, 0x3f317217, v125
	v_fma_f32 v129, v125, s17, -v129
	v_fmac_f32_e32 v129, 0x3377d1cf, v125
	v_fmac_f32_e32 v129, 0x3f317217, v125
	v_cmp_lt_f32_e64 s[0:1], |v125|, s86
	v_add_f32_e32 v36, 1.0, v36
	v_mul_f32_e32 v41, 0xbfb8aa3b, v41
	v_cndmask_b32_e64 v125, v125, v129, s[0:1]
	v_cndmask_b32_e32 v129, 0, v224, vcc
	v_sub_f32_e32 v125, v125, v129
	v_fma_f32 v129, v178, v201, v179
	v_cmp_gt_f32_e32 vcc, s16, v129
	v_exp_f32_e32 v41, v41
	v_mul_f32_e32 v37, 0xbfb8aa3b, v37
	v_cndmask_b32_e64 v144, 0, 32, vcc
	v_ldexp_f32 v129, v129, v144
	v_log_f32_e32 v129, v129
	v_add_f32_e32 v41, 1.0, v41
	v_exp_f32_e32 v37, v37
	v_mul_f32_e32 v30, 0xbfb8aa3b, v30
	v_mul_f32_e32 v144, 0x3f317217, v129
	v_fma_f32 v144, v129, s17, -v144
	v_fmac_f32_e32 v144, 0x3377d1cf, v129
	v_fmac_f32_e32 v144, 0x3f317217, v129
	v_cmp_lt_f32_e64 s[0:1], |v129|, s86
	v_add_f32_e32 v37, 1.0, v37
	v_exp_f32_e32 v30, v30
	v_cndmask_b32_e64 v129, v129, v144, s[0:1]
	v_cndmask_b32_e32 v144, 0, v224, vcc
	v_sub_f32_e32 v129, v129, v144
	v_mul_f32_e32 v144, v200, v201
	global_store_dwordx4 v[212:213], v[122:125], off offset:-4096 nt
	global_store_dwordx4 v[212:213], v[126:129], off offset:-4080 nt
	v_mul_f32_e32 v26, 0xbfb8aa3b, v26
	v_cvt_pk_bf16_f32 v122, v130, v138
	v_cvt_pk_bf16_f32 v123, v136, v132
	v_cvt_pk_bf16_f32 v124, v134, v140
	v_cvt_pk_bf16_f32 v125, v142, v144
	s_nop 0
	v_pk_add_f32 v[128:129], v[188:189], 1.0 op_sel_hi:[1,0] neg_lo:[1,0] neg_hi:[1,0]
	v_rcp_f32_e32 v144, v114
	v_fma_f32 v114, v188, v129, v189
	v_cmp_gt_f32_e32 vcc, s16, v114
	v_mad_i64_i32 v[126:127], s[0:1], v164, s8, v[208:209]
	s_nop 0
	v_cndmask_b32_e64 v118, 0, 32, vcc
	v_ldexp_f32 v114, v114, v118
	v_log_f32_e32 v114, v114
	v_pk_add_f32 v[198:199], v[144:145], 1.0 op_sel_hi:[1,0] neg_lo:[1,0] neg_hi:[1,0]
	v_lshl_add_u64 v[214:215], v[126:127], 0, v[210:211]
	global_store_dwordx4 v[214:215], v[122:125], off
	v_mul_f32_e32 v118, 0x3f317217, v114
	v_fma_f32 v118, v114, s17, -v118
	v_fmac_f32_e32 v118, 0x3377d1cf, v114
	v_fmac_f32_e32 v118, 0x3f317217, v114
	v_cmp_lt_f32_e64 s[0:1], |v114|, s86
	v_pk_add_f32 v[126:127], v[186:187], 1.0 op_sel_hi:[1,0] neg_lo:[1,0] neg_hi:[1,0]
	v_rcp_f32_e32 v140, v115
	v_cndmask_b32_e64 v114, v114, v118, s[0:1]
	v_cndmask_b32_e32 v118, 0, v224, vcc
	v_sub_f32_e32 v114, v114, v118
	v_fma_f32 v118, v144, v199, v145
	v_cmp_gt_f32_e32 vcc, s16, v118
	v_fma_f32 v115, v186, v127, v187
	v_pk_add_f32 v[196:197], v[140:141], 1.0 op_sel_hi:[1,0] neg_lo:[1,0] neg_hi:[1,0]
	v_cndmask_b32_e64 v122, 0, 32, vcc
	v_ldexp_f32 v118, v118, v122
	v_log_f32_e32 v118, v118
	v_rcp_f32_e32 v142, v120
	v_rcp_f32_e32 v134, v116
	v_rcp_f32_e32 v138, v121
	v_mul_f32_e32 v122, 0x3f317217, v118
	v_fma_f32 v122, v118, s17, -v122
	v_fmac_f32_e32 v122, 0x3377d1cf, v118
	v_fmac_f32_e32 v122, 0x3f317217, v118
	v_cmp_lt_f32_e64 s[0:1], |v118|, s86
	v_pk_add_f32 v[124:125], v[142:143], 1.0 op_sel_hi:[1,0] neg_lo:[1,0] neg_hi:[1,0]
	v_pk_add_f32 v[194:195], v[134:135], 1.0 op_sel_hi:[1,0] neg_lo:[1,0] neg_hi:[1,0]
	v_cndmask_b32_e64 v118, v118, v122, s[0:1]
	v_cndmask_b32_e32 v122, 0, v224, vcc
	v_cmp_gt_f32_e32 vcc, s16, v115
	v_sub_f32_e32 v118, v118, v122
	v_fma_f32 v116, v142, v125, v143
	v_cndmask_b32_e64 v119, 0, 32, vcc
	v_ldexp_f32 v115, v115, v119
	v_log_f32_e32 v115, v115
	v_rcp_f32_e32 v130, v117
	v_mul_f32_e32 v128, v128, v129
	v_mul_f32_e32 v126, v126, v127
	v_mul_f32_e32 v119, 0x3f317217, v115
	v_fma_f32 v119, v115, s17, -v119
	v_fmac_f32_e32 v119, 0x3377d1cf, v115
	v_fmac_f32_e32 v119, 0x3f317217, v115
	v_cmp_lt_f32_e64 s[0:1], |v115|, s86
	v_pk_add_f32 v[166:167], v[130:131], 1.0 op_sel_hi:[1,0] neg_lo:[1,0] neg_hi:[1,0]
	v_mul_f32_e32 v132, v198, v199
	v_cndmask_b32_e64 v115, v115, v119, s[0:1]
	v_cndmask_b32_e32 v119, 0, v224, vcc
	v_sub_f32_e32 v115, v115, v119
	v_fma_f32 v119, v140, v197, v141
	v_cmp_gt_f32_e32 vcc, s16, v119
	v_mul_f32_e32 v136, v196, v197
	v_mul_f32_e32 v124, v124, v125
	v_cndmask_b32_e64 v122, 0, 32, vcc
	v_ldexp_f32 v119, v119, v122
	v_log_f32_e32 v119, v119
	v_add_f32_e32 v30, 1.0, v30
	v_exp_f32_e32 v26, v26
	v_mul_f32_e32 v31, 0xbfb8aa3b, v31
	v_mul_f32_e32 v122, 0x3f317217, v119
	v_fma_f32 v122, v119, s17, -v122
	v_fmac_f32_e32 v122, 0x3377d1cf, v119
	v_fmac_f32_e32 v122, 0x3f317217, v119
	v_cmp_lt_f32_e64 s[0:1], |v119|, s86
	v_add_f32_e32 v26, 1.0, v26
	v_exp_f32_e32 v31, v31
	v_cndmask_b32_e64 v119, v119, v122, s[0:1]
	v_cndmask_b32_e32 v122, 0, v224, vcc
	v_cmp_gt_f32_e32 vcc, s16, v116
	v_sub_f32_e32 v119, v119, v122
	v_mul_f32_e32 v27, 0xbfb8aa3b, v27
	v_cndmask_b32_e64 v120, 0, 32, vcc
	v_ldexp_f32 v116, v116, v120
	v_log_f32_e32 v116, v116
	v_add_f32_e32 v31, 1.0, v31
	v_exp_f32_e32 v27, v27
	v_mul_f32_e32 v32, 0xbfb8aa3b, v32
	v_mul_f32_e32 v120, 0x3f317217, v116
	v_fma_f32 v120, v116, s17, -v120
	v_fmac_f32_e32 v120, 0x3377d1cf, v116
	v_fmac_f32_e32 v120, 0x3f317217, v116
	v_cmp_lt_f32_e64 s[0:1], |v116|, s86
	v_add_f32_e32 v27, 1.0, v27
	v_exp_f32_e32 v32, v32
	v_cndmask_b32_e64 v116, v116, v120, s[0:1]
	v_cndmask_b32_e32 v120, 0, v224, vcc
	v_sub_f32_e32 v116, v116, v120
	v_fma_f32 v120, v134, v195, v135
	v_cmp_gt_f32_e32 vcc, s16, v120
	v_mul_f32_e32 v134, v194, v195
	v_mul_f32_e32 v28, 0xbfb8aa3b, v28
	v_cndmask_b32_e64 v122, 0, 32, vcc
	v_ldexp_f32 v120, v120, v122
	v_log_f32_e32 v120, v120
	v_add_f32_e32 v32, 1.0, v32
	v_exp_f32_e32 v28, v28
	v_mul_f32_e32 v33, 0xbfb8aa3b, v33
	v_mul_f32_e32 v122, 0x3f317217, v120
	v_fma_f32 v122, v120, s17, -v122
	v_fmac_f32_e32 v122, 0x3377d1cf, v120
	v_fmac_f32_e32 v122, 0x3f317217, v120
	v_cmp_lt_f32_e64 s[0:1], |v120|, s86
	v_add_f32_e32 v28, 1.0, v28
	v_exp_f32_e32 v33, v33
	v_cndmask_b32_e64 v120, v120, v122, s[0:1]
	v_cndmask_b32_e32 v122, 0, v224, vcc
	v_sub_f32_e32 v120, v120, v122
	v_pk_add_f32 v[122:123], v[138:139], 1.0 op_sel_hi:[1,0] neg_lo:[1,0] neg_hi:[1,0]
	v_mul_f32_e32 v29, 0xbfb8aa3b, v29
	v_fma_f32 v117, v138, v123, v139
	v_cmp_gt_f32_e32 vcc, s16, v117
	v_mul_f32_e32 v122, v122, v123
	v_add_f32_e32 v33, 1.0, v33
	v_cndmask_b32_e64 v121, 0, 32, vcc
	v_ldexp_f32 v117, v117, v121
	v_log_f32_e32 v117, v117
	v_exp_f32_e32 v29, v29
	v_mul_f32_e32 v22, 0xbfb8aa3b, v22
	v_exp_f32_e32 v22, v22
	v_mul_f32_e32 v121, 0x3f317217, v117
	v_fma_f32 v121, v117, s17, -v121
	v_fmac_f32_e32 v121, 0x3377d1cf, v117
	v_fmac_f32_e32 v121, 0x3f317217, v117
	v_cmp_lt_f32_e64 s[0:1], |v117|, s86
	v_add_f32_e32 v29, 1.0, v29
	v_mul_f32_e32 v18, 0xbfb8aa3b, v18
	v_cndmask_b32_e64 v117, v117, v121, s[0:1]
	v_cndmask_b32_e32 v121, 0, v224, vcc
	v_sub_f32_e32 v117, v117, v121
	v_fma_f32 v121, v130, v167, v131
	v_cmp_gt_f32_e32 vcc, s16, v121
	v_add_f32_e32 v22, 1.0, v22
	v_exp_f32_e32 v18, v18
	v_cndmask_b32_e64 v130, 0, 32, vcc
	v_ldexp_f32 v121, v121, v130
	v_log_f32_e32 v121, v121
	v_add_f32_e32 v18, 1.0, v18
	v_mul_f32_e32 v23, 0xbfb8aa3b, v23
	v_exp_f32_e32 v23, v23
	v_mul_f32_e32 v130, 0x3f317217, v121
	v_fma_f32 v130, v121, s17, -v130
	v_fmac_f32_e32 v130, 0x3377d1cf, v121
	v_fmac_f32_e32 v130, 0x3f317217, v121
	v_cmp_lt_f32_e64 s[0:1], |v121|, s86
	v_mul_f32_e32 v19, 0xbfb8aa3b, v19
	v_add_f32_e32 v23, 1.0, v23
	v_cndmask_b32_e64 v121, v121, v130, s[0:1]
	v_cndmask_b32_e32 v130, 0, v224, vcc
	v_sub_f32_e32 v121, v121, v130
	global_store_dwordx4 v[212:213], v[114:117], off offset:-3584 nt
	global_store_dwordx4 v[212:213], v[118:121], off offset:-3568 nt
	v_mul_f32_e32 v130, v166, v167
	v_cvt_pk_bf16_f32 v114, v128, v126
	v_cvt_pk_bf16_f32 v115, v124, v122
	v_cvt_pk_bf16_f32 v116, v132, v136
	v_cvt_pk_bf16_f32 v117, v134, v130
	global_store_dwordx4 v[214:215], v[114:117], off offset:256
	v_rcp_f32_e32 v118, v106
	v_rcp_f32_e32 v120, v107
	v_or_b32_e32 v114, 16, v164
	v_ashrrev_i32_e32 v115, 31, v114
	v_lshlrev_b64 v[116:117], 12, v[114:115]
	v_rcp_f32_e32 v115, v110
	v_rcp_f32_e32 v122, v108
	v_rcp_f32_e32 v126, v109
	v_lshl_add_u64 v[116:117], s[12:13], 0, v[116:117]
	v_fma_f32 v106, v115, v193, v171
	v_cmp_gt_f32_e32 vcc, s16, v106
	v_lshl_add_u64 v[116:117], v[116:117], 0, v[168:169]
	v_sub_f32_e32 v115, 1.0, v115
	v_cndmask_b32_e64 v110, 0, 32, vcc
	v_ldexp_f32 v106, v106, v110
	v_log_f32_e32 v106, v106
	v_mul_f32_e32 v115, v115, v193
	v_exp_f32_e32 v19, v19
	v_mul_f32_e32 v24, 0xbfb8aa3b, v24
	v_mul_f32_e32 v110, 0x3f317217, v106
	v_fma_f32 v110, v106, s17, -v110
	v_fmac_f32_e32 v110, 0x3377d1cf, v106
	v_fmac_f32_e32 v110, 0x3f317217, v106
	v_cmp_lt_f32_e64 s[0:1], |v106|, s86
	v_add_f32_e32 v19, 1.0, v19
	v_exp_f32_e32 v24, v24
	v_cndmask_b32_e64 v106, v106, v110, s[0:1]
	v_cndmask_b32_e32 v110, 0, v224, vcc
	v_sub_f32_e32 v106, v106, v110
	v_fma_f32 v110, v118, v207, v185
	v_cmp_gt_f32_e32 vcc, s16, v110
	v_sub_f32_e32 v118, 1.0, v118
	v_mul_f32_e32 v118, v118, v207
	v_cndmask_b32_e64 v119, 0, 32, vcc
	v_ldexp_f32 v110, v110, v119
	v_log_f32_e32 v110, v110
	v_mul_f32_e32 v20, 0xbfb8aa3b, v20
	v_add_f32_e32 v24, 1.0, v24
	v_exp_f32_e32 v20, v20
	v_mul_f32_e32 v119, 0x3f317217, v110
	v_fma_f32 v119, v110, s17, -v119
	v_fmac_f32_e32 v119, 0x3377d1cf, v110
	v_fmac_f32_e32 v119, 0x3f317217, v110
	v_cmp_lt_f32_e64 s[0:1], |v110|, s86
	v_add_f32_e32 v20, 1.0, v20
	v_mul_f32_e32 v25, 0xbfb8aa3b, v25
	v_cndmask_b32_e64 v110, v110, v119, s[0:1]
	v_cndmask_b32_e32 v119, 0, v224, vcc
	v_sub_f32_e32 v110, v110, v119
	v_rcp_f32_e32 v119, v111
	v_exp_f32_e32 v25, v25
	v_mul_f32_e32 v21, 0xbfb8aa3b, v21
	v_exp_f32_e32 v21, v21
	v_fma_f32 v107, v119, v191, v173
	v_cmp_gt_f32_e32 vcc, s16, v107
	v_sub_f32_e32 v119, 1.0, v119
	v_mul_f32_e32 v119, v119, v191
	v_cndmask_b32_e64 v111, 0, 32, vcc
	v_ldexp_f32 v107, v107, v111
	v_log_f32_e32 v107, v107
	v_add_f32_e32 v25, 1.0, v25
	v_add_f32_e32 v21, 1.0, v21
	v_mul_f32_e32 v14, 0xbfb8aa3b, v14
	v_mul_f32_e32 v111, 0x3f317217, v107
	v_fma_f32 v111, v107, s17, -v111
	v_fmac_f32_e32 v111, 0x3377d1cf, v107
	v_fmac_f32_e32 v111, 0x3f317217, v107
	v_cmp_lt_f32_e64 s[0:1], |v107|, s86
	v_exp_f32_e32 v14, v14
	v_mul_f32_e32 v10, 0xbfb8aa3b, v10
	v_cndmask_b32_e64 v107, v107, v111, s[0:1]
	v_cndmask_b32_e32 v111, 0, v224, vcc
	v_sub_f32_e32 v107, v107, v111
	v_fma_f32 v111, v120, v205, v183
	v_cmp_gt_f32_e32 vcc, s16, v111
	v_sub_f32_e32 v120, 1.0, v120
	v_mul_f32_e32 v120, v120, v205
	v_cndmask_b32_e64 v121, 0, 32, vcc
	v_ldexp_f32 v111, v111, v121
	v_log_f32_e32 v111, v111
	v_add_f32_e32 v14, 1.0, v14
	v_exp_f32_e32 v10, v10
	v_mul_f32_e32 v15, 0xbfb8aa3b, v15
	v_mul_f32_e32 v121, 0x3f317217, v111
	v_fma_f32 v121, v111, s17, -v121
	v_fmac_f32_e32 v121, 0x3377d1cf, v111
	v_fmac_f32_e32 v121, 0x3f317217, v111
	v_cmp_lt_f32_e64 s[0:1], |v111|, s86
	v_add_f32_e32 v10, 1.0, v10
	v_exp_f32_e32 v15, v15
	v_cndmask_b32_e64 v111, v111, v121, s[0:1]
	v_cndmask_b32_e32 v121, 0, v224, vcc
	v_sub_f32_e32 v111, v111, v121
	v_rcp_f32_e32 v121, v112
	v_add_f32_e32 v15, 1.0, v15
	v_mul_f32_e32 v11, 0xbfb8aa3b, v11
	v_exp_f32_e32 v11, v11
	v_fma_f32 v108, v121, v137, v175
	v_cmp_gt_f32_e32 vcc, s16, v108
	v_sub_f32_e32 v121, 1.0, v121
	v_mul_f32_e32 v121, v121, v137
	v_cndmask_b32_e64 v112, 0, 32, vcc
	v_ldexp_f32 v108, v108, v112
	v_log_f32_e32 v108, v108
	v_add_f32_e32 v11, 1.0, v11
	v_mul_f32_e32 v16, 0xbfb8aa3b, v16
	v_exp_f32_e32 v16, v16
	v_mul_f32_e32 v112, 0x3f317217, v108
	v_fma_f32 v112, v108, s17, -v112
	v_fmac_f32_e32 v112, 0x3377d1cf, v108
	v_fmac_f32_e32 v112, 0x3f317217, v108
	v_cmp_lt_f32_e64 s[0:1], |v108|, s86
	v_add_f32_e32 v16, 1.0, v16
	v_mul_f32_e32 v12, 0xbfb8aa3b, v12
	v_cndmask_b32_e64 v108, v108, v112, s[0:1]
	v_cndmask_b32_e32 v112, 0, v224, vcc
	v_sub_f32_e32 v108, v108, v112
	v_fma_f32 v112, v122, v203, v181
	v_cmp_gt_f32_e32 vcc, s16, v112
	v_sub_f32_e32 v122, 1.0, v122
	v_mul_f32_e32 v122, v122, v203
	v_cndmask_b32_e64 v124, 0, 32, vcc
	v_ldexp_f32 v112, v112, v124
	v_log_f32_e32 v112, v112
	v_exp_f32_e32 v12, v12
	v_mul_f32_e32 v17, 0xbfb8aa3b, v17
	v_exp_f32_e32 v17, v17
	v_mul_f32_e32 v124, 0x3f317217, v112
	v_fma_f32 v124, v112, s17, -v124
	v_fmac_f32_e32 v124, 0x3377d1cf, v112
	v_fmac_f32_e32 v124, 0x3f317217, v112
	v_cmp_lt_f32_e64 s[0:1], |v112|, s86
	v_add_f32_e32 v12, 1.0, v12
	v_add_f32_e32 v17, 1.0, v17
	v_cndmask_b32_e64 v112, v112, v124, s[0:1]
	v_cndmask_b32_e32 v124, 0, v224, vcc
	v_sub_f32_e32 v112, v112, v124
	v_rcp_f32_e32 v124, v113
	v_mul_f32_e32 v13, 0xbfb8aa3b, v13
	v_exp_f32_e32 v13, v13
	v_mul_f32_e32 v6, 0xbfb8aa3b, v6
	v_fma_f32 v109, v124, v133, v177
	v_cmp_gt_f32_e32 vcc, s16, v109
	v_sub_f32_e32 v124, 1.0, v124
	v_mul_f32_e32 v124, v124, v133
	v_cndmask_b32_e64 v113, 0, 32, vcc
	v_ldexp_f32 v109, v109, v113
	v_log_f32_e32 v109, v109
	v_add_f32_e32 v13, 1.0, v13
	v_exp_f32_e32 v6, v6
	v_mul_f32_e32 v2, 0xbfb8aa3b, v2
	v_mul_f32_e32 v113, 0x3f317217, v109
	v_fma_f32 v113, v109, s17, -v113
	v_fmac_f32_e32 v113, 0x3377d1cf, v109
	v_fmac_f32_e32 v113, 0x3f317217, v109
	v_cmp_lt_f32_e64 s[0:1], |v109|, s86
	v_add_f32_e32 v6, 1.0, v6
	v_exp_f32_e32 v2, v2
	v_cndmask_b32_e64 v109, v109, v113, s[0:1]
	v_cndmask_b32_e32 v113, 0, v224, vcc
	v_sub_f32_e32 v109, v109, v113
	v_fma_f32 v113, v126, v201, v179
	v_cmp_gt_f32_e32 vcc, s16, v113
	v_sub_f32_e32 v126, 1.0, v126
	v_mul_f32_e32 v126, v126, v201
	v_cndmask_b32_e64 v128, 0, 32, vcc
	v_ldexp_f32 v113, v113, v128
	v_log_f32_e32 v113, v113
	v_add_f32_e32 v2, 1.0, v2
	v_mul_f32_e32 v7, 0xbfb8aa3b, v7
	v_exp_f32_e32 v7, v7
	v_mul_f32_e32 v128, 0x3f317217, v113
	v_fma_f32 v128, v113, s17, -v128
	v_fmac_f32_e32 v128, 0x3377d1cf, v113
	v_fmac_f32_e32 v128, 0x3f317217, v113
	v_cmp_lt_f32_e64 s[0:1], |v113|, s86
	v_add_f32_e32 v7, 1.0, v7
	v_mul_f32_e32 v3, 0xbfb8aa3b, v3
	v_cndmask_b32_e64 v113, v113, v128, s[0:1]
	v_cndmask_b32_e32 v128, 0, v224, vcc
	v_sub_f32_e32 v113, v113, v128
	global_store_dwordx4 v[116:117], v[106:109], off offset:-4096 nt
	global_store_dwordx4 v[116:117], v[110:113], off offset:-4080 nt
	v_exp_f32_e32 v3, v3
	v_mad_i64_i32 v[106:107], s[0:1], v114, s8, v[208:209]
	v_cvt_pk_bf16_f32 v108, v115, v119
	v_lshl_add_u64 v[106:107], v[106:107], 0, v[210:211]
	v_cvt_pk_bf16_f32 v109, v121, v124
	v_cvt_pk_bf16_f32 v110, v118, v120
	v_cvt_pk_bf16_f32 v111, v122, v126
	global_store_dwordx4 v[106:107], v[108:111], off
	v_rcp_f32_e32 v113, v100
	v_rcp_f32_e32 v115, v101
	v_rcp_f32_e32 v108, v102
	v_rcp_f32_e32 v109, v98
	v_rcp_f32_e32 v111, v99
	v_add_f32_e32 v3, 1.0, v3
	v_fma_f32 v98, v108, v129, v189
	v_cmp_gt_f32_e32 vcc, s16, v98
	v_sub_f32_e32 v108, 1.0, v108
	v_mul_f32_e32 v108, v108, v129
	v_cndmask_b32_e64 v102, 0, 32, vcc
	v_ldexp_f32 v98, v98, v102
	v_log_f32_e32 v98, v98
	v_mul_f32_e32 v8, 0xbfb8aa3b, v8
	v_exp_f32_e32 v8, v8
	v_mul_f32_e32 v4, 0xbfb8aa3b, v4
	v_mul_f32_e32 v102, 0x3f317217, v98
	v_fma_f32 v102, v98, s17, -v102
	v_fmac_f32_e32 v102, 0x3377d1cf, v98
	v_fmac_f32_e32 v102, 0x3f317217, v98
	v_cmp_lt_f32_e64 s[0:1], |v98|, s86
	v_add_f32_e32 v8, 1.0, v8
	v_exp_f32_e32 v4, v4
	v_cndmask_b32_e64 v98, v98, v102, s[0:1]
	v_cndmask_b32_e32 v102, 0, v224, vcc
	v_sub_f32_e32 v98, v98, v102
	v_fma_f32 v102, v109, v199, v145
	v_cmp_gt_f32_e32 vcc, s16, v102
	v_sub_f32_e32 v109, 1.0, v109
	v_mul_f32_e32 v109, v109, v199
	v_cndmask_b32_e64 v110, 0, 32, vcc
	v_ldexp_f32 v102, v102, v110
	v_log_f32_e32 v102, v102
	v_add_f32_e32 v4, 1.0, v4
	v_mul_f32_e32 v9, 0xbfb8aa3b, v9
	v_exp_f32_e32 v9, v9
	v_mul_f32_e32 v110, 0x3f317217, v102
	v_fma_f32 v110, v102, s17, -v110
	v_fmac_f32_e32 v110, 0x3377d1cf, v102
	v_fmac_f32_e32 v110, 0x3f317217, v102
	v_cmp_lt_f32_e64 s[0:1], |v102|, s86
	v_add_f32_e32 v9, 1.0, v9
	v_mul_f32_e32 v5, 0xbfb8aa3b, v5
	v_cndmask_b32_e64 v102, v102, v110, s[0:1]
	v_cndmask_b32_e32 v110, 0, v224, vcc
	v_sub_f32_e32 v102, v102, v110
	v_rcp_f32_e32 v110, v103
	v_exp_f32_e32 v5, v5
	v_readlane_b32 s53, v254, 12
	v_readlane_b32 s54, v254, 13
	v_fma_f32 v99, v110, v127, v187
	v_cmp_gt_f32_e32 vcc, s16, v99
	v_sub_f32_e32 v110, 1.0, v110
	v_mul_f32_e32 v110, v110, v127
	v_cndmask_b32_e64 v103, 0, 32, vcc
	v_ldexp_f32 v99, v99, v103
	v_log_f32_e32 v99, v99
	v_add_f32_e32 v5, 1.0, v5
	v_readlane_b32 s55, v254, 14
	v_readlane_b32 s56, v254, 15
	v_mul_f32_e32 v103, 0x3f317217, v99
	v_fma_f32 v103, v99, s17, -v103
	v_fmac_f32_e32 v103, 0x3377d1cf, v99
	v_fmac_f32_e32 v103, 0x3f317217, v99
	v_cmp_lt_f32_e64 s[0:1], |v99|, s86
	v_readlane_b32 s57, v254, 16
	v_readlane_b32 s58, v254, 17
	v_cndmask_b32_e64 v99, v99, v103, s[0:1]
	v_cndmask_b32_e32 v103, 0, v224, vcc
	v_sub_f32_e32 v99, v99, v103
	v_fma_f32 v103, v111, v197, v141
	v_cmp_gt_f32_e32 vcc, s16, v103
	v_sub_f32_e32 v111, 1.0, v111
	v_mul_f32_e32 v111, v111, v197
	v_cndmask_b32_e64 v112, 0, 32, vcc
	v_ldexp_f32 v103, v103, v112
	v_log_f32_e32 v103, v103
	v_readlane_b32 s59, v254, 18
	v_readlane_b32 s60, v254, 19
	v_readlane_b32 s61, v254, 20
	v_mul_f32_e32 v112, 0x3f317217, v103
	v_fma_f32 v112, v103, s17, -v112
	v_fmac_f32_e32 v112, 0x3377d1cf, v103
	v_fmac_f32_e32 v112, 0x3f317217, v103
	v_cmp_lt_f32_e64 s[0:1], |v103|, s86
	v_readlane_b32 s64, v254, 23
	v_readlane_b32 s65, v254, 24
	v_cndmask_b32_e64 v103, v103, v112, s[0:1]
	v_cndmask_b32_e32 v112, 0, v224, vcc
	v_sub_f32_e32 v103, v103, v112
	v_rcp_f32_e32 v112, v104
	v_readlane_b32 s66, v254, 25
	v_readlane_b32 s67, v254, 26
	v_fma_f32 v100, v112, v125, v143
	v_cmp_gt_f32_e32 vcc, s16, v100
	v_sub_f32_e32 v112, 1.0, v112
	v_mul_f32_e32 v112, v112, v125
	v_cndmask_b32_e64 v104, 0, 32, vcc
	v_ldexp_f32 v100, v100, v104
	v_log_f32_e32 v100, v100
	s_nop 0
	v_mul_f32_e32 v104, 0x3f317217, v100
	v_fma_f32 v104, v100, s17, -v104
	v_fmac_f32_e32 v104, 0x3377d1cf, v100
	v_fmac_f32_e32 v104, 0x3f317217, v100
	v_cmp_lt_f32_e64 s[0:1], |v100|, s86
	s_nop 1
	v_cndmask_b32_e64 v100, v100, v104, s[0:1]
	v_cndmask_b32_e32 v104, 0, v224, vcc
	v_sub_f32_e32 v100, v100, v104
	v_fma_f32 v104, v113, v195, v135
	v_cmp_gt_f32_e32 vcc, s16, v104
	v_sub_f32_e32 v113, 1.0, v113
	v_mul_f32_e32 v113, v113, v195
	v_cndmask_b32_e64 v114, 0, 32, vcc
	v_ldexp_f32 v104, v104, v114
	v_log_f32_e32 v104, v104
	s_nop 0
	v_mul_f32_e32 v114, 0x3f317217, v104
	v_fma_f32 v114, v104, s17, -v114
	v_fmac_f32_e32 v114, 0x3377d1cf, v104
	v_fmac_f32_e32 v114, 0x3f317217, v104
	v_cmp_lt_f32_e64 s[0:1], |v104|, s86
	s_nop 1
	v_cndmask_b32_e64 v104, v104, v114, s[0:1]
	v_cndmask_b32_e32 v114, 0, v224, vcc
	v_sub_f32_e32 v104, v104, v114
	v_rcp_f32_e32 v114, v105
	s_nop 0
	v_fma_f32 v101, v114, v123, v139
	v_cmp_gt_f32_e32 vcc, s16, v101
	v_sub_f32_e32 v114, 1.0, v114
	v_mul_f32_e32 v114, v114, v123
	v_cndmask_b32_e64 v105, 0, 32, vcc
	v_ldexp_f32 v101, v101, v105
	v_log_f32_e32 v101, v101
	s_nop 0
	v_mul_f32_e32 v105, 0x3f317217, v101
	v_fma_f32 v105, v101, s17, -v105
	v_fmac_f32_e32 v105, 0x3377d1cf, v101
	v_fmac_f32_e32 v105, 0x3f317217, v101
	v_cmp_lt_f32_e64 s[0:1], |v101|, s86
	s_nop 1
	v_cndmask_b32_e64 v101, v101, v105, s[0:1]
	v_cndmask_b32_e32 v105, 0, v224, vcc
	v_sub_f32_e32 v101, v101, v105
	v_fma_f32 v105, v115, v167, v131
	v_cmp_gt_f32_e32 vcc, s16, v105
	v_sub_f32_e32 v115, 1.0, v115
	v_mul_f32_e32 v115, v115, v167
	v_cndmask_b32_e64 v118, 0, 32, vcc
	v_ldexp_f32 v105, v105, v118
	v_log_f32_e32 v105, v105
	s_nop 0
	v_mul_f32_e32 v118, 0x3f317217, v105
	v_fma_f32 v118, v105, s17, -v118
	v_fmac_f32_e32 v118, 0x3377d1cf, v105
	v_fmac_f32_e32 v118, 0x3f317217, v105
	v_cmp_lt_f32_e64 s[0:1], |v105|, s86
	s_nop 1
	v_cndmask_b32_e64 v105, v105, v118, s[0:1]
	v_cndmask_b32_e32 v118, 0, v224, vcc
	v_sub_f32_e32 v105, v105, v118
	global_store_dwordx4 v[116:117], v[98:101], off offset:-3584 nt
	global_store_dwordx4 v[116:117], v[102:105], off offset:-3568 nt
	s_nop 0
	v_cvt_pk_bf16_f32 v98, v108, v110
	v_cvt_pk_bf16_f32 v99, v112, v114
	v_cvt_pk_bf16_f32 v100, v109, v111
	v_cvt_pk_bf16_f32 v101, v113, v115
	global_store_dwordx4 v[106:107], v[98:101], off offset:256
	v_rcp_f32_e32 v102, v90
	v_rcp_f32_e32 v104, v91
	v_or_b32_e32 v98, 32, v164
	v_ashrrev_i32_e32 v99, 31, v98
	v_lshlrev_b64 v[100:101], 12, v[98:99]
	v_rcp_f32_e32 v99, v94
	v_rcp_f32_e32 v106, v92
	v_rcp_f32_e32 v108, v93
	v_lshl_add_u64 v[100:101], s[12:13], 0, v[100:101]
	v_fma_f32 v90, v99, v193, v171
	v_cmp_gt_f32_e32 vcc, s16, v90
	v_lshl_add_u64 v[100:101], v[100:101], 0, v[168:169]
	v_sub_f32_e32 v99, 1.0, v99
	v_cndmask_b32_e64 v94, 0, 32, vcc
	v_ldexp_f32 v90, v90, v94
	v_log_f32_e32 v90, v90
	v_mul_f32_e32 v99, v99, v193
	v_mul_f32_e32 v94, 0x3f317217, v90
	v_fma_f32 v94, v90, s17, -v94
	v_fmac_f32_e32 v94, 0x3377d1cf, v90
	v_fmac_f32_e32 v94, 0x3f317217, v90
	v_cmp_lt_f32_e64 s[0:1], |v90|, s86
	s_nop 1
	v_cndmask_b32_e64 v90, v90, v94, s[0:1]
	v_cndmask_b32_e32 v94, 0, v224, vcc
	v_sub_f32_e32 v90, v90, v94
	v_fma_f32 v94, v102, v207, v185
	v_cmp_gt_f32_e32 vcc, s16, v94
	v_sub_f32_e32 v102, 1.0, v102
	v_mul_f32_e32 v102, v102, v207
	v_cndmask_b32_e64 v103, 0, 32, vcc
	v_ldexp_f32 v94, v94, v103
	v_log_f32_e32 v94, v94
	s_nop 0
	v_mul_f32_e32 v103, 0x3f317217, v94
	v_fma_f32 v103, v94, s17, -v103
	v_fmac_f32_e32 v103, 0x3377d1cf, v94
	v_fmac_f32_e32 v103, 0x3f317217, v94
	v_cmp_lt_f32_e64 s[0:1], |v94|, s86
	s_nop 1
	v_cndmask_b32_e64 v94, v94, v103, s[0:1]
	v_cndmask_b32_e32 v103, 0, v224, vcc
	v_sub_f32_e32 v94, v94, v103
	v_rcp_f32_e32 v103, v95
	s_nop 0
	v_fma_f32 v91, v103, v191, v173
	v_cmp_gt_f32_e32 vcc, s16, v91
	v_sub_f32_e32 v103, 1.0, v103
	v_mul_f32_e32 v103, v103, v191
	v_cndmask_b32_e64 v95, 0, 32, vcc
	v_ldexp_f32 v91, v91, v95
	v_log_f32_e32 v91, v91
	s_nop 0
	v_mul_f32_e32 v95, 0x3f317217, v91
	v_fma_f32 v95, v91, s17, -v95
	v_fmac_f32_e32 v95, 0x3377d1cf, v91
	v_fmac_f32_e32 v95, 0x3f317217, v91
	v_cmp_lt_f32_e64 s[0:1], |v91|, s86
	s_nop 1
	v_cndmask_b32_e64 v91, v91, v95, s[0:1]
	v_cndmask_b32_e32 v95, 0, v224, vcc
	v_sub_f32_e32 v91, v91, v95
	v_fma_f32 v95, v104, v205, v183
	v_cmp_gt_f32_e32 vcc, s16, v95
	v_sub_f32_e32 v104, 1.0, v104
	v_mul_f32_e32 v104, v104, v205
	v_cndmask_b32_e64 v105, 0, 32, vcc
	v_ldexp_f32 v95, v95, v105
	v_log_f32_e32 v95, v95
	s_nop 0
	v_mul_f32_e32 v105, 0x3f317217, v95
	v_fma_f32 v105, v95, s17, -v105
	v_fmac_f32_e32 v105, 0x3377d1cf, v95
	v_fmac_f32_e32 v105, 0x3f317217, v95
	v_cmp_lt_f32_e64 s[0:1], |v95|, s86
	s_nop 1
	v_cndmask_b32_e64 v95, v95, v105, s[0:1]
	v_cndmask_b32_e32 v105, 0, v224, vcc
	v_sub_f32_e32 v95, v95, v105
	v_rcp_f32_e32 v105, v96
	s_nop 0
	v_fma_f32 v92, v105, v137, v175
	v_cmp_gt_f32_e32 vcc, s16, v92
	v_sub_f32_e32 v105, 1.0, v105
	v_mul_f32_e32 v105, v105, v137
	v_cndmask_b32_e64 v96, 0, 32, vcc
	v_ldexp_f32 v92, v92, v96
	v_log_f32_e32 v92, v92
	s_nop 0
	v_mul_f32_e32 v96, 0x3f317217, v92
	v_fma_f32 v96, v92, s17, -v96
	v_fmac_f32_e32 v96, 0x3377d1cf, v92
	v_fmac_f32_e32 v96, 0x3f317217, v92
	v_cmp_lt_f32_e64 s[0:1], |v92|, s86
	s_nop 1
	v_cndmask_b32_e64 v92, v92, v96, s[0:1]
	v_cndmask_b32_e32 v96, 0, v224, vcc
	v_sub_f32_e32 v92, v92, v96
	v_fma_f32 v96, v106, v203, v181
	v_cmp_gt_f32_e32 vcc, s16, v96
	v_sub_f32_e32 v106, 1.0, v106
	v_mul_f32_e32 v106, v106, v203
	v_cndmask_b32_e64 v107, 0, 32, vcc
	v_ldexp_f32 v96, v96, v107
	v_log_f32_e32 v96, v96
	s_nop 0
	v_mul_f32_e32 v107, 0x3f317217, v96
	v_fma_f32 v107, v96, s17, -v107
	v_fmac_f32_e32 v107, 0x3377d1cf, v96
	v_fmac_f32_e32 v107, 0x3f317217, v96
	v_cmp_lt_f32_e64 s[0:1], |v96|, s86
	s_nop 1
	v_cndmask_b32_e64 v96, v96, v107, s[0:1]
	v_cndmask_b32_e32 v107, 0, v224, vcc
	v_sub_f32_e32 v96, v96, v107
	v_rcp_f32_e32 v107, v97
	s_nop 0
	v_fma_f32 v93, v107, v133, v177
	v_cmp_gt_f32_e32 vcc, s16, v93
	v_sub_f32_e32 v107, 1.0, v107
	v_mul_f32_e32 v107, v107, v133
	v_cndmask_b32_e64 v97, 0, 32, vcc
	v_ldexp_f32 v93, v93, v97
	v_log_f32_e32 v93, v93
	s_nop 0
	v_mul_f32_e32 v97, 0x3f317217, v93
	v_fma_f32 v97, v93, s17, -v97
	v_fmac_f32_e32 v97, 0x3377d1cf, v93
	v_fmac_f32_e32 v97, 0x3f317217, v93
	v_cmp_lt_f32_e64 s[0:1], |v93|, s86
	s_nop 1
	v_cndmask_b32_e64 v93, v93, v97, s[0:1]
	v_cndmask_b32_e32 v97, 0, v224, vcc
	v_sub_f32_e32 v93, v93, v97
	v_fma_f32 v97, v108, v201, v179
	v_cmp_gt_f32_e32 vcc, s16, v97
	v_sub_f32_e32 v108, 1.0, v108
	v_mul_f32_e32 v108, v108, v201
	v_cndmask_b32_e64 v109, 0, 32, vcc
	v_ldexp_f32 v97, v97, v109
	v_log_f32_e32 v97, v97
	s_nop 0
	v_mul_f32_e32 v109, 0x3f317217, v97
	v_fma_f32 v109, v97, s17, -v109
	v_fmac_f32_e32 v109, 0x3377d1cf, v97
	v_fmac_f32_e32 v109, 0x3f317217, v97
	v_cmp_lt_f32_e64 s[0:1], |v97|, s86
	s_nop 1
	v_cndmask_b32_e64 v97, v97, v109, s[0:1]
	v_cndmask_b32_e32 v109, 0, v224, vcc
	v_sub_f32_e32 v97, v97, v109
	global_store_dwordx4 v[100:101], v[90:93], off offset:-4096 nt
	global_store_dwordx4 v[100:101], v[94:97], off offset:-4080 nt
	s_nop 0
	v_mad_i64_i32 v[90:91], s[0:1], v98, s8, v[208:209]
	v_cvt_pk_bf16_f32 v92, v99, v103
	v_lshl_add_u64 v[90:91], v[90:91], 0, v[210:211]
	v_cvt_pk_bf16_f32 v93, v105, v107
	v_cvt_pk_bf16_f32 v94, v102, v104
	v_cvt_pk_bf16_f32 v95, v106, v108
	global_store_dwordx4 v[90:91], v[92:95], off
	v_rcp_f32_e32 v97, v84
	v_rcp_f32_e32 v99, v85
	v_rcp_f32_e32 v92, v86
	v_rcp_f32_e32 v93, v82
	v_rcp_f32_e32 v95, v83
	v_fma_f32 v82, v92, v129, v189
	v_cmp_gt_f32_e32 vcc, s16, v82
	v_sub_f32_e32 v92, 1.0, v92
	v_mul_f32_e32 v92, v92, v129
	v_cndmask_b32_e64 v86, 0, 32, vcc
	v_ldexp_f32 v82, v82, v86
	v_log_f32_e32 v82, v82
	s_nop 0
	v_mul_f32_e32 v86, 0x3f317217, v82
	v_fma_f32 v86, v82, s17, -v86
	v_fmac_f32_e32 v86, 0x3377d1cf, v82
	v_fmac_f32_e32 v86, 0x3f317217, v82
	v_cmp_lt_f32_e64 s[0:1], |v82|, s86
	s_nop 1
	v_cndmask_b32_e64 v82, v82, v86, s[0:1]
	v_cndmask_b32_e32 v86, 0, v224, vcc
	v_sub_f32_e32 v82, v82, v86
	v_fma_f32 v86, v93, v199, v145
	v_cmp_gt_f32_e32 vcc, s16, v86
	v_sub_f32_e32 v93, 1.0, v93
	v_mul_f32_e32 v93, v93, v199
	v_cndmask_b32_e64 v94, 0, 32, vcc
	v_ldexp_f32 v86, v86, v94
	v_log_f32_e32 v86, v86
	s_nop 0
	v_mul_f32_e32 v94, 0x3f317217, v86
	v_fma_f32 v94, v86, s17, -v94
	v_fmac_f32_e32 v94, 0x3377d1cf, v86
	v_fmac_f32_e32 v94, 0x3f317217, v86
	v_cmp_lt_f32_e64 s[0:1], |v86|, s86
	s_nop 1
	v_cndmask_b32_e64 v86, v86, v94, s[0:1]
	v_cndmask_b32_e32 v94, 0, v224, vcc
	v_sub_f32_e32 v86, v86, v94
	v_rcp_f32_e32 v94, v87
	s_nop 0
	v_fma_f32 v83, v94, v127, v187
	v_cmp_gt_f32_e32 vcc, s16, v83
	v_sub_f32_e32 v94, 1.0, v94
	v_mul_f32_e32 v94, v94, v127
	v_cndmask_b32_e64 v87, 0, 32, vcc
	v_ldexp_f32 v83, v83, v87
	v_log_f32_e32 v83, v83
	s_nop 0
	v_mul_f32_e32 v87, 0x3f317217, v83
	v_fma_f32 v87, v83, s17, -v87
	v_fmac_f32_e32 v87, 0x3377d1cf, v83
	v_fmac_f32_e32 v87, 0x3f317217, v83
	v_cmp_lt_f32_e64 s[0:1], |v83|, s86
	s_nop 1
	v_cndmask_b32_e64 v83, v83, v87, s[0:1]
	v_cndmask_b32_e32 v87, 0, v224, vcc
	v_sub_f32_e32 v83, v83, v87
	v_fma_f32 v87, v95, v197, v141
	v_cmp_gt_f32_e32 vcc, s16, v87
	v_sub_f32_e32 v95, 1.0, v95
	v_mul_f32_e32 v95, v95, v197
	v_cndmask_b32_e64 v96, 0, 32, vcc
	v_ldexp_f32 v87, v87, v96
	v_log_f32_e32 v87, v87
	s_nop 0
	v_mul_f32_e32 v96, 0x3f317217, v87
	v_fma_f32 v96, v87, s17, -v96
	v_fmac_f32_e32 v96, 0x3377d1cf, v87
	v_fmac_f32_e32 v96, 0x3f317217, v87
	v_cmp_lt_f32_e64 s[0:1], |v87|, s86
	s_nop 1
	v_cndmask_b32_e64 v87, v87, v96, s[0:1]
	v_cndmask_b32_e32 v96, 0, v224, vcc
	v_sub_f32_e32 v87, v87, v96
	v_rcp_f32_e32 v96, v88
	s_nop 0
	v_fma_f32 v84, v96, v125, v143
	v_cmp_gt_f32_e32 vcc, s16, v84
	v_sub_f32_e32 v96, 1.0, v96
	v_mul_f32_e32 v96, v96, v125
	v_cndmask_b32_e64 v88, 0, 32, vcc
	v_ldexp_f32 v84, v84, v88
	v_log_f32_e32 v84, v84
	s_nop 0
	v_mul_f32_e32 v88, 0x3f317217, v84
	v_fma_f32 v88, v84, s17, -v88
	v_fmac_f32_e32 v88, 0x3377d1cf, v84
	v_fmac_f32_e32 v88, 0x3f317217, v84
	v_cmp_lt_f32_e64 s[0:1], |v84|, s86
	s_nop 1
	v_cndmask_b32_e64 v84, v84, v88, s[0:1]
	v_cndmask_b32_e32 v88, 0, v224, vcc
	v_sub_f32_e32 v84, v84, v88
	v_fma_f32 v88, v97, v195, v135
	v_cmp_gt_f32_e32 vcc, s16, v88
	v_sub_f32_e32 v97, 1.0, v97
	v_mul_f32_e32 v97, v97, v195
	v_cndmask_b32_e64 v98, 0, 32, vcc
	v_ldexp_f32 v88, v88, v98
	v_log_f32_e32 v88, v88
	s_nop 0
	v_mul_f32_e32 v98, 0x3f317217, v88
	v_fma_f32 v98, v88, s17, -v98
	v_fmac_f32_e32 v98, 0x3377d1cf, v88
	v_fmac_f32_e32 v98, 0x3f317217, v88
	v_cmp_lt_f32_e64 s[0:1], |v88|, s86
	s_nop 1
	v_cndmask_b32_e64 v88, v88, v98, s[0:1]
	v_cndmask_b32_e32 v98, 0, v224, vcc
	v_sub_f32_e32 v88, v88, v98
	v_rcp_f32_e32 v98, v89
	s_nop 0
	v_fma_f32 v85, v98, v123, v139
	v_cmp_gt_f32_e32 vcc, s16, v85
	v_sub_f32_e32 v98, 1.0, v98
	v_mul_f32_e32 v98, v98, v123
	v_cndmask_b32_e64 v89, 0, 32, vcc
	v_ldexp_f32 v85, v85, v89
	v_log_f32_e32 v85, v85
	s_nop 0
	v_mul_f32_e32 v89, 0x3f317217, v85
	v_fma_f32 v89, v85, s17, -v89
	v_fmac_f32_e32 v89, 0x3377d1cf, v85
	v_fmac_f32_e32 v89, 0x3f317217, v85
	v_cmp_lt_f32_e64 s[0:1], |v85|, s86
	s_nop 1
	v_cndmask_b32_e64 v85, v85, v89, s[0:1]
	v_cndmask_b32_e32 v89, 0, v224, vcc
	v_sub_f32_e32 v85, v85, v89
	v_fma_f32 v89, v99, v167, v131
	v_cmp_gt_f32_e32 vcc, s16, v89
	v_sub_f32_e32 v99, 1.0, v99
	v_mul_f32_e32 v99, v99, v167
	v_cndmask_b32_e64 v102, 0, 32, vcc
	v_ldexp_f32 v89, v89, v102
	v_log_f32_e32 v89, v89
	s_nop 0
	v_mul_f32_e32 v102, 0x3f317217, v89
	v_fma_f32 v102, v89, s17, -v102
	v_fmac_f32_e32 v102, 0x3377d1cf, v89
	v_fmac_f32_e32 v102, 0x3f317217, v89
	v_cmp_lt_f32_e64 s[0:1], |v89|, s86
	s_nop 1
	v_cndmask_b32_e64 v89, v89, v102, s[0:1]
	v_cndmask_b32_e32 v102, 0, v224, vcc
	v_sub_f32_e32 v89, v89, v102
	global_store_dwordx4 v[100:101], v[82:85], off offset:-3584 nt
	global_store_dwordx4 v[100:101], v[86:89], off offset:-3568 nt
	s_nop 0
	v_cvt_pk_bf16_f32 v82, v92, v94
	v_cvt_pk_bf16_f32 v83, v96, v98
	v_cvt_pk_bf16_f32 v84, v93, v95
	v_cvt_pk_bf16_f32 v85, v97, v99
	global_store_dwordx4 v[90:91], v[82:85], off offset:256
	v_rcp_f32_e32 v86, v74
	v_rcp_f32_e32 v88, v75
	v_or_b32_e32 v82, 48, v164
	v_ashrrev_i32_e32 v83, 31, v82
	v_lshlrev_b64 v[84:85], 12, v[82:83]
	v_rcp_f32_e32 v83, v78
	v_rcp_f32_e32 v90, v76
	v_rcp_f32_e32 v92, v77
	v_lshl_add_u64 v[84:85], s[12:13], 0, v[84:85]
	v_fma_f32 v74, v83, v193, v171
	v_cmp_gt_f32_e32 vcc, s16, v74
	v_lshl_add_u64 v[84:85], v[84:85], 0, v[168:169]
	v_sub_f32_e32 v83, 1.0, v83
	v_cndmask_b32_e64 v78, 0, 32, vcc
	v_ldexp_f32 v74, v74, v78
	v_log_f32_e32 v74, v74
	v_mul_f32_e32 v83, v83, v193
	v_mul_f32_e32 v78, 0x3f317217, v74
	v_fma_f32 v78, v74, s17, -v78
	v_fmac_f32_e32 v78, 0x3377d1cf, v74
	v_fmac_f32_e32 v78, 0x3f317217, v74
	v_cmp_lt_f32_e64 s[0:1], |v74|, s86
	s_nop 1
	v_cndmask_b32_e64 v74, v74, v78, s[0:1]
	v_cndmask_b32_e32 v78, 0, v224, vcc
	v_sub_f32_e32 v74, v74, v78
	v_fma_f32 v78, v86, v207, v185
	v_cmp_gt_f32_e32 vcc, s16, v78
	v_sub_f32_e32 v86, 1.0, v86
	v_mul_f32_e32 v86, v86, v207
	v_cndmask_b32_e64 v87, 0, 32, vcc
	v_ldexp_f32 v78, v78, v87
	v_log_f32_e32 v78, v78
	s_nop 0
	v_mul_f32_e32 v87, 0x3f317217, v78
	v_fma_f32 v87, v78, s17, -v87
	v_fmac_f32_e32 v87, 0x3377d1cf, v78
	v_fmac_f32_e32 v87, 0x3f317217, v78
	v_cmp_lt_f32_e64 s[0:1], |v78|, s86
	s_nop 1
	v_cndmask_b32_e64 v78, v78, v87, s[0:1]
	v_cndmask_b32_e32 v87, 0, v224, vcc
	v_sub_f32_e32 v78, v78, v87
	v_rcp_f32_e32 v87, v79
	s_nop 0
	v_fma_f32 v75, v87, v191, v173
	v_cmp_gt_f32_e32 vcc, s16, v75
	v_sub_f32_e32 v87, 1.0, v87
	v_mul_f32_e32 v87, v87, v191
	v_cndmask_b32_e64 v79, 0, 32, vcc
	v_ldexp_f32 v75, v75, v79
	v_log_f32_e32 v75, v75
	s_nop 0
	v_mul_f32_e32 v79, 0x3f317217, v75
	v_fma_f32 v79, v75, s17, -v79
	v_fmac_f32_e32 v79, 0x3377d1cf, v75
	v_fmac_f32_e32 v79, 0x3f317217, v75
	v_cmp_lt_f32_e64 s[0:1], |v75|, s86
	s_nop 1
	v_cndmask_b32_e64 v75, v75, v79, s[0:1]
	v_cndmask_b32_e32 v79, 0, v224, vcc
	v_sub_f32_e32 v75, v75, v79
	v_fma_f32 v79, v88, v205, v183
	v_cmp_gt_f32_e32 vcc, s16, v79
	v_sub_f32_e32 v88, 1.0, v88
	v_mul_f32_e32 v88, v88, v205
	v_cndmask_b32_e64 v89, 0, 32, vcc
	v_ldexp_f32 v79, v79, v89
	v_log_f32_e32 v79, v79
	s_nop 0
	v_mul_f32_e32 v89, 0x3f317217, v79
	v_fma_f32 v89, v79, s17, -v89
	v_fmac_f32_e32 v89, 0x3377d1cf, v79
	v_fmac_f32_e32 v89, 0x3f317217, v79
	v_cmp_lt_f32_e64 s[0:1], |v79|, s86
	s_nop 1
	v_cndmask_b32_e64 v79, v79, v89, s[0:1]
	v_cndmask_b32_e32 v89, 0, v224, vcc
	v_sub_f32_e32 v79, v79, v89
	v_rcp_f32_e32 v89, v80
	s_nop 0
	v_fma_f32 v76, v89, v137, v175
	v_cmp_gt_f32_e32 vcc, s16, v76
	v_sub_f32_e32 v89, 1.0, v89
	v_mul_f32_e32 v89, v89, v137
	v_cndmask_b32_e64 v80, 0, 32, vcc
	v_ldexp_f32 v76, v76, v80
	v_log_f32_e32 v76, v76
	s_nop 0
	v_mul_f32_e32 v80, 0x3f317217, v76
	v_fma_f32 v80, v76, s17, -v80
	v_fmac_f32_e32 v80, 0x3377d1cf, v76
	v_fmac_f32_e32 v80, 0x3f317217, v76
	v_cmp_lt_f32_e64 s[0:1], |v76|, s86
	s_nop 1
	v_cndmask_b32_e64 v76, v76, v80, s[0:1]
	v_cndmask_b32_e32 v80, 0, v224, vcc
	v_sub_f32_e32 v76, v76, v80
	v_fma_f32 v80, v90, v203, v181
	v_cmp_gt_f32_e32 vcc, s16, v80
	v_sub_f32_e32 v90, 1.0, v90
	v_mul_f32_e32 v90, v90, v203
	v_cndmask_b32_e64 v91, 0, 32, vcc
	v_ldexp_f32 v80, v80, v91
	v_log_f32_e32 v80, v80
	s_nop 0
	v_mul_f32_e32 v91, 0x3f317217, v80
	v_fma_f32 v91, v80, s17, -v91
	v_fmac_f32_e32 v91, 0x3377d1cf, v80
	v_fmac_f32_e32 v91, 0x3f317217, v80
	v_cmp_lt_f32_e64 s[0:1], |v80|, s86
	s_nop 1
	v_cndmask_b32_e64 v80, v80, v91, s[0:1]
	v_cndmask_b32_e32 v91, 0, v224, vcc
	v_sub_f32_e32 v80, v80, v91
	v_rcp_f32_e32 v91, v81
	s_nop 0
	v_fma_f32 v77, v91, v133, v177
	v_cmp_gt_f32_e32 vcc, s16, v77
	v_sub_f32_e32 v91, 1.0, v91
	v_mul_f32_e32 v91, v91, v133
	v_cndmask_b32_e64 v81, 0, 32, vcc
	v_ldexp_f32 v77, v77, v81
	v_log_f32_e32 v77, v77
	s_nop 0
	v_mul_f32_e32 v81, 0x3f317217, v77
	v_fma_f32 v81, v77, s17, -v81
	v_fmac_f32_e32 v81, 0x3377d1cf, v77
	v_fmac_f32_e32 v81, 0x3f317217, v77
	v_cmp_lt_f32_e64 s[0:1], |v77|, s86
	s_nop 1
	v_cndmask_b32_e64 v77, v77, v81, s[0:1]
	v_cndmask_b32_e32 v81, 0, v224, vcc
	v_sub_f32_e32 v77, v77, v81
	v_fma_f32 v81, v92, v201, v179
	v_cmp_gt_f32_e32 vcc, s16, v81
	v_sub_f32_e32 v92, 1.0, v92
	v_mul_f32_e32 v92, v92, v201
	v_cndmask_b32_e64 v93, 0, 32, vcc
	v_ldexp_f32 v81, v81, v93
	v_log_f32_e32 v81, v81
	s_nop 0
	v_mul_f32_e32 v93, 0x3f317217, v81
	v_fma_f32 v93, v81, s17, -v93
	v_fmac_f32_e32 v93, 0x3377d1cf, v81
	v_fmac_f32_e32 v93, 0x3f317217, v81
	v_cmp_lt_f32_e64 s[0:1], |v81|, s86
	s_nop 1
	v_cndmask_b32_e64 v81, v81, v93, s[0:1]
	v_cndmask_b32_e32 v93, 0, v224, vcc
	v_sub_f32_e32 v81, v81, v93
	global_store_dwordx4 v[84:85], v[74:77], off offset:-4096 nt
	global_store_dwordx4 v[84:85], v[78:81], off offset:-4080 nt
	s_nop 0
	v_mad_i64_i32 v[74:75], s[0:1], v82, s8, v[208:209]
	v_cvt_pk_bf16_f32 v76, v83, v87
	v_lshl_add_u64 v[74:75], v[74:75], 0, v[210:211]
	v_cvt_pk_bf16_f32 v77, v89, v91
	v_cvt_pk_bf16_f32 v78, v86, v88
	v_cvt_pk_bf16_f32 v79, v90, v92
	global_store_dwordx4 v[74:75], v[76:79], off
	v_rcp_f32_e32 v81, v68
	v_rcp_f32_e32 v83, v69
	v_rcp_f32_e32 v76, v70
	v_rcp_f32_e32 v77, v66
	v_rcp_f32_e32 v79, v67
	v_fma_f32 v66, v76, v129, v189
	v_cmp_gt_f32_e32 vcc, s16, v66
	v_sub_f32_e32 v76, 1.0, v76
	v_mul_f32_e32 v76, v76, v129
	v_cndmask_b32_e64 v70, 0, 32, vcc
	v_ldexp_f32 v66, v66, v70
	v_log_f32_e32 v66, v66
	s_nop 0
	v_mul_f32_e32 v70, 0x3f317217, v66
	v_fma_f32 v70, v66, s17, -v70
	v_fmac_f32_e32 v70, 0x3377d1cf, v66
	v_fmac_f32_e32 v70, 0x3f317217, v66
	v_cmp_lt_f32_e64 s[0:1], |v66|, s86
	s_nop 1
	v_cndmask_b32_e64 v66, v66, v70, s[0:1]
	v_cndmask_b32_e32 v70, 0, v224, vcc
	v_sub_f32_e32 v66, v66, v70
	v_fma_f32 v70, v77, v199, v145
	v_cmp_gt_f32_e32 vcc, s16, v70
	v_sub_f32_e32 v77, 1.0, v77
	v_mul_f32_e32 v77, v77, v199
	v_cndmask_b32_e64 v78, 0, 32, vcc
	v_ldexp_f32 v70, v70, v78
	v_log_f32_e32 v70, v70
	s_nop 0
	v_mul_f32_e32 v78, 0x3f317217, v70
	v_fma_f32 v78, v70, s17, -v78
	v_fmac_f32_e32 v78, 0x3377d1cf, v70
	v_fmac_f32_e32 v78, 0x3f317217, v70
	v_cmp_lt_f32_e64 s[0:1], |v70|, s86
	s_nop 1
	v_cndmask_b32_e64 v70, v70, v78, s[0:1]
	v_cndmask_b32_e32 v78, 0, v224, vcc
	v_sub_f32_e32 v70, v70, v78
	v_rcp_f32_e32 v78, v71
	s_nop 0
	v_fma_f32 v67, v78, v127, v187
	v_cmp_gt_f32_e32 vcc, s16, v67
	v_sub_f32_e32 v78, 1.0, v78
	v_mul_f32_e32 v78, v78, v127
	v_cndmask_b32_e64 v71, 0, 32, vcc
	v_ldexp_f32 v67, v67, v71
	v_log_f32_e32 v67, v67
	s_nop 0
	v_mul_f32_e32 v71, 0x3f317217, v67
	v_fma_f32 v71, v67, s17, -v71
	v_fmac_f32_e32 v71, 0x3377d1cf, v67
	v_fmac_f32_e32 v71, 0x3f317217, v67
	v_cmp_lt_f32_e64 s[0:1], |v67|, s86
	s_nop 1
	v_cndmask_b32_e64 v67, v67, v71, s[0:1]
	v_cndmask_b32_e32 v71, 0, v224, vcc
	v_sub_f32_e32 v67, v67, v71
	v_fma_f32 v71, v79, v197, v141
	v_cmp_gt_f32_e32 vcc, s16, v71
	v_sub_f32_e32 v79, 1.0, v79
	v_mul_f32_e32 v79, v79, v197
	v_cndmask_b32_e64 v80, 0, 32, vcc
	v_ldexp_f32 v71, v71, v80
	v_log_f32_e32 v71, v71
	s_nop 0
	v_mul_f32_e32 v80, 0x3f317217, v71
	v_fma_f32 v80, v71, s17, -v80
	v_fmac_f32_e32 v80, 0x3377d1cf, v71
	v_fmac_f32_e32 v80, 0x3f317217, v71
	v_cmp_lt_f32_e64 s[0:1], |v71|, s86
	s_nop 1
	v_cndmask_b32_e64 v71, v71, v80, s[0:1]
	v_cndmask_b32_e32 v80, 0, v224, vcc
	v_sub_f32_e32 v71, v71, v80
	v_rcp_f32_e32 v80, v72
	s_nop 0
	v_fma_f32 v68, v80, v125, v143
	v_cmp_gt_f32_e32 vcc, s16, v68
	v_sub_f32_e32 v80, 1.0, v80
	v_mul_f32_e32 v80, v80, v125
	v_cndmask_b32_e64 v72, 0, 32, vcc
	v_ldexp_f32 v68, v68, v72
	v_log_f32_e32 v68, v68
	s_nop 0
	v_mul_f32_e32 v72, 0x3f317217, v68
	v_fma_f32 v72, v68, s17, -v72
	v_fmac_f32_e32 v72, 0x3377d1cf, v68
	v_fmac_f32_e32 v72, 0x3f317217, v68
	v_cmp_lt_f32_e64 s[0:1], |v68|, s86
	s_nop 1
	v_cndmask_b32_e64 v68, v68, v72, s[0:1]
	v_cndmask_b32_e32 v72, 0, v224, vcc
	v_sub_f32_e32 v68, v68, v72
	v_fma_f32 v72, v81, v195, v135
	v_cmp_gt_f32_e32 vcc, s16, v72
	v_sub_f32_e32 v81, 1.0, v81
	v_mul_f32_e32 v81, v81, v195
	v_cndmask_b32_e64 v82, 0, 32, vcc
	v_ldexp_f32 v72, v72, v82
	v_log_f32_e32 v72, v72
	s_nop 0
	v_mul_f32_e32 v82, 0x3f317217, v72
	v_fma_f32 v82, v72, s17, -v82
	v_fmac_f32_e32 v82, 0x3377d1cf, v72
	v_fmac_f32_e32 v82, 0x3f317217, v72
	v_cmp_lt_f32_e64 s[0:1], |v72|, s86
	s_nop 1
	v_cndmask_b32_e64 v72, v72, v82, s[0:1]
	v_cndmask_b32_e32 v82, 0, v224, vcc
	v_sub_f32_e32 v72, v72, v82
	v_rcp_f32_e32 v82, v73
	s_nop 0
	v_fma_f32 v69, v82, v123, v139
	v_cmp_gt_f32_e32 vcc, s16, v69
	v_sub_f32_e32 v82, 1.0, v82
	v_mul_f32_e32 v82, v82, v123
	v_cndmask_b32_e64 v73, 0, 32, vcc
	v_ldexp_f32 v69, v69, v73
	v_log_f32_e32 v69, v69
	s_nop 0
	v_mul_f32_e32 v73, 0x3f317217, v69
	v_fma_f32 v73, v69, s17, -v73
	v_fmac_f32_e32 v73, 0x3377d1cf, v69
	v_fmac_f32_e32 v73, 0x3f317217, v69
	v_cmp_lt_f32_e64 s[0:1], |v69|, s86
	s_nop 1
	v_cndmask_b32_e64 v69, v69, v73, s[0:1]
	v_cndmask_b32_e32 v73, 0, v224, vcc
	v_sub_f32_e32 v69, v69, v73
	v_fma_f32 v73, v83, v167, v131
	v_cmp_gt_f32_e32 vcc, s16, v73
	v_sub_f32_e32 v83, 1.0, v83
	v_mul_f32_e32 v83, v83, v167
	v_cndmask_b32_e64 v86, 0, 32, vcc
	v_ldexp_f32 v73, v73, v86
	v_log_f32_e32 v73, v73
	s_nop 0
	v_mul_f32_e32 v86, 0x3f317217, v73
	v_fma_f32 v86, v73, s17, -v86
	v_fmac_f32_e32 v86, 0x3377d1cf, v73
	v_fmac_f32_e32 v86, 0x3f317217, v73
	v_cmp_lt_f32_e64 s[0:1], |v73|, s86
	s_nop 1
	v_cndmask_b32_e64 v73, v73, v86, s[0:1]
	v_cndmask_b32_e32 v86, 0, v224, vcc
	v_sub_f32_e32 v73, v73, v86
	global_store_dwordx4 v[84:85], v[66:69], off offset:-3584 nt
	global_store_dwordx4 v[84:85], v[70:73], off offset:-3568 nt
	s_nop 0
	v_cvt_pk_bf16_f32 v66, v76, v78
	v_cvt_pk_bf16_f32 v67, v80, v82
	v_cvt_pk_bf16_f32 v68, v77, v79
	v_cvt_pk_bf16_f32 v69, v81, v83
	global_store_dwordx4 v[74:75], v[66:69], off offset:256
	v_rcp_f32_e32 v70, v58
	v_rcp_f32_e32 v72, v59
	v_add_u32_e32 v66, 0x80, v164
	v_ashrrev_i32_e32 v67, 31, v66
	v_lshlrev_b64 v[68:69], 12, v[66:67]
	v_rcp_f32_e32 v67, v62
	v_rcp_f32_e32 v74, v60
	v_rcp_f32_e32 v76, v61
	v_lshl_add_u64 v[68:69], s[12:13], 0, v[68:69]
	v_fma_f32 v58, v67, v193, v171
	v_cmp_gt_f32_e32 vcc, s16, v58
	v_lshl_add_u64 v[68:69], v[68:69], 0, v[168:169]
	v_sub_f32_e32 v67, 1.0, v67
	v_cndmask_b32_e64 v62, 0, 32, vcc
	v_ldexp_f32 v58, v58, v62
	v_log_f32_e32 v58, v58
	v_mul_f32_e32 v67, v67, v193
	v_mul_f32_e32 v62, 0x3f317217, v58
	v_fma_f32 v62, v58, s17, -v62
	v_fmac_f32_e32 v62, 0x3377d1cf, v58
	v_fmac_f32_e32 v62, 0x3f317217, v58
	v_cmp_lt_f32_e64 s[0:1], |v58|, s86
	s_nop 1
	v_cndmask_b32_e64 v58, v58, v62, s[0:1]
	v_cndmask_b32_e32 v62, 0, v224, vcc
	v_sub_f32_e32 v58, v58, v62
	v_fma_f32 v62, v70, v207, v185
	v_cmp_gt_f32_e32 vcc, s16, v62
	v_sub_f32_e32 v70, 1.0, v70
	v_mul_f32_e32 v70, v70, v207
	v_cndmask_b32_e64 v71, 0, 32, vcc
	v_ldexp_f32 v62, v62, v71
	v_log_f32_e32 v62, v62
	s_nop 0
	v_mul_f32_e32 v71, 0x3f317217, v62
	v_fma_f32 v71, v62, s17, -v71
	v_fmac_f32_e32 v71, 0x3377d1cf, v62
	v_fmac_f32_e32 v71, 0x3f317217, v62
	v_cmp_lt_f32_e64 s[0:1], |v62|, s86
	s_nop 1
	v_cndmask_b32_e64 v62, v62, v71, s[0:1]
	v_cndmask_b32_e32 v71, 0, v224, vcc
	v_sub_f32_e32 v62, v62, v71
	v_rcp_f32_e32 v71, v63
	s_nop 0
	v_fma_f32 v59, v71, v191, v173
	v_cmp_gt_f32_e32 vcc, s16, v59
	v_sub_f32_e32 v71, 1.0, v71
	v_mul_f32_e32 v71, v71, v191
	v_cndmask_b32_e64 v63, 0, 32, vcc
	v_ldexp_f32 v59, v59, v63
	v_log_f32_e32 v59, v59
	s_nop 0
	v_mul_f32_e32 v63, 0x3f317217, v59
	v_fma_f32 v63, v59, s17, -v63
	v_fmac_f32_e32 v63, 0x3377d1cf, v59
	v_fmac_f32_e32 v63, 0x3f317217, v59
	v_cmp_lt_f32_e64 s[0:1], |v59|, s86
	s_nop 1
	v_cndmask_b32_e64 v59, v59, v63, s[0:1]
	v_cndmask_b32_e32 v63, 0, v224, vcc
	v_sub_f32_e32 v59, v59, v63
	v_fma_f32 v63, v72, v205, v183
	v_cmp_gt_f32_e32 vcc, s16, v63
	v_sub_f32_e32 v72, 1.0, v72
	v_mul_f32_e32 v72, v72, v205
	v_cndmask_b32_e64 v73, 0, 32, vcc
	v_ldexp_f32 v63, v63, v73
	v_log_f32_e32 v63, v63
	s_nop 0
	v_mul_f32_e32 v73, 0x3f317217, v63
	v_fma_f32 v73, v63, s17, -v73
	v_fmac_f32_e32 v73, 0x3377d1cf, v63
	v_fmac_f32_e32 v73, 0x3f317217, v63
	v_cmp_lt_f32_e64 s[0:1], |v63|, s86
	s_nop 1
	v_cndmask_b32_e64 v63, v63, v73, s[0:1]
	v_cndmask_b32_e32 v73, 0, v224, vcc
	v_sub_f32_e32 v63, v63, v73
	v_rcp_f32_e32 v73, v64
	s_nop 0
	v_fma_f32 v60, v73, v137, v175
	v_cmp_gt_f32_e32 vcc, s16, v60
	v_sub_f32_e32 v73, 1.0, v73
	v_mul_f32_e32 v73, v73, v137
	v_cndmask_b32_e64 v64, 0, 32, vcc
	v_ldexp_f32 v60, v60, v64
	v_log_f32_e32 v60, v60
	s_nop 0
	v_mul_f32_e32 v64, 0x3f317217, v60
	v_fma_f32 v64, v60, s17, -v64
	v_fmac_f32_e32 v64, 0x3377d1cf, v60
	v_fmac_f32_e32 v64, 0x3f317217, v60
	v_cmp_lt_f32_e64 s[0:1], |v60|, s86
	s_nop 1
	v_cndmask_b32_e64 v60, v60, v64, s[0:1]
	v_cndmask_b32_e32 v64, 0, v224, vcc
	v_sub_f32_e32 v60, v60, v64
	v_fma_f32 v64, v74, v203, v181
	v_cmp_gt_f32_e32 vcc, s16, v64
	v_sub_f32_e32 v74, 1.0, v74
	v_mul_f32_e32 v74, v74, v203
	v_cndmask_b32_e64 v75, 0, 32, vcc
	v_ldexp_f32 v64, v64, v75
	v_log_f32_e32 v64, v64
	s_nop 0
	v_mul_f32_e32 v75, 0x3f317217, v64
	v_fma_f32 v75, v64, s17, -v75
	v_fmac_f32_e32 v75, 0x3377d1cf, v64
	v_fmac_f32_e32 v75, 0x3f317217, v64
	v_cmp_lt_f32_e64 s[0:1], |v64|, s86
	s_nop 1
	v_cndmask_b32_e64 v64, v64, v75, s[0:1]
	v_cndmask_b32_e32 v75, 0, v224, vcc
	v_sub_f32_e32 v64, v64, v75
	v_rcp_f32_e32 v75, v65
	s_nop 0
	v_fma_f32 v61, v75, v133, v177
	v_cmp_gt_f32_e32 vcc, s16, v61
	v_sub_f32_e32 v75, 1.0, v75
	v_mul_f32_e32 v75, v75, v133
	v_cndmask_b32_e64 v65, 0, 32, vcc
	v_ldexp_f32 v61, v61, v65
	v_log_f32_e32 v61, v61
	s_nop 0
	v_mul_f32_e32 v65, 0x3f317217, v61
	v_fma_f32 v65, v61, s17, -v65
	v_fmac_f32_e32 v65, 0x3377d1cf, v61
	v_fmac_f32_e32 v65, 0x3f317217, v61
	v_cmp_lt_f32_e64 s[0:1], |v61|, s86
	s_nop 1
	v_cndmask_b32_e64 v61, v61, v65, s[0:1]
	v_cndmask_b32_e32 v65, 0, v224, vcc
	v_sub_f32_e32 v61, v61, v65
	v_fma_f32 v65, v76, v201, v179
	v_cmp_gt_f32_e32 vcc, s16, v65
	v_sub_f32_e32 v76, 1.0, v76
	v_mul_f32_e32 v76, v76, v201
	v_cndmask_b32_e64 v77, 0, 32, vcc
	v_ldexp_f32 v65, v65, v77
	v_log_f32_e32 v65, v65
	s_nop 0
	v_mul_f32_e32 v77, 0x3f317217, v65
	v_fma_f32 v77, v65, s17, -v77
	v_fmac_f32_e32 v77, 0x3377d1cf, v65
	v_fmac_f32_e32 v77, 0x3f317217, v65
	v_cmp_lt_f32_e64 s[0:1], |v65|, s86
	s_nop 1
	v_cndmask_b32_e64 v65, v65, v77, s[0:1]
	v_cndmask_b32_e32 v77, 0, v224, vcc
	v_sub_f32_e32 v65, v65, v77
	global_store_dwordx4 v[68:69], v[58:61], off offset:-4096 nt
	global_store_dwordx4 v[68:69], v[62:65], off offset:-4080 nt
	s_nop 0
	v_mad_i64_i32 v[58:59], s[0:1], v66, s8, v[208:209]
	v_cvt_pk_bf16_f32 v60, v67, v71
	v_lshl_add_u64 v[58:59], v[58:59], 0, v[210:211]
	v_cvt_pk_bf16_f32 v61, v73, v75
	v_cvt_pk_bf16_f32 v62, v70, v72
	v_cvt_pk_bf16_f32 v63, v74, v76
	global_store_dwordx4 v[58:59], v[60:63], off
	v_rcp_f32_e32 v65, v52
	v_rcp_f32_e32 v67, v53
	v_rcp_f32_e32 v60, v54
	v_rcp_f32_e32 v61, v50
	v_rcp_f32_e32 v63, v51
	v_fma_f32 v50, v60, v129, v189
	v_cmp_gt_f32_e32 vcc, s16, v50
	v_sub_f32_e32 v60, 1.0, v60
	v_mul_f32_e32 v60, v60, v129
	v_cndmask_b32_e64 v54, 0, 32, vcc
	v_ldexp_f32 v50, v50, v54
	v_log_f32_e32 v50, v50
	s_nop 0
	v_mul_f32_e32 v54, 0x3f317217, v50
	v_fma_f32 v54, v50, s17, -v54
	v_fmac_f32_e32 v54, 0x3377d1cf, v50
	v_fmac_f32_e32 v54, 0x3f317217, v50
	v_cmp_lt_f32_e64 s[0:1], |v50|, s86
	s_nop 1
	v_cndmask_b32_e64 v50, v50, v54, s[0:1]
	v_cndmask_b32_e32 v54, 0, v224, vcc
	v_sub_f32_e32 v50, v50, v54
	v_fma_f32 v54, v61, v199, v145
	v_cmp_gt_f32_e32 vcc, s16, v54
	v_sub_f32_e32 v61, 1.0, v61
	v_mul_f32_e32 v61, v61, v199
	v_cndmask_b32_e64 v62, 0, 32, vcc
	v_ldexp_f32 v54, v54, v62
	v_log_f32_e32 v54, v54
	s_nop 0
	v_mul_f32_e32 v62, 0x3f317217, v54
	v_fma_f32 v62, v54, s17, -v62
	v_fmac_f32_e32 v62, 0x3377d1cf, v54
	v_fmac_f32_e32 v62, 0x3f317217, v54
	v_cmp_lt_f32_e64 s[0:1], |v54|, s86
	s_nop 1
	v_cndmask_b32_e64 v54, v54, v62, s[0:1]
	v_cndmask_b32_e32 v62, 0, v224, vcc
	v_sub_f32_e32 v54, v54, v62
	v_rcp_f32_e32 v62, v55
	s_nop 0
	v_fma_f32 v51, v62, v127, v187
	v_cmp_gt_f32_e32 vcc, s16, v51
	v_sub_f32_e32 v62, 1.0, v62
	v_mul_f32_e32 v62, v62, v127
	v_cndmask_b32_e64 v55, 0, 32, vcc
	v_ldexp_f32 v51, v51, v55
	v_log_f32_e32 v51, v51
	s_nop 0
	v_mul_f32_e32 v55, 0x3f317217, v51
	v_fma_f32 v55, v51, s17, -v55
	v_fmac_f32_e32 v55, 0x3377d1cf, v51
	v_fmac_f32_e32 v55, 0x3f317217, v51
	v_cmp_lt_f32_e64 s[0:1], |v51|, s86
	s_nop 1
	v_cndmask_b32_e64 v51, v51, v55, s[0:1]
	v_cndmask_b32_e32 v55, 0, v224, vcc
	v_sub_f32_e32 v51, v51, v55
	v_fma_f32 v55, v63, v197, v141
	v_cmp_gt_f32_e32 vcc, s16, v55
	v_sub_f32_e32 v63, 1.0, v63
	v_mul_f32_e32 v63, v63, v197
	v_cndmask_b32_e64 v64, 0, 32, vcc
	v_ldexp_f32 v55, v55, v64
	v_log_f32_e32 v55, v55
	s_nop 0
	v_mul_f32_e32 v64, 0x3f317217, v55
	v_fma_f32 v64, v55, s17, -v64
	v_fmac_f32_e32 v64, 0x3377d1cf, v55
	v_fmac_f32_e32 v64, 0x3f317217, v55
	v_cmp_lt_f32_e64 s[0:1], |v55|, s86
	s_nop 1
	v_cndmask_b32_e64 v55, v55, v64, s[0:1]
	v_cndmask_b32_e32 v64, 0, v224, vcc
	v_sub_f32_e32 v55, v55, v64
	v_rcp_f32_e32 v64, v56
	s_nop 0
	v_fma_f32 v52, v64, v125, v143
	v_cmp_gt_f32_e32 vcc, s16, v52
	v_sub_f32_e32 v64, 1.0, v64
	v_mul_f32_e32 v64, v64, v125
	v_cndmask_b32_e64 v56, 0, 32, vcc
	v_ldexp_f32 v52, v52, v56
	v_log_f32_e32 v52, v52
	s_nop 0
	v_mul_f32_e32 v56, 0x3f317217, v52
	v_fma_f32 v56, v52, s17, -v56
	v_fmac_f32_e32 v56, 0x3377d1cf, v52
	v_fmac_f32_e32 v56, 0x3f317217, v52
	v_cmp_lt_f32_e64 s[0:1], |v52|, s86
	s_nop 1
	v_cndmask_b32_e64 v52, v52, v56, s[0:1]
	v_cndmask_b32_e32 v56, 0, v224, vcc
	v_sub_f32_e32 v52, v52, v56
	v_fma_f32 v56, v65, v195, v135
	v_cmp_gt_f32_e32 vcc, s16, v56
	v_sub_f32_e32 v65, 1.0, v65
	v_mul_f32_e32 v65, v65, v195
	v_cndmask_b32_e64 v66, 0, 32, vcc
	v_ldexp_f32 v56, v56, v66
	v_log_f32_e32 v56, v56
	s_nop 0
	v_mul_f32_e32 v66, 0x3f317217, v56
	v_fma_f32 v66, v56, s17, -v66
	v_fmac_f32_e32 v66, 0x3377d1cf, v56
	v_fmac_f32_e32 v66, 0x3f317217, v56
	v_cmp_lt_f32_e64 s[0:1], |v56|, s86
	s_nop 1
	v_cndmask_b32_e64 v56, v56, v66, s[0:1]
	v_cndmask_b32_e32 v66, 0, v224, vcc
	v_sub_f32_e32 v56, v56, v66
	v_rcp_f32_e32 v66, v57
	s_nop 0
	v_fma_f32 v53, v66, v123, v139
	v_cmp_gt_f32_e32 vcc, s16, v53
	v_sub_f32_e32 v66, 1.0, v66
	v_mul_f32_e32 v66, v66, v123
	v_cndmask_b32_e64 v57, 0, 32, vcc
	v_ldexp_f32 v53, v53, v57
	v_log_f32_e32 v53, v53
	s_nop 0
	v_mul_f32_e32 v57, 0x3f317217, v53
	v_fma_f32 v57, v53, s17, -v57
	v_fmac_f32_e32 v57, 0x3377d1cf, v53
	v_fmac_f32_e32 v57, 0x3f317217, v53
	v_cmp_lt_f32_e64 s[0:1], |v53|, s86
	s_nop 1
	v_cndmask_b32_e64 v53, v53, v57, s[0:1]
	v_cndmask_b32_e32 v57, 0, v224, vcc
	v_sub_f32_e32 v53, v53, v57
	v_fma_f32 v57, v67, v167, v131
	v_cmp_gt_f32_e32 vcc, s16, v57
	v_sub_f32_e32 v67, 1.0, v67
	v_mul_f32_e32 v67, v67, v167
	v_cndmask_b32_e64 v70, 0, 32, vcc
	v_ldexp_f32 v57, v57, v70
	v_log_f32_e32 v57, v57
	s_nop 0
	v_mul_f32_e32 v70, 0x3f317217, v57
	v_fma_f32 v70, v57, s17, -v70
	v_fmac_f32_e32 v70, 0x3377d1cf, v57
	v_fmac_f32_e32 v70, 0x3f317217, v57
	v_cmp_lt_f32_e64 s[0:1], |v57|, s86
	s_nop 1
	v_cndmask_b32_e64 v57, v57, v70, s[0:1]
	v_cndmask_b32_e32 v70, 0, v224, vcc
	v_sub_f32_e32 v57, v57, v70
	global_store_dwordx4 v[68:69], v[50:53], off offset:-3584 nt
	global_store_dwordx4 v[68:69], v[54:57], off offset:-3568 nt
	s_nop 0
	v_cvt_pk_bf16_f32 v50, v60, v62
	v_cvt_pk_bf16_f32 v51, v64, v66
	v_cvt_pk_bf16_f32 v52, v61, v63
	v_cvt_pk_bf16_f32 v53, v65, v67
	global_store_dwordx4 v[58:59], v[50:53], off offset:256
	v_rcp_f32_e32 v54, v42
	v_rcp_f32_e32 v56, v43
	v_add_u32_e32 v50, 0x90, v164
	v_ashrrev_i32_e32 v51, 31, v50
	v_lshlrev_b64 v[52:53], 12, v[50:51]
	v_rcp_f32_e32 v51, v46
	v_rcp_f32_e32 v58, v44
	v_rcp_f32_e32 v60, v45
	v_lshl_add_u64 v[52:53], s[12:13], 0, v[52:53]
	v_fma_f32 v42, v51, v193, v171
	v_cmp_gt_f32_e32 vcc, s16, v42
	v_lshl_add_u64 v[52:53], v[52:53], 0, v[168:169]
	v_sub_f32_e32 v51, 1.0, v51
	v_cndmask_b32_e64 v46, 0, 32, vcc
	v_ldexp_f32 v42, v42, v46
	v_log_f32_e32 v42, v42
	v_mul_f32_e32 v51, v51, v193
	v_mul_f32_e32 v46, 0x3f317217, v42
	v_fma_f32 v46, v42, s17, -v46
	v_fmac_f32_e32 v46, 0x3377d1cf, v42
	v_fmac_f32_e32 v46, 0x3f317217, v42
	v_cmp_lt_f32_e64 s[0:1], |v42|, s86
	s_nop 1
	v_cndmask_b32_e64 v42, v42, v46, s[0:1]
	v_cndmask_b32_e32 v46, 0, v224, vcc
	v_sub_f32_e32 v42, v42, v46
	v_fma_f32 v46, v54, v207, v185
	v_cmp_gt_f32_e32 vcc, s16, v46
	v_sub_f32_e32 v54, 1.0, v54
	v_mul_f32_e32 v54, v54, v207
	v_cndmask_b32_e64 v55, 0, 32, vcc
	v_ldexp_f32 v46, v46, v55
	v_log_f32_e32 v46, v46
	s_nop 0
	v_mul_f32_e32 v55, 0x3f317217, v46
	v_fma_f32 v55, v46, s17, -v55
	v_fmac_f32_e32 v55, 0x3377d1cf, v46
	v_fmac_f32_e32 v55, 0x3f317217, v46
	v_cmp_lt_f32_e64 s[0:1], |v46|, s86
	s_nop 1
	v_cndmask_b32_e64 v46, v46, v55, s[0:1]
	v_cndmask_b32_e32 v55, 0, v224, vcc
	v_sub_f32_e32 v46, v46, v55
	v_rcp_f32_e32 v55, v47
	s_nop 0
	v_fma_f32 v43, v55, v191, v173
	v_cmp_gt_f32_e32 vcc, s16, v43
	v_sub_f32_e32 v55, 1.0, v55
	v_mul_f32_e32 v55, v55, v191
	v_cndmask_b32_e64 v47, 0, 32, vcc
	v_ldexp_f32 v43, v43, v47
	v_log_f32_e32 v43, v43
	s_nop 0
	v_mul_f32_e32 v47, 0x3f317217, v43
	v_fma_f32 v47, v43, s17, -v47
	v_fmac_f32_e32 v47, 0x3377d1cf, v43
	v_fmac_f32_e32 v47, 0x3f317217, v43
	v_cmp_lt_f32_e64 s[0:1], |v43|, s86
	s_nop 1
	v_cndmask_b32_e64 v43, v43, v47, s[0:1]
	v_cndmask_b32_e32 v47, 0, v224, vcc
	v_sub_f32_e32 v43, v43, v47
	v_fma_f32 v47, v56, v205, v183
	v_cmp_gt_f32_e32 vcc, s16, v47
	v_sub_f32_e32 v56, 1.0, v56
	v_mul_f32_e32 v56, v56, v205
	v_cndmask_b32_e64 v57, 0, 32, vcc
	v_ldexp_f32 v47, v47, v57
	v_log_f32_e32 v47, v47
	s_nop 0
	v_mul_f32_e32 v57, 0x3f317217, v47
	v_fma_f32 v57, v47, s17, -v57
	v_fmac_f32_e32 v57, 0x3377d1cf, v47
	v_fmac_f32_e32 v57, 0x3f317217, v47
	v_cmp_lt_f32_e64 s[0:1], |v47|, s86
	s_nop 1
	v_cndmask_b32_e64 v47, v47, v57, s[0:1]
	v_cndmask_b32_e32 v57, 0, v224, vcc
	v_sub_f32_e32 v47, v47, v57
	v_rcp_f32_e32 v57, v48
	s_nop 0
	v_fma_f32 v44, v57, v137, v175
	v_cmp_gt_f32_e32 vcc, s16, v44
	v_sub_f32_e32 v57, 1.0, v57
	v_mul_f32_e32 v57, v57, v137
	v_cndmask_b32_e64 v48, 0, 32, vcc
	v_ldexp_f32 v44, v44, v48
	v_log_f32_e32 v44, v44
	s_nop 0
	v_mul_f32_e32 v48, 0x3f317217, v44
	v_fma_f32 v48, v44, s17, -v48
	v_fmac_f32_e32 v48, 0x3377d1cf, v44
	v_fmac_f32_e32 v48, 0x3f317217, v44
	v_cmp_lt_f32_e64 s[0:1], |v44|, s86
	s_nop 1
	v_cndmask_b32_e64 v44, v44, v48, s[0:1]
	v_cndmask_b32_e32 v48, 0, v224, vcc
	v_sub_f32_e32 v44, v44, v48
	v_fma_f32 v48, v58, v203, v181
	v_cmp_gt_f32_e32 vcc, s16, v48
	v_sub_f32_e32 v58, 1.0, v58
	v_mul_f32_e32 v58, v58, v203
	v_cndmask_b32_e64 v59, 0, 32, vcc
	v_ldexp_f32 v48, v48, v59
	v_log_f32_e32 v48, v48
	s_nop 0
	v_mul_f32_e32 v59, 0x3f317217, v48
	v_fma_f32 v59, v48, s17, -v59
	v_fmac_f32_e32 v59, 0x3377d1cf, v48
	v_fmac_f32_e32 v59, 0x3f317217, v48
	v_cmp_lt_f32_e64 s[0:1], |v48|, s86
	s_nop 1
	v_cndmask_b32_e64 v48, v48, v59, s[0:1]
	v_cndmask_b32_e32 v59, 0, v224, vcc
	v_sub_f32_e32 v48, v48, v59
	v_rcp_f32_e32 v59, v49
	s_nop 0
	v_fma_f32 v45, v59, v133, v177
	v_cmp_gt_f32_e32 vcc, s16, v45
	v_sub_f32_e32 v59, 1.0, v59
	v_mul_f32_e32 v59, v59, v133
	v_cndmask_b32_e64 v49, 0, 32, vcc
	v_ldexp_f32 v45, v45, v49
	v_log_f32_e32 v45, v45
	s_nop 0
	v_mul_f32_e32 v49, 0x3f317217, v45
	v_fma_f32 v49, v45, s17, -v49
	v_fmac_f32_e32 v49, 0x3377d1cf, v45
	v_fmac_f32_e32 v49, 0x3f317217, v45
	v_cmp_lt_f32_e64 s[0:1], |v45|, s86
	s_nop 1
	v_cndmask_b32_e64 v45, v45, v49, s[0:1]
	v_cndmask_b32_e32 v49, 0, v224, vcc
	v_sub_f32_e32 v45, v45, v49
	v_fma_f32 v49, v60, v201, v179
	v_cmp_gt_f32_e32 vcc, s16, v49
	v_sub_f32_e32 v60, 1.0, v60
	v_mul_f32_e32 v60, v60, v201
	v_cndmask_b32_e64 v61, 0, 32, vcc
	v_ldexp_f32 v49, v49, v61
	v_log_f32_e32 v49, v49
	s_nop 0
	v_mul_f32_e32 v61, 0x3f317217, v49
	v_fma_f32 v61, v49, s17, -v61
	v_fmac_f32_e32 v61, 0x3377d1cf, v49
	v_fmac_f32_e32 v61, 0x3f317217, v49
	v_cmp_lt_f32_e64 s[0:1], |v49|, s86
	s_nop 1
	v_cndmask_b32_e64 v49, v49, v61, s[0:1]
	v_cndmask_b32_e32 v61, 0, v224, vcc
	v_sub_f32_e32 v49, v49, v61
	global_store_dwordx4 v[52:53], v[42:45], off offset:-4096 nt
	global_store_dwordx4 v[52:53], v[46:49], off offset:-4080 nt
	s_nop 0
	v_mad_i64_i32 v[42:43], s[0:1], v50, s8, v[208:209]
	v_cvt_pk_bf16_f32 v44, v51, v55
	v_lshl_add_u64 v[42:43], v[42:43], 0, v[210:211]
	v_cvt_pk_bf16_f32 v45, v57, v59
	v_cvt_pk_bf16_f32 v46, v54, v56
	v_cvt_pk_bf16_f32 v47, v58, v60
	global_store_dwordx4 v[42:43], v[44:47], off
	v_rcp_f32_e32 v49, v36
	v_rcp_f32_e32 v51, v37
	v_rcp_f32_e32 v44, v38
	v_rcp_f32_e32 v45, v34
	v_rcp_f32_e32 v47, v35
	v_fma_f32 v34, v44, v129, v189
	v_cmp_gt_f32_e32 vcc, s16, v34
	v_sub_f32_e32 v44, 1.0, v44
	v_mul_f32_e32 v44, v44, v129
	v_cndmask_b32_e64 v38, 0, 32, vcc
	v_ldexp_f32 v34, v34, v38
	v_log_f32_e32 v34, v34
	s_nop 0
	v_mul_f32_e32 v38, 0x3f317217, v34
	v_fma_f32 v38, v34, s17, -v38
	v_fmac_f32_e32 v38, 0x3377d1cf, v34
	v_fmac_f32_e32 v38, 0x3f317217, v34
	v_cmp_lt_f32_e64 s[0:1], |v34|, s86
	s_nop 1
	v_cndmask_b32_e64 v34, v34, v38, s[0:1]
	v_cndmask_b32_e32 v38, 0, v224, vcc
	v_sub_f32_e32 v34, v34, v38
	v_fma_f32 v38, v45, v199, v145
	v_cmp_gt_f32_e32 vcc, s16, v38
	v_sub_f32_e32 v45, 1.0, v45
	v_mul_f32_e32 v45, v45, v199
	v_cndmask_b32_e64 v46, 0, 32, vcc
	v_ldexp_f32 v38, v38, v46
	v_log_f32_e32 v38, v38
	s_nop 0
	v_mul_f32_e32 v46, 0x3f317217, v38
	v_fma_f32 v46, v38, s17, -v46
	v_fmac_f32_e32 v46, 0x3377d1cf, v38
	v_fmac_f32_e32 v46, 0x3f317217, v38
	v_cmp_lt_f32_e64 s[0:1], |v38|, s86
	s_nop 1
	v_cndmask_b32_e64 v38, v38, v46, s[0:1]
	v_cndmask_b32_e32 v46, 0, v224, vcc
	v_sub_f32_e32 v38, v38, v46
	v_rcp_f32_e32 v46, v39
	s_nop 0
	v_fma_f32 v35, v46, v127, v187
	v_cmp_gt_f32_e32 vcc, s16, v35
	v_sub_f32_e32 v46, 1.0, v46
	v_mul_f32_e32 v46, v46, v127
	v_cndmask_b32_e64 v39, 0, 32, vcc
	v_ldexp_f32 v35, v35, v39
	v_log_f32_e32 v35, v35
	s_nop 0
	v_mul_f32_e32 v39, 0x3f317217, v35
	v_fma_f32 v39, v35, s17, -v39
	v_fmac_f32_e32 v39, 0x3377d1cf, v35
	v_fmac_f32_e32 v39, 0x3f317217, v35
	v_cmp_lt_f32_e64 s[0:1], |v35|, s86
	s_nop 1
	v_cndmask_b32_e64 v35, v35, v39, s[0:1]
	v_cndmask_b32_e32 v39, 0, v224, vcc
	v_sub_f32_e32 v35, v35, v39
	v_fma_f32 v39, v47, v197, v141
	v_cmp_gt_f32_e32 vcc, s16, v39
	v_sub_f32_e32 v47, 1.0, v47
	v_mul_f32_e32 v47, v47, v197
	v_cndmask_b32_e64 v48, 0, 32, vcc
	v_ldexp_f32 v39, v39, v48
	v_log_f32_e32 v39, v39
	s_nop 0
	v_mul_f32_e32 v48, 0x3f317217, v39
	v_fma_f32 v48, v39, s17, -v48
	v_fmac_f32_e32 v48, 0x3377d1cf, v39
	v_fmac_f32_e32 v48, 0x3f317217, v39
	v_cmp_lt_f32_e64 s[0:1], |v39|, s86
	s_nop 1
	v_cndmask_b32_e64 v39, v39, v48, s[0:1]
	v_cndmask_b32_e32 v48, 0, v224, vcc
	v_sub_f32_e32 v39, v39, v48
	v_rcp_f32_e32 v48, v40
	s_nop 0
	v_fma_f32 v36, v48, v125, v143
	v_cmp_gt_f32_e32 vcc, s16, v36
	v_sub_f32_e32 v48, 1.0, v48
	v_mul_f32_e32 v48, v48, v125
	v_cndmask_b32_e64 v40, 0, 32, vcc
	v_ldexp_f32 v36, v36, v40
	v_log_f32_e32 v36, v36
	s_nop 0
	v_mul_f32_e32 v40, 0x3f317217, v36
	v_fma_f32 v40, v36, s17, -v40
	v_fmac_f32_e32 v40, 0x3377d1cf, v36
	v_fmac_f32_e32 v40, 0x3f317217, v36
	v_cmp_lt_f32_e64 s[0:1], |v36|, s86
	s_nop 1
	v_cndmask_b32_e64 v36, v36, v40, s[0:1]
	v_cndmask_b32_e32 v40, 0, v224, vcc
	v_sub_f32_e32 v36, v36, v40
	v_fma_f32 v40, v49, v195, v135
	v_cmp_gt_f32_e32 vcc, s16, v40
	v_sub_f32_e32 v49, 1.0, v49
	v_mul_f32_e32 v49, v49, v195
	v_cndmask_b32_e64 v50, 0, 32, vcc
	v_ldexp_f32 v40, v40, v50
	v_log_f32_e32 v40, v40
	s_nop 0
	v_mul_f32_e32 v50, 0x3f317217, v40
	v_fma_f32 v50, v40, s17, -v50
	v_fmac_f32_e32 v50, 0x3377d1cf, v40
	v_fmac_f32_e32 v50, 0x3f317217, v40
	v_cmp_lt_f32_e64 s[0:1], |v40|, s86
	s_nop 1
	v_cndmask_b32_e64 v40, v40, v50, s[0:1]
	v_cndmask_b32_e32 v50, 0, v224, vcc
	v_sub_f32_e32 v40, v40, v50
	v_rcp_f32_e32 v50, v41
	s_nop 0
	v_fma_f32 v37, v50, v123, v139
	v_cmp_gt_f32_e32 vcc, s16, v37
	v_sub_f32_e32 v50, 1.0, v50
	v_mul_f32_e32 v50, v50, v123
	v_cndmask_b32_e64 v41, 0, 32, vcc
	v_ldexp_f32 v37, v37, v41
	v_log_f32_e32 v37, v37
	s_nop 0
	v_mul_f32_e32 v41, 0x3f317217, v37
	v_fma_f32 v41, v37, s17, -v41
	v_fmac_f32_e32 v41, 0x3377d1cf, v37
	v_fmac_f32_e32 v41, 0x3f317217, v37
	v_cmp_lt_f32_e64 s[0:1], |v37|, s86
	s_nop 1
	v_cndmask_b32_e64 v37, v37, v41, s[0:1]
	v_cndmask_b32_e32 v41, 0, v224, vcc
	v_sub_f32_e32 v37, v37, v41
	v_fma_f32 v41, v51, v167, v131
	v_cmp_gt_f32_e32 vcc, s16, v41
	v_sub_f32_e32 v51, 1.0, v51
	v_mul_f32_e32 v51, v51, v167
	v_cndmask_b32_e64 v54, 0, 32, vcc
	v_ldexp_f32 v41, v41, v54
	v_log_f32_e32 v41, v41
	s_nop 0
	v_mul_f32_e32 v54, 0x3f317217, v41
	v_fma_f32 v54, v41, s17, -v54
	v_fmac_f32_e32 v54, 0x3377d1cf, v41
	v_fmac_f32_e32 v54, 0x3f317217, v41
	v_cmp_lt_f32_e64 s[0:1], |v41|, s86
	s_nop 1
	v_cndmask_b32_e64 v41, v41, v54, s[0:1]
	v_cndmask_b32_e32 v54, 0, v224, vcc
	v_sub_f32_e32 v41, v41, v54
	global_store_dwordx4 v[52:53], v[34:37], off offset:-3584 nt
	global_store_dwordx4 v[52:53], v[38:41], off offset:-3568 nt
	s_nop 0
	v_cvt_pk_bf16_f32 v34, v44, v46
	v_cvt_pk_bf16_f32 v35, v48, v50
	v_cvt_pk_bf16_f32 v36, v45, v47
	v_cvt_pk_bf16_f32 v37, v49, v51
	global_store_dwordx4 v[42:43], v[34:37], off offset:256
	v_rcp_f32_e32 v38, v26
	v_rcp_f32_e32 v40, v27
	v_add_u32_e32 v34, 0xa0, v164
	v_ashrrev_i32_e32 v35, 31, v34
	v_lshlrev_b64 v[36:37], 12, v[34:35]
	v_rcp_f32_e32 v35, v30
	v_rcp_f32_e32 v42, v28
	v_rcp_f32_e32 v44, v29
	v_lshl_add_u64 v[36:37], s[12:13], 0, v[36:37]
	v_fma_f32 v26, v35, v193, v171
	v_cmp_gt_f32_e32 vcc, s16, v26
	v_lshl_add_u64 v[36:37], v[36:37], 0, v[168:169]
	v_sub_f32_e32 v35, 1.0, v35
	v_cndmask_b32_e64 v30, 0, 32, vcc
	v_ldexp_f32 v26, v26, v30
	v_log_f32_e32 v26, v26
	v_mul_f32_e32 v35, v35, v193
	v_mul_f32_e32 v30, 0x3f317217, v26
	v_fma_f32 v30, v26, s17, -v30
	v_fmac_f32_e32 v30, 0x3377d1cf, v26
	v_fmac_f32_e32 v30, 0x3f317217, v26
	v_cmp_lt_f32_e64 s[0:1], |v26|, s86
	s_nop 1
	v_cndmask_b32_e64 v26, v26, v30, s[0:1]
	v_cndmask_b32_e32 v30, 0, v224, vcc
	v_sub_f32_e32 v26, v26, v30
	v_fma_f32 v30, v38, v207, v185
	v_cmp_gt_f32_e32 vcc, s16, v30
	v_sub_f32_e32 v38, 1.0, v38
	v_mul_f32_e32 v38, v38, v207
	v_cndmask_b32_e64 v39, 0, 32, vcc
	v_ldexp_f32 v30, v30, v39
	v_log_f32_e32 v30, v30
	s_nop 0
	v_mul_f32_e32 v39, 0x3f317217, v30
	v_fma_f32 v39, v30, s17, -v39
	v_fmac_f32_e32 v39, 0x3377d1cf, v30
	v_fmac_f32_e32 v39, 0x3f317217, v30
	v_cmp_lt_f32_e64 s[0:1], |v30|, s86
	s_nop 1
	v_cndmask_b32_e64 v30, v30, v39, s[0:1]
	v_cndmask_b32_e32 v39, 0, v224, vcc
	v_sub_f32_e32 v30, v30, v39
	v_rcp_f32_e32 v39, v31
	s_nop 0
	v_fma_f32 v27, v39, v191, v173
	v_cmp_gt_f32_e32 vcc, s16, v27
	v_sub_f32_e32 v39, 1.0, v39
	v_mul_f32_e32 v39, v39, v191
	v_cndmask_b32_e64 v31, 0, 32, vcc
	v_ldexp_f32 v27, v27, v31
	v_log_f32_e32 v27, v27
	s_nop 0
	v_mul_f32_e32 v31, 0x3f317217, v27
	v_fma_f32 v31, v27, s17, -v31
	v_fmac_f32_e32 v31, 0x3377d1cf, v27
	v_fmac_f32_e32 v31, 0x3f317217, v27
	v_cmp_lt_f32_e64 s[0:1], |v27|, s86
	s_nop 1
	v_cndmask_b32_e64 v27, v27, v31, s[0:1]
	v_cndmask_b32_e32 v31, 0, v224, vcc
	v_sub_f32_e32 v27, v27, v31
	v_fma_f32 v31, v40, v205, v183
	v_cmp_gt_f32_e32 vcc, s16, v31
	v_sub_f32_e32 v40, 1.0, v40
	v_mul_f32_e32 v40, v40, v205
	v_cndmask_b32_e64 v41, 0, 32, vcc
	v_ldexp_f32 v31, v31, v41
	v_log_f32_e32 v31, v31
	s_nop 0
	v_mul_f32_e32 v41, 0x3f317217, v31
	v_fma_f32 v41, v31, s17, -v41
	v_fmac_f32_e32 v41, 0x3377d1cf, v31
	v_fmac_f32_e32 v41, 0x3f317217, v31
	v_cmp_lt_f32_e64 s[0:1], |v31|, s86
	s_nop 1
	v_cndmask_b32_e64 v31, v31, v41, s[0:1]
	v_cndmask_b32_e32 v41, 0, v224, vcc
	v_sub_f32_e32 v31, v31, v41
	v_rcp_f32_e32 v41, v32
	s_nop 0
	v_fma_f32 v28, v41, v137, v175
	v_cmp_gt_f32_e32 vcc, s16, v28
	v_sub_f32_e32 v41, 1.0, v41
	v_mul_f32_e32 v41, v41, v137
	v_cndmask_b32_e64 v32, 0, 32, vcc
	v_ldexp_f32 v28, v28, v32
	v_log_f32_e32 v28, v28
	s_nop 0
	v_mul_f32_e32 v32, 0x3f317217, v28
	v_fma_f32 v32, v28, s17, -v32
	v_fmac_f32_e32 v32, 0x3377d1cf, v28
	v_fmac_f32_e32 v32, 0x3f317217, v28
	v_cmp_lt_f32_e64 s[0:1], |v28|, s86
	s_nop 1
	v_cndmask_b32_e64 v28, v28, v32, s[0:1]
	v_cndmask_b32_e32 v32, 0, v224, vcc
	v_sub_f32_e32 v28, v28, v32
	v_fma_f32 v32, v42, v203, v181
	v_cmp_gt_f32_e32 vcc, s16, v32
	v_sub_f32_e32 v42, 1.0, v42
	v_mul_f32_e32 v42, v42, v203
	v_cndmask_b32_e64 v43, 0, 32, vcc
	v_ldexp_f32 v32, v32, v43
	v_log_f32_e32 v32, v32
	s_nop 0
	v_mul_f32_e32 v43, 0x3f317217, v32
	v_fma_f32 v43, v32, s17, -v43
	v_fmac_f32_e32 v43, 0x3377d1cf, v32
	v_fmac_f32_e32 v43, 0x3f317217, v32
	v_cmp_lt_f32_e64 s[0:1], |v32|, s86
	s_nop 1
	v_cndmask_b32_e64 v32, v32, v43, s[0:1]
	v_cndmask_b32_e32 v43, 0, v224, vcc
	v_sub_f32_e32 v32, v32, v43
	v_rcp_f32_e32 v43, v33
	s_nop 0
	v_fma_f32 v29, v43, v133, v177
	v_cmp_gt_f32_e32 vcc, s16, v29
	v_sub_f32_e32 v43, 1.0, v43
	v_mul_f32_e32 v43, v43, v133
	v_cndmask_b32_e64 v33, 0, 32, vcc
	v_ldexp_f32 v29, v29, v33
	v_log_f32_e32 v29, v29
	s_nop 0
	v_mul_f32_e32 v33, 0x3f317217, v29
	v_fma_f32 v33, v29, s17, -v33
	v_fmac_f32_e32 v33, 0x3377d1cf, v29
	v_fmac_f32_e32 v33, 0x3f317217, v29
	v_cmp_lt_f32_e64 s[0:1], |v29|, s86
	s_nop 1
	v_cndmask_b32_e64 v29, v29, v33, s[0:1]
	v_cndmask_b32_e32 v33, 0, v224, vcc
	v_sub_f32_e32 v29, v29, v33
	v_fma_f32 v33, v44, v201, v179
	v_cmp_gt_f32_e32 vcc, s16, v33
	v_sub_f32_e32 v44, 1.0, v44
	v_mul_f32_e32 v44, v44, v201
	v_cndmask_b32_e64 v45, 0, 32, vcc
	v_ldexp_f32 v33, v33, v45
	v_log_f32_e32 v33, v33
	s_nop 0
	v_mul_f32_e32 v45, 0x3f317217, v33
	v_fma_f32 v45, v33, s17, -v45
	v_fmac_f32_e32 v45, 0x3377d1cf, v33
	v_fmac_f32_e32 v45, 0x3f317217, v33
	v_cmp_lt_f32_e64 s[0:1], |v33|, s86
	s_nop 1
	v_cndmask_b32_e64 v33, v33, v45, s[0:1]
	v_cndmask_b32_e32 v45, 0, v224, vcc
	v_sub_f32_e32 v33, v33, v45
	global_store_dwordx4 v[36:37], v[26:29], off offset:-4096 nt
	global_store_dwordx4 v[36:37], v[30:33], off offset:-4080 nt
	s_nop 0
	v_mad_i64_i32 v[26:27], s[0:1], v34, s8, v[208:209]
	v_cvt_pk_bf16_f32 v28, v35, v39
	v_lshl_add_u64 v[26:27], v[26:27], 0, v[210:211]
	v_cvt_pk_bf16_f32 v29, v41, v43
	v_cvt_pk_bf16_f32 v30, v38, v40
	v_cvt_pk_bf16_f32 v31, v42, v44
	global_store_dwordx4 v[26:27], v[28:31], off
	v_rcp_f32_e32 v33, v20
	v_rcp_f32_e32 v35, v21
	v_rcp_f32_e32 v28, v22
	v_rcp_f32_e32 v29, v18
	v_rcp_f32_e32 v31, v19
	v_fma_f32 v18, v28, v129, v189
	v_cmp_gt_f32_e32 vcc, s16, v18
	v_sub_f32_e32 v28, 1.0, v28
	v_mul_f32_e32 v28, v28, v129
	v_cndmask_b32_e64 v22, 0, 32, vcc
	v_ldexp_f32 v18, v18, v22
	v_log_f32_e32 v18, v18
	s_nop 0
	v_mul_f32_e32 v22, 0x3f317217, v18
	v_fma_f32 v22, v18, s17, -v22
	v_fmac_f32_e32 v22, 0x3377d1cf, v18
	v_fmac_f32_e32 v22, 0x3f317217, v18
	v_cmp_lt_f32_e64 s[0:1], |v18|, s86
	s_nop 1
	v_cndmask_b32_e64 v18, v18, v22, s[0:1]
	v_cndmask_b32_e32 v22, 0, v224, vcc
	v_sub_f32_e32 v18, v18, v22
	v_fma_f32 v22, v29, v199, v145
	v_cmp_gt_f32_e32 vcc, s16, v22
	v_sub_f32_e32 v29, 1.0, v29
	v_mul_f32_e32 v29, v29, v199
	v_cndmask_b32_e64 v30, 0, 32, vcc
	v_ldexp_f32 v22, v22, v30
	v_log_f32_e32 v22, v22
	s_nop 0
	v_mul_f32_e32 v30, 0x3f317217, v22
	v_fma_f32 v30, v22, s17, -v30
	v_fmac_f32_e32 v30, 0x3377d1cf, v22
	v_fmac_f32_e32 v30, 0x3f317217, v22
	v_cmp_lt_f32_e64 s[0:1], |v22|, s86
	s_nop 1
	v_cndmask_b32_e64 v22, v22, v30, s[0:1]
	v_cndmask_b32_e32 v30, 0, v224, vcc
	v_sub_f32_e32 v22, v22, v30
	v_rcp_f32_e32 v30, v23
	s_nop 0
	v_fma_f32 v19, v30, v127, v187
	v_cmp_gt_f32_e32 vcc, s16, v19
	v_sub_f32_e32 v30, 1.0, v30
	v_mul_f32_e32 v30, v30, v127
	v_cndmask_b32_e64 v23, 0, 32, vcc
	v_ldexp_f32 v19, v19, v23
	v_log_f32_e32 v19, v19
	s_nop 0
	v_mul_f32_e32 v23, 0x3f317217, v19
	v_fma_f32 v23, v19, s17, -v23
	v_fmac_f32_e32 v23, 0x3377d1cf, v19
	v_fmac_f32_e32 v23, 0x3f317217, v19
	v_cmp_lt_f32_e64 s[0:1], |v19|, s86
	s_nop 1
	v_cndmask_b32_e64 v19, v19, v23, s[0:1]
	v_cndmask_b32_e32 v23, 0, v224, vcc
	v_sub_f32_e32 v19, v19, v23
	v_fma_f32 v23, v31, v197, v141
	v_cmp_gt_f32_e32 vcc, s16, v23
	v_sub_f32_e32 v31, 1.0, v31
	v_mul_f32_e32 v31, v31, v197
	v_cndmask_b32_e64 v32, 0, 32, vcc
	v_ldexp_f32 v23, v23, v32
	v_log_f32_e32 v23, v23
	s_nop 0
	v_mul_f32_e32 v32, 0x3f317217, v23
	v_fma_f32 v32, v23, s17, -v32
	v_fmac_f32_e32 v32, 0x3377d1cf, v23
	v_fmac_f32_e32 v32, 0x3f317217, v23
	v_cmp_lt_f32_e64 s[0:1], |v23|, s86
	s_nop 1
	v_cndmask_b32_e64 v23, v23, v32, s[0:1]
	v_cndmask_b32_e32 v32, 0, v224, vcc
	v_sub_f32_e32 v23, v23, v32
	v_rcp_f32_e32 v32, v24
	s_nop 0
	v_fma_f32 v20, v32, v125, v143
	v_cmp_gt_f32_e32 vcc, s16, v20
	v_sub_f32_e32 v32, 1.0, v32
	v_mul_f32_e32 v32, v32, v125
	v_cndmask_b32_e64 v24, 0, 32, vcc
	v_ldexp_f32 v20, v20, v24
	v_log_f32_e32 v20, v20
	s_nop 0
	v_mul_f32_e32 v24, 0x3f317217, v20
	v_fma_f32 v24, v20, s17, -v24
	v_fmac_f32_e32 v24, 0x3377d1cf, v20
	v_fmac_f32_e32 v24, 0x3f317217, v20
	v_cmp_lt_f32_e64 s[0:1], |v20|, s86
	s_nop 1
	v_cndmask_b32_e64 v20, v20, v24, s[0:1]
	v_cndmask_b32_e32 v24, 0, v224, vcc
	v_sub_f32_e32 v20, v20, v24
	v_fma_f32 v24, v33, v195, v135
	v_cmp_gt_f32_e32 vcc, s16, v24
	v_sub_f32_e32 v33, 1.0, v33
	v_mul_f32_e32 v33, v33, v195
	v_cndmask_b32_e64 v34, 0, 32, vcc
	v_ldexp_f32 v24, v24, v34
	v_log_f32_e32 v24, v24
	s_nop 0
	v_mul_f32_e32 v34, 0x3f317217, v24
	v_fma_f32 v34, v24, s17, -v34
	v_fmac_f32_e32 v34, 0x3377d1cf, v24
	v_fmac_f32_e32 v34, 0x3f317217, v24
	v_cmp_lt_f32_e64 s[0:1], |v24|, s86
	s_nop 1
	v_cndmask_b32_e64 v24, v24, v34, s[0:1]
	v_cndmask_b32_e32 v34, 0, v224, vcc
	v_sub_f32_e32 v24, v24, v34
	v_rcp_f32_e32 v34, v25
	s_nop 0
	v_fma_f32 v21, v34, v123, v139
	v_cmp_gt_f32_e32 vcc, s16, v21
	v_sub_f32_e32 v34, 1.0, v34
	v_mul_f32_e32 v34, v34, v123
	v_cndmask_b32_e64 v25, 0, 32, vcc
	v_ldexp_f32 v21, v21, v25
	v_log_f32_e32 v21, v21
	s_nop 0
	v_mul_f32_e32 v25, 0x3f317217, v21
	v_fma_f32 v25, v21, s17, -v25
	v_fmac_f32_e32 v25, 0x3377d1cf, v21
	v_fmac_f32_e32 v25, 0x3f317217, v21
	v_cmp_lt_f32_e64 s[0:1], |v21|, s86
	s_nop 1
	v_cndmask_b32_e64 v21, v21, v25, s[0:1]
	v_cndmask_b32_e32 v25, 0, v224, vcc
	v_sub_f32_e32 v21, v21, v25
	v_fma_f32 v25, v35, v167, v131
	v_cmp_gt_f32_e32 vcc, s16, v25
	v_sub_f32_e32 v35, 1.0, v35
	v_mul_f32_e32 v35, v35, v167
	v_cndmask_b32_e64 v38, 0, 32, vcc
	v_ldexp_f32 v25, v25, v38
	v_log_f32_e32 v25, v25
	s_nop 0
	v_mul_f32_e32 v38, 0x3f317217, v25
	v_fma_f32 v38, v25, s17, -v38
	v_fmac_f32_e32 v38, 0x3377d1cf, v25
	v_fmac_f32_e32 v38, 0x3f317217, v25
	v_cmp_lt_f32_e64 s[0:1], |v25|, s86
	s_nop 1
	v_cndmask_b32_e64 v25, v25, v38, s[0:1]
	v_cndmask_b32_e32 v38, 0, v224, vcc
	v_sub_f32_e32 v25, v25, v38
	global_store_dwordx4 v[36:37], v[18:21], off offset:-3584 nt
	global_store_dwordx4 v[36:37], v[22:25], off offset:-3568 nt
	s_nop 0
	v_cvt_pk_bf16_f32 v18, v28, v30
	v_cvt_pk_bf16_f32 v19, v32, v34
	v_cvt_pk_bf16_f32 v20, v29, v31
	v_cvt_pk_bf16_f32 v21, v33, v35
	global_store_dwordx4 v[26:27], v[18:21], off offset:256
	v_rcp_f32_e32 v22, v10
	v_rcp_f32_e32 v24, v11
	v_add_u32_e32 v18, 0xb0, v164
	v_ashrrev_i32_e32 v19, 31, v18
	v_lshlrev_b64 v[20:21], 12, v[18:19]
	v_rcp_f32_e32 v19, v14
	v_fmac_f32_e32 v185, v22, v207
	v_fmac_f32_e32 v183, v24, v205
	v_rcp_f32_e32 v26, v12
	v_fmac_f32_e32 v171, v19, v193
	v_cmp_gt_f32_e32 vcc, s16, v171
	v_rcp_f32_e32 v28, v13
	v_fmac_f32_e32 v181, v26, v203
	v_cndmask_b32_e64 v10, 0, 32, vcc
	v_ldexp_f32 v10, v171, v10
	v_log_f32_e32 v10, v10
	v_fmac_f32_e32 v179, v28, v201
	v_lshl_add_u64 v[20:21], s[12:13], 0, v[20:21]
	v_lshl_add_u64 v[20:21], v[20:21], 0, v[168:169]
	v_mul_f32_e32 v14, 0x3f317217, v10
	v_fma_f32 v14, v10, s17, -v14
	v_fmac_f32_e32 v14, 0x3377d1cf, v10
	v_fmac_f32_e32 v14, 0x3f317217, v10
	v_cmp_lt_f32_e64 s[0:1], |v10|, s86
	v_sub_f32_e32 v19, 1.0, v19
	v_mul_f32_e32 v19, v19, v193
	v_cndmask_b32_e64 v10, v10, v14, s[0:1]
	v_cndmask_b32_e32 v14, 0, v224, vcc
	v_cmp_gt_f32_e32 vcc, s16, v185
	v_sub_f32_e32 v10, v10, v14
	v_sub_f32_e32 v22, 1.0, v22
	v_cndmask_b32_e64 v14, 0, 32, vcc
	v_ldexp_f32 v14, v185, v14
	v_log_f32_e32 v14, v14
	v_sub_f32_e32 v24, 1.0, v24
	v_sub_f32_e32 v26, 1.0, v26
	v_sub_f32_e32 v28, 1.0, v28
	v_mul_f32_e32 v23, 0x3f317217, v14
	v_fma_f32 v23, v14, s17, -v23
	v_fmac_f32_e32 v23, 0x3377d1cf, v14
	v_fmac_f32_e32 v23, 0x3f317217, v14
	v_cmp_lt_f32_e64 s[0:1], |v14|, s86
	v_mul_f32_e32 v22, v22, v207
	v_mul_f32_e32 v24, v24, v205
	v_cndmask_b32_e64 v14, v14, v23, s[0:1]
	v_cndmask_b32_e32 v23, 0, v224, vcc
	v_sub_f32_e32 v14, v14, v23
	v_rcp_f32_e32 v23, v15
	v_mul_f32_e32 v26, v26, v203
	v_mul_f32_e32 v28, v28, v201
	v_fmac_f32_e32 v173, v23, v191
	v_cmp_gt_f32_e32 vcc, s16, v173
	v_sub_f32_e32 v23, 1.0, v23
	v_mul_f32_e32 v23, v23, v191
	v_cndmask_b32_e64 v11, 0, 32, vcc
	v_ldexp_f32 v11, v173, v11
	v_log_f32_e32 v11, v11
	s_nop 0
	v_mul_f32_e32 v15, 0x3f317217, v11
	v_fma_f32 v15, v11, s17, -v15
	v_fmac_f32_e32 v15, 0x3377d1cf, v11
	v_fmac_f32_e32 v15, 0x3f317217, v11
	v_cmp_lt_f32_e64 s[0:1], |v11|, s86
	s_nop 1
	v_cndmask_b32_e64 v11, v11, v15, s[0:1]
	v_cndmask_b32_e32 v15, 0, v224, vcc
	v_cmp_gt_f32_e32 vcc, s16, v183
	v_sub_f32_e32 v11, v11, v15
	s_nop 0
	v_cndmask_b32_e64 v15, 0, 32, vcc
	v_ldexp_f32 v15, v183, v15
	v_log_f32_e32 v15, v15
	s_nop 0
	v_mul_f32_e32 v25, 0x3f317217, v15
	v_fma_f32 v25, v15, s17, -v25
	v_fmac_f32_e32 v25, 0x3377d1cf, v15
	v_fmac_f32_e32 v25, 0x3f317217, v15
	v_cmp_lt_f32_e64 s[0:1], |v15|, s86
	s_nop 1
	v_cndmask_b32_e64 v15, v15, v25, s[0:1]
	v_cndmask_b32_e32 v25, 0, v224, vcc
	v_sub_f32_e32 v15, v15, v25
	v_rcp_f32_e32 v25, v16
	s_nop 0
	v_fmac_f32_e32 v175, v25, v137
	v_cmp_gt_f32_e32 vcc, s16, v175
	v_sub_f32_e32 v25, 1.0, v25
	v_mul_f32_e32 v25, v25, v137
	v_cndmask_b32_e64 v12, 0, 32, vcc
	v_ldexp_f32 v12, v175, v12
	v_log_f32_e32 v12, v12
	s_nop 0
	v_mul_f32_e32 v16, 0x3f317217, v12
	v_fma_f32 v16, v12, s17, -v16
	v_fmac_f32_e32 v16, 0x3377d1cf, v12
	v_fmac_f32_e32 v16, 0x3f317217, v12
	v_cmp_lt_f32_e64 s[0:1], |v12|, s86
	s_nop 1
	v_cndmask_b32_e64 v12, v12, v16, s[0:1]
	v_cndmask_b32_e32 v16, 0, v224, vcc
	v_cmp_gt_f32_e32 vcc, s16, v181
	v_sub_f32_e32 v12, v12, v16
	s_nop 0
	v_cndmask_b32_e64 v16, 0, 32, vcc
	v_ldexp_f32 v16, v181, v16
	v_log_f32_e32 v16, v16
	s_nop 0
	v_mul_f32_e32 v27, 0x3f317217, v16
	v_fma_f32 v27, v16, s17, -v27
	v_fmac_f32_e32 v27, 0x3377d1cf, v16
	v_fmac_f32_e32 v27, 0x3f317217, v16
	v_cmp_lt_f32_e64 s[0:1], |v16|, s86
	s_nop 1
	v_cndmask_b32_e64 v16, v16, v27, s[0:1]
	v_cndmask_b32_e32 v27, 0, v224, vcc
	v_sub_f32_e32 v16, v16, v27
	v_rcp_f32_e32 v27, v17
	s_nop 0
	v_fmac_f32_e32 v177, v27, v133
	v_cmp_gt_f32_e32 vcc, s16, v177
	v_sub_f32_e32 v27, 1.0, v27
	v_mul_f32_e32 v27, v27, v133
	v_cndmask_b32_e64 v13, 0, 32, vcc
	v_ldexp_f32 v13, v177, v13
	v_log_f32_e32 v13, v13
	s_nop 0
	v_mul_f32_e32 v17, 0x3f317217, v13
	v_fma_f32 v17, v13, s17, -v17
	v_fmac_f32_e32 v17, 0x3377d1cf, v13
	v_fmac_f32_e32 v17, 0x3f317217, v13
	v_cmp_lt_f32_e64 s[0:1], |v13|, s86
	s_nop 1
	v_cndmask_b32_e64 v13, v13, v17, s[0:1]
	v_cndmask_b32_e32 v17, 0, v224, vcc
	v_cmp_gt_f32_e32 vcc, s16, v179
	v_sub_f32_e32 v13, v13, v17
	s_nop 0
	v_cndmask_b32_e64 v17, 0, 32, vcc
	v_ldexp_f32 v17, v179, v17
	v_log_f32_e32 v17, v17
	s_nop 0
	v_mul_f32_e32 v29, 0x3f317217, v17
	v_fma_f32 v29, v17, s17, -v29
	v_fmac_f32_e32 v29, 0x3377d1cf, v17
	v_fmac_f32_e32 v29, 0x3f317217, v17
	v_cmp_lt_f32_e64 s[0:1], |v17|, s86
	s_nop 1
	v_cndmask_b32_e64 v17, v17, v29, s[0:1]
	v_cndmask_b32_e32 v29, 0, v224, vcc
	v_sub_f32_e32 v17, v17, v29
	global_store_dwordx4 v[20:21], v[10:13], off offset:-4096 nt
	global_store_dwordx4 v[20:21], v[14:17], off offset:-4080 nt
	s_nop 0
	v_mad_i64_i32 v[10:11], s[0:1], v18, s8, v[208:209]
	v_cvt_pk_bf16_f32 v12, v19, v23
	v_lshl_add_u64 v[10:11], v[10:11], 0, v[210:211]
	v_cvt_pk_bf16_f32 v13, v25, v27
	v_cvt_pk_bf16_f32 v14, v22, v24
	v_cvt_pk_bf16_f32 v15, v26, v28
	global_store_dwordx4 v[10:11], v[12:15], off
	v_rcp_f32_e32 v17, v4
	v_rcp_f32_e32 v19, v5
	v_rcp_f32_e32 v12, v6
	v_rcp_f32_e32 v13, v2
	v_rcp_f32_e32 v15, v3
	v_fmac_f32_e32 v135, v17, v195
	v_fmac_f32_e32 v189, v12, v129
	v_cmp_gt_f32_e32 vcc, s16, v189
	v_fmac_f32_e32 v145, v13, v199
	v_fmac_f32_e32 v141, v15, v197
	v_cndmask_b32_e64 v2, 0, 32, vcc
	v_ldexp_f32 v2, v189, v2
	v_log_f32_e32 v2, v2
	v_fmac_f32_e32 v131, v19, v167
	v_sub_f32_e32 v12, 1.0, v12
	v_sub_f32_e32 v13, 1.0, v13
	v_mul_f32_e32 v6, 0x3f317217, v2
	v_fma_f32 v6, v2, s17, -v6
	v_fmac_f32_e32 v6, 0x3377d1cf, v2
	v_fmac_f32_e32 v6, 0x3f317217, v2
	v_cmp_lt_f32_e64 s[0:1], |v2|, s86
	v_sub_f32_e32 v15, 1.0, v15
	v_sub_f32_e32 v17, 1.0, v17
	v_cndmask_b32_e64 v2, v2, v6, s[0:1]
	v_cndmask_b32_e32 v6, 0, v224, vcc
	v_cmp_gt_f32_e32 vcc, s16, v145
	v_sub_f32_e32 v2, v2, v6
	v_sub_f32_e32 v19, 1.0, v19
	v_cndmask_b32_e64 v6, 0, 32, vcc
	v_ldexp_f32 v6, v145, v6
	v_log_f32_e32 v6, v6
	v_mul_f32_e32 v12, v12, v129
	v_mul_f32_e32 v13, v13, v199
	v_mul_f32_e32 v15, v15, v197
	v_mul_f32_e32 v14, 0x3f317217, v6
	v_fma_f32 v14, v6, s17, -v14
	v_fmac_f32_e32 v14, 0x3377d1cf, v6
	v_fmac_f32_e32 v14, 0x3f317217, v6
	v_cmp_lt_f32_e64 s[0:1], |v6|, s86
	v_mul_f32_e32 v17, v17, v195
	v_mul_f32_e32 v19, v19, v167
	v_cndmask_b32_e64 v6, v6, v14, s[0:1]
	v_cndmask_b32_e32 v14, 0, v224, vcc
	v_sub_f32_e32 v6, v6, v14
	v_rcp_f32_e32 v14, v7
	s_nop 0
	v_fmac_f32_e32 v187, v14, v127
	v_cmp_gt_f32_e32 vcc, s16, v187
	v_sub_f32_e32 v14, 1.0, v14
	v_mul_f32_e32 v14, v14, v127
	v_cndmask_b32_e64 v3, 0, 32, vcc
	v_ldexp_f32 v3, v187, v3
	v_log_f32_e32 v3, v3
	s_nop 0
	v_mul_f32_e32 v7, 0x3f317217, v3
	v_fma_f32 v7, v3, s17, -v7
	v_fmac_f32_e32 v7, 0x3377d1cf, v3
	v_fmac_f32_e32 v7, 0x3f317217, v3
	v_cmp_lt_f32_e64 s[0:1], |v3|, s86
	s_nop 1
	v_cndmask_b32_e64 v3, v3, v7, s[0:1]
	v_cndmask_b32_e32 v7, 0, v224, vcc
	v_cmp_gt_f32_e32 vcc, s16, v141
	v_sub_f32_e32 v3, v3, v7
	s_nop 0
	v_cndmask_b32_e64 v7, 0, 32, vcc
	v_ldexp_f32 v7, v141, v7
	v_log_f32_e32 v7, v7
	s_nop 0
	v_mul_f32_e32 v16, 0x3f317217, v7
	v_fma_f32 v16, v7, s17, -v16
	v_fmac_f32_e32 v16, 0x3377d1cf, v7
	v_fmac_f32_e32 v16, 0x3f317217, v7
	v_cmp_lt_f32_e64 s[0:1], |v7|, s86
	s_nop 1
	v_cndmask_b32_e64 v7, v7, v16, s[0:1]
	v_cndmask_b32_e32 v16, 0, v224, vcc
	v_sub_f32_e32 v7, v7, v16
	v_rcp_f32_e32 v16, v8
	s_nop 0
	v_fmac_f32_e32 v143, v16, v125
	v_cmp_gt_f32_e32 vcc, s16, v143
	v_sub_f32_e32 v16, 1.0, v16
	v_mul_f32_e32 v16, v16, v125
	v_cndmask_b32_e64 v4, 0, 32, vcc
	v_ldexp_f32 v4, v143, v4
	v_log_f32_e32 v4, v4
	s_nop 0
	v_mul_f32_e32 v8, 0x3f317217, v4
	v_fma_f32 v8, v4, s17, -v8
	v_fmac_f32_e32 v8, 0x3377d1cf, v4
	v_fmac_f32_e32 v8, 0x3f317217, v4
	v_cmp_lt_f32_e64 s[0:1], |v4|, s86
	s_nop 1
	v_cndmask_b32_e64 v4, v4, v8, s[0:1]
	v_cndmask_b32_e32 v8, 0, v224, vcc
	v_cmp_gt_f32_e32 vcc, s16, v135
	v_sub_f32_e32 v4, v4, v8
	s_nop 0
	v_cndmask_b32_e64 v8, 0, 32, vcc
	v_ldexp_f32 v8, v135, v8
	v_log_f32_e32 v8, v8
	s_nop 0
	v_mul_f32_e32 v18, 0x3f317217, v8
	v_fma_f32 v18, v8, s17, -v18
	v_fmac_f32_e32 v18, 0x3377d1cf, v8
	v_fmac_f32_e32 v18, 0x3f317217, v8
	v_cmp_lt_f32_e64 s[0:1], |v8|, s86
	s_nop 1
	v_cndmask_b32_e64 v8, v8, v18, s[0:1]
	v_cndmask_b32_e32 v18, 0, v224, vcc
	v_sub_f32_e32 v8, v8, v18
	v_rcp_f32_e32 v18, v9
	s_nop 0
	v_fmac_f32_e32 v139, v18, v123
	v_cmp_gt_f32_e32 vcc, s16, v139
	v_sub_f32_e32 v18, 1.0, v18
	v_mul_f32_e32 v18, v18, v123
	v_cndmask_b32_e64 v5, 0, 32, vcc
	v_ldexp_f32 v5, v139, v5
	v_log_f32_e32 v5, v5
	s_nop 0
	v_mul_f32_e32 v9, 0x3f317217, v5
	v_fma_f32 v9, v5, s17, -v9
	v_fmac_f32_e32 v9, 0x3377d1cf, v5
	v_fmac_f32_e32 v9, 0x3f317217, v5
	v_cmp_lt_f32_e64 s[0:1], |v5|, s86
	s_nop 1
	v_cndmask_b32_e64 v5, v5, v9, s[0:1]
	v_cndmask_b32_e32 v9, 0, v224, vcc
	v_cmp_gt_f32_e32 vcc, s16, v131
	v_sub_f32_e32 v5, v5, v9
	s_nop 0
	v_cndmask_b32_e64 v9, 0, 32, vcc
	v_ldexp_f32 v9, v131, v9
	v_log_f32_e32 v9, v9
	s_nop 0
	v_mul_f32_e32 v22, 0x3f317217, v9
	v_fma_f32 v22, v9, s17, -v22
	v_fmac_f32_e32 v22, 0x3377d1cf, v9
	v_fmac_f32_e32 v22, 0x3f317217, v9
	v_cmp_lt_f32_e64 s[0:1], |v9|, s86
	s_nop 1
	v_cndmask_b32_e64 v9, v9, v22, s[0:1]
	v_cndmask_b32_e32 v22, 0, v224, vcc
	v_sub_f32_e32 v9, v9, v22
	global_store_dwordx4 v[20:21], v[2:5], off offset:-3584 nt
	global_store_dwordx4 v[20:21], v[6:9], off offset:-3568 nt
	s_nop 0
	v_cvt_pk_bf16_f32 v2, v12, v14
	v_cvt_pk_bf16_f32 v3, v16, v18
	v_cvt_pk_bf16_f32 v4, v13, v15
	v_cvt_pk_bf16_f32 v5, v17, v19
	global_store_dwordx4 v[10:11], v[2:5], off offset:256
	s_andn2_b64 vcc, exec, s[2:3]
	s_mov_b64 s[0:1], -1
	s_cbranch_vccnz .LBB0_142

.LBB0_1055:
	s_cmp_lt_i32 s44, 6
	s_cselect_b64 s[0:1], -1, 0
	s_cmp_gt_i32 s45, 5
	s_cselect_b64 s[2:3], -1, 0
	s_and_b64 s[0:1], s[0:1], s[2:3]
	s_andn2_b64 vcc, exec, s[0:1]
	s_cbranch_vccnz .LBB0_1121
	v_readlane_b32 s0, v254, 3
	s_lshl_b32 s0, s0, 3
	v_readlane_b32 s1, v254, 27
	s_add_i32 s2, s0, s1
	s_cmpk_gt_i32 s2, 0x203f
	v_mov_b32_e32 v1, v0
	s_cbranch_scc1 .LBB0_1067
	v_and_b32_e32 v2, 63, v1
	v_mbcnt_lo_u32_b32 v1, -1, 0
	v_mbcnt_hi_u32_b32 v3, -1, v1
	v_and_b32_e32 v1, 64, v3
	v_add_u32_e32 v4, 64, v1
	v_xor_b32_e32 v1, 1, v3
	v_cmp_lt_i32_e32 vcc, v1, v4
	v_xor_b32_e32 v5, 2, v3
	v_readlane_b32 s48, v254, 11
	v_cndmask_b32_e32 v1, v3, v1, vcc
	v_cmp_lt_i32_e32 vcc, v5, v4
	v_readlane_b32 s50, v254, 13
	v_readlane_b32 s51, v254, 14
	v_cndmask_b32_e32 v5, v3, v5, vcc
	v_lshlrev_b32_e32 v206, 2, v5
	v_xor_b32_e32 v5, 4, v3
	v_cmp_lt_i32_e32 vcc, v5, v4
	v_readlane_b32 s52, v254, 15
	v_readlane_b32 s53, v254, 16
	v_cndmask_b32_e32 v5, v3, v5, vcc
	v_lshlrev_b32_e32 v207, 2, v5
	v_xor_b32_e32 v5, 8, v3
	v_cmp_lt_i32_e32 vcc, v5, v4
	v_mov_b32_e32 v131, 0
	v_lshlrev_b32_e32 v130, 4, v2
	v_cndmask_b32_e32 v5, v3, v5, vcc
	v_lshlrev_b32_e32 v208, 2, v5
	v_xor_b32_e32 v5, 16, v3
	v_cmp_lt_i32_e32 vcc, v5, v4
	v_readlane_b32 s54, v254, 17
	v_readlane_b32 s55, v254, 18
	v_cndmask_b32_e32 v5, v3, v5, vcc
	s_mov_b64 s[12:13], s[52:53]
	s_mov_b64 s[10:11], s[50:51]
	v_lshlrev_b32_e32 v209, 2, v5
	v_xor_b32_e32 v5, 32, v3
	v_lshl_add_u64 v[132:133], s[10:11], 0, v[130:131]
	s_mov_b64 s[0:1], 0x1000
	v_lshl_add_u64 v[142:143], s[12:13], 0, v[130:131]
	v_cmp_lt_i32_e32 vcc, v5, v4
	v_lshlrev_b32_e32 v130, 3, v2
	v_lshl_add_u64 v[134:135], v[132:133], 0, s[0:1]
	v_cndmask_b32_e32 v3, v3, v5, vcc
	v_lshl_add_u64 v[144:145], v[142:143], 0, s[0:1]
	v_lshl_add_u64 v[4:5], s[68:69], 0, v[130:131]
	s_mov_b64 s[0:1], 0x21800000
	v_readlane_b32 s3, v254, 2
	v_lshl_add_u64 v[152:153], v[4:5], 0, s[0:1]
	s_mov_b64 s[0:1], 0x25c00000
	s_lshl_b32 s16, s3, 3
	s_mul_i32 s4, s3, 24
	v_lshl_add_u64 v[154:155], v[4:5], 0, s[0:1]
	s_mov_b64 s[0:1], 0x2a000000
	s_lshl_b32 s17, s3, 4
	s_ashr_i32 s3, s2, 31
	v_lshl_add_u64 v[156:157], v[4:5], 0, s[0:1]
	s_lshl_b64 s[0:1], s[2:3], 12
	s_add_u32 s0, s68, s0
	s_addc_u32 s1, s69, s1
	s_mov_b64 s[6:7], 0x1400
	s_mov_b64 s[8:9], 0x1800
	s_mov_b64 s[10:11], 0x1c00
	v_lshl_add_u64 v[4:5], s[0:1], 0, v[130:131]
	s_mov_b64 s[0:1], 0x2a000e00
	s_ashr_i32 s5, s4, 31
	v_lshl_add_u64 v[136:137], v[132:133], 0, s[6:7]
	v_lshl_add_u64 v[138:139], v[132:133], 0, s[8:9]
	v_lshl_add_u64 v[140:141], v[132:133], 0, s[10:11]
	v_lshlrev_b32_e32 v1, 2, v1
	v_lshlrev_b32_e32 v210, 2, v3
	v_lshl_add_u64 v[146:147], v[142:143], 0, s[6:7]
	v_lshl_add_u64 v[148:149], v[142:143], 0, s[8:9]
	v_lshl_add_u64 v[150:151], v[142:143], 0, s[10:11]
	v_lshl_add_u64 v[158:159], v[4:5], 0, s[0:1]
	s_lshl_b64 s[8:9], s[4:5], 12
	v_lshlrev_b32_e32 v130, 4, v2
	s_mov_b32 s18, 0xf7800000
	s_movk_i32 s19, 0x1000
	s_mov_b32 s20, 0xffff0000
	v_mov_b32_e32 v211, 0x358637bd
	s_mov_b32 s21, 0xf800000
	v_mov_b32_e32 v212, 0x260
	s_movk_i32 s22, 0x7fff
	s_mov_b32 s23, 0xfbc00000
	v_readlane_b32 s49, v254, 12
	v_readlane_b32 s56, v254, 19
	v_readlane_b32 s57, v254, 20
	v_readlane_b32 s58, v254, 21
	v_readlane_b32 s59, v254, 22
	v_readlane_b32 s60, v254, 23
	v_readlane_b32 s61, v254, 24
	v_readlane_b32 s62, v254, 25
	v_readlane_b32 s63, v254, 26
	s_mov_b64 s[14:15], s[54:55]
	v_readlane_b32 s24, v254, 27
	v_and_b32_e32 v253, 63, v0
	v_lshlrev_b32_e32 v253, 4, v253
	s_nop 1
	s_lshl_b32 s24, s24, 14
	v_add_u32_e32 v253, s24, v253
	global_load_dwordx4 v[160:163], v[142:143], off
	global_load_dwordx4 v[164:167], v[142:143], off offset:1024
	global_load_dwordx4 v[168:171], v[142:143], off offset:2048
	global_load_dwordx4 v[172:175], v[142:143], off offset:3072
	global_load_dwordx4 v[176:179], v[144:145], off
	global_load_dwordx4 v[180:183], v[146:147], off
	global_load_dwordx4 v[184:187], v[148:149], off
	global_load_dwordx4 v[188:191], v[150:151], off
	s_waitcnt vmcnt(0)
	ds_write_b128 v253, v[160:163]
	ds_write_b128 v253, v[164:167] offset:1024
	ds_write_b128 v253, v[168:171] offset:2048
	ds_write_b128 v253, v[172:175] offset:3072
	ds_write_b128 v253, v[176:179] offset:4096
	ds_write_b128 v253, v[180:183] offset:5120
	ds_write_b128 v253, v[184:187] offset:6144
	ds_write_b128 v253, v[188:191] offset:7168
	s_waitcnt lgkmcnt(0)
	s_branch .LBB0_1059

.LBB0_1063:
	s_waitcnt vmcnt(0)
	v_and_b32_e32 v215, 0xffff0000, v52
	v_and_b32_e32 v217, 0xffff0000, v53
	v_lshlrev_b32_e32 v214, 16, v52
	v_lshlrev_b32_e32 v216, 16, v53
	v_mul_f32_e32 v52, v217, v217
	v_lshlrev_b32_e32 v227, 16, v42
	v_and_b32_e32 v229, 0xffff0000, v42
	v_mul_f32_e32 v42, v215, v215
	v_pk_fma_f32 v[52:53], v[216:217], v[216:217], v[52:53] op_sel_hi:[1,1,0]
	v_and_b32_e32 v221, 0xffff0000, v51
	v_and_b32_e32 v220, 0xffff0000, v50
	v_lshlrev_b32_e32 v230, 16, v43
	v_and_b32_e32 v231, 0xffff0000, v43
	v_pk_fma_f32 v[42:43], v[214:215], v[214:215], v[42:43] op_sel_hi:[1,1,0]
	v_lshlrev_b32_e32 v219, 16, v51
	v_lshlrev_b32_e32 v218, 16, v50
	v_pk_mul_f32 v[50:51], v[220:221], v[220:221]
	v_lshlrev_b32_e32 v222, 16, v44
	v_and_b32_e32 v223, 0xffff0000, v44
	v_lshlrev_b32_e32 v224, 16, v45
	v_and_b32_e32 v225, 0xffff0000, v45
	v_mov_b32_e32 v226, v42
	v_mov_b32_e32 v44, v52
	v_mov_b32_e32 v45, v227
	v_pk_fma_f32 v[50:51], v[218:219], v[218:219], v[50:51]
	v_pk_add_f32 v[42:43], v[42:43], v[52:53]
	v_pk_mul_f32 v[44:45], v[226:227], v[44:45]
	v_mul_f32_e32 v54, v229, v229
	v_mov_b32_e32 v43, v45
	v_pk_add_f32 v[44:45], v[50:51], v[50:51] op_sel:[0,1] op_sel_hi:[1,0]
	v_mul_f32_e32 v50, v225, v225
	v_mov_b32_e32 v45, v54
	v_pk_add_f32 v[42:43], v[42:43], v[44:45]
	v_mul_f32_e32 v44, v223, v223
	v_mul_f32_e32 v55, v230, v230
	v_mul_f32_e32 v56, v231, v231
	v_pk_fma_f32 v[44:45], v[222:223], v[222:223], v[44:45] op_sel_hi:[1,1,0]
	v_pk_fma_f32 v[50:51], v[224:225], v[224:225], v[50:51] op_sel_hi:[1,1,0]
	v_mov_b32_e32 v45, v55
	v_mov_b32_e32 v51, v56
	v_and_b32_e32 v235, 0xffff0000, v41
	v_and_b32_e32 v234, 0xffff0000, v40
	v_pk_add_f32 v[44:45], v[44:45], v[50:51]
	v_lshlrev_b32_e32 v233, 16, v41
	v_lshlrev_b32_e32 v232, 16, v40
	v_pk_mul_f32 v[40:41], v[234:235], v[234:235]
	v_pk_add_f32 v[42:43], v[42:43], v[44:45]
	v_pk_fma_f32 v[40:41], v[232:233], v[232:233], v[40:41]
	v_and_b32_e32 v203, 0xffff0000, v39
	v_pk_add_f32 v[40:41], v[40:41], v[40:41] op_sel:[0,1] op_sel_hi:[1,0]
	v_and_b32_e32 v202, 0xffff0000, v38
	v_lshlrev_b32_e32 v197, 16, v34
	v_and_b32_e32 v195, 0xffff0000, v34
	v_lshlrev_b32_e32 v192, 16, v35
	v_and_b32_e32 v193, 0xffff0000, v35
	v_pk_add_f32 v[34:35], v[42:43], v[42:43] op_sel:[0,1] op_sel_hi:[1,0]
	v_lshlrev_b32_e32 v205, 16, v39
	v_lshlrev_b32_e32 v204, 16, v38
	v_pk_mul_f32 v[38:39], v[202:203], v[202:203]
	v_lshlrev_b32_e32 v198, 16, v36
	v_and_b32_e32 v199, 0xffff0000, v36
	v_lshlrev_b32_e32 v200, 16, v37
	v_and_b32_e32 v201, 0xffff0000, v37
	v_mov_b32_e32 v196, v34
	v_mov_b32_e32 v36, v40
	v_mov_b32_e32 v37, v197
	v_pk_fma_f32 v[38:39], v[204:205], v[204:205], v[38:39]
	v_pk_add_f32 v[34:35], v[34:35], v[40:41]
	v_pk_mul_f32 v[36:37], v[196:197], v[36:37]
	v_mul_f32_e32 v44, v195, v195
	v_mov_b32_e32 v35, v37
	v_pk_add_f32 v[36:37], v[38:39], v[38:39] op_sel:[0,1] op_sel_hi:[1,0]
	v_mul_f32_e32 v38, v201, v201
	v_mov_b32_e32 v37, v44
	v_pk_add_f32 v[34:35], v[34:35], v[36:37]
	v_mul_f32_e32 v36, v199, v199
	v_mul_f32_e32 v45, v192, v192
	v_mul_f32_e32 v50, v193, v193
	v_pk_fma_f32 v[36:37], v[198:199], v[198:199], v[36:37] op_sel_hi:[1,1,0]
	v_pk_fma_f32 v[38:39], v[200:201], v[200:201], v[38:39] op_sel_hi:[1,1,0]
	v_mov_b32_e32 v37, v45
	v_mov_b32_e32 v39, v50
	v_pk_add_f32 v[36:37], v[36:37], v[38:39]
	global_load_dwordx4 v[46:49], v[132:133], off
	global_load_dwordx4 v[62:65], v[132:133], off offset:1024
	v_pk_add_f32 v[34:35], v[34:35], v[36:37]
	global_load_dwordx4 v[58:61], v[132:133], off offset:2048
	global_load_dwordx4 v[54:57], v[132:133], off offset:3072
	v_add_f32_e32 v34, v34, v35
	ds_bpermute_b32 v35, v1, v34
	s_waitcnt lgkmcnt(0)
	v_add_f32_e32 v34, v34, v35
	ds_bpermute_b32 v35, v206, v34
	s_waitcnt lgkmcnt(0)
	v_add_f32_e32 v34, v34, v35
	ds_bpermute_b32 v35, v207, v34
	s_waitcnt lgkmcnt(0)
	v_add_f32_e32 v34, v34, v35
	ds_bpermute_b32 v35, v208, v34
	s_waitcnt lgkmcnt(0)
	v_add_f32_e32 v34, v34, v35
	ds_bpermute_b32 v35, v209, v34
	s_waitcnt lgkmcnt(0)
	v_add_f32_e32 v34, v34, v35
	ds_bpermute_b32 v35, v210, v34
	s_waitcnt lgkmcnt(0)
	v_add_f32_e32 v34, v34, v35
	v_fmamk_f32 v34, v34, 0x3a000000, v211
	v_mul_f32_e32 v35, 0x4f800000, v34
	v_cmp_gt_f32_e32 vcc, s21, v34
	s_nop 1
	v_cndmask_b32_e32 v34, v34, v35, vcc
	v_sqrt_f32_e32 v35, v34
	s_nop 0
	v_add_u32_e32 v36, -1, v35
	v_fma_f32 v37, -v36, v35, v34
	v_cmp_ge_f32_e64 s[0:1], 0, v37
	v_add_u32_e32 v37, 1, v35
	s_nop 0
	v_cndmask_b32_e64 v36, v35, v36, s[0:1]
	v_fma_f32 v35, -v37, v35, v34
	v_cmp_lt_f32_e64 s[0:1], 0, v35
	s_nop 1
	v_cndmask_b32_e64 v35, v36, v37, s[0:1]
	v_mul_f32_e32 v36, 0x37800000, v35
	v_cndmask_b32_e32 v35, v35, v36, vcc
	v_cmp_class_f32_e32 vcc, v34, v212
	s_nop 1
	v_cndmask_b32_e32 v194, v35, v34, vcc
	global_load_dwordx4 v[50:53], v[134:135], off
	global_load_dwordx4 v[42:45], v[136:137], off
	global_load_dwordx4 v[38:41], v[138:139], off
	global_load_dwordx4 v[34:37], v[140:141], off
	v_div_scale_f32 v196, s[0:1], v194, v194, 1.0
	v_rcp_f32_e32 v213, v196
	s_nop 0
	v_fma_f32 v226, -v196, v213, 1.0
	v_fmac_f32_e32 v213, v226, v213
	v_div_scale_f32 v226, vcc, 1.0, v194, 1.0
	v_mul_f32_e32 v228, v226, v213
	v_fma_f32 v236, -v196, v228, v226
	v_fmac_f32_e32 v228, v236, v213
	v_fma_f32 v196, -v196, v228, v226
	v_div_fmas_f32 v196, v196, v213, v228
	v_div_fixup_f32 v196, v196, v194, 1.0
	v_pk_mul_f32 v[214:215], v[196:197], v[214:215] op_sel_hi:[0,1]
	s_waitcnt vmcnt(7)
	v_pk_fma_f32 v[126:127], v[46:47], v[214:215], v[126:127]
	v_pk_mul_f32 v[216:217], v[196:197], v[216:217] op_sel_hi:[0,1]
	v_bfe_u32 v194, v126, 16, 1
	v_add3_u32 v194, v126, v194, s22
	v_bfe_u32 v213, v127, 16, 1
	v_pk_fma_f32 v[128:129], v[48:49], v[216:217], v[128:129]
	v_lshrrev_b32_e32 v194, 16, v194
	v_add3_u32 v213, v127, v213, s22
	v_and_or_b32 v214, v213, s20, v194
	v_bfe_u32 v194, v128, 16, 1
	v_add3_u32 v194, v128, v194, s22
	v_bfe_u32 v213, v129, 16, 1
	v_lshrrev_b32_e32 v194, 16, v194
	v_add3_u32 v213, v129, v213, s22
	v_add_co_u32_e32 v216, vcc, s23, v158
	v_and_or_b32 v215, v213, s20, v194
	s_nop 0
	v_addc_co_u32_e32 v217, vcc, -1, v159, vcc
	global_store_dwordx2 v[216:217], v[214:215], off offset:-3584
	v_mov_b32_e32 v214, v218
	v_mov_b32_e32 v215, v220
	v_mul_f32_e32 v194, v127, v127
	v_mul_f32_e32 v213, v129, v129
	v_pk_mul_f32 v[214:215], v[196:197], v[214:215] op_sel_hi:[0,1]
	v_fmac_f32_e32 v194, v126, v126
	v_fmac_f32_e32 v213, v128, v128
	s_waitcnt vmcnt(7)
	v_pk_fma_f32 v[122:123], v[62:63], v[214:215], v[122:123]
	v_add_f32_e32 v194, v194, v213
	v_mov_b32_e32 v220, v219
	v_bfe_u32 v213, v122, 16, 1
	v_pk_mul_f32 v[218:219], v[196:197], v[220:221] op_sel_hi:[0,1]
	v_add3_u32 v213, v122, v213, s22
	v_bfe_u32 v214, v123, 16, 1
	v_pk_fma_f32 v[124:125], v[64:65], v[218:219], v[124:125]
	v_lshrrev_b32_e32 v213, 16, v213
	v_add3_u32 v214, v123, v214, s22
	v_and_or_b32 v214, v214, s20, v213
	v_bfe_u32 v213, v124, 16, 1
	v_add3_u32 v213, v124, v213, s22
	v_bfe_u32 v215, v125, 16, 1
	v_lshrrev_b32_e32 v213, 16, v213
	v_add3_u32 v215, v125, v215, s22
	v_and_or_b32 v215, v215, s20, v213
	global_store_dwordx2 v[216:217], v[214:215], off offset:-3072
	v_mul_f32_e32 v213, v123, v123
	v_mul_f32_e32 v214, v125, v125
	v_fmac_f32_e32 v213, v122, v122
	v_fmac_f32_e32 v214, v124, v124
	v_add_f32_e32 v213, v213, v214
	v_pk_mul_f32 v[214:215], v[196:197], v[222:223] op_sel_hi:[0,1]
	s_waitcnt vmcnt(7)
	v_pk_fma_f32 v[118:119], v[58:59], v[214:215], v[118:119]
	v_add_f32_e32 v194, v194, v213
	v_bfe_u32 v213, v118, 16, 1
	v_pk_mul_f32 v[218:219], v[196:197], v[224:225] op_sel_hi:[0,1]
	v_add3_u32 v213, v118, v213, s22
	v_bfe_u32 v214, v119, 16, 1
	v_pk_fma_f32 v[120:121], v[60:61], v[218:219], v[120:121]
	v_lshrrev_b32_e32 v213, 16, v213
	v_add3_u32 v214, v119, v214, s22
	v_and_or_b32 v214, v214, s20, v213
	v_bfe_u32 v213, v120, 16, 1
	v_add3_u32 v213, v120, v213, s22
	v_bfe_u32 v215, v121, 16, 1
	v_lshrrev_b32_e32 v213, 16, v213
	v_add3_u32 v215, v121, v215, s22
	v_and_or_b32 v215, v215, s20, v213
	global_store_dwordx2 v[216:217], v[214:215], off offset:-2560
	v_mul_f32_e32 v213, v119, v119
	v_mul_f32_e32 v214, v121, v121
	v_fmac_f32_e32 v213, v118, v118
	v_fmac_f32_e32 v214, v120, v120
	v_mov_b32_e32 v228, v227
	v_add_f32_e32 v213, v213, v214
	v_pk_mul_f32 v[214:215], v[196:197], v[228:229] op_sel_hi:[0,1]
	s_waitcnt vmcnt(7)
	v_pk_fma_f32 v[114:115], v[54:55], v[214:215], v[114:115]
	v_add_f32_e32 v194, v213, v194
	v_bfe_u32 v213, v114, 16, 1
	v_pk_mul_f32 v[218:219], v[196:197], v[230:231] op_sel_hi:[0,1]
	v_add3_u32 v213, v114, v213, s22
	v_bfe_u32 v214, v115, 16, 1
	v_pk_fma_f32 v[116:117], v[56:57], v[218:219], v[116:117]
	v_lshrrev_b32_e32 v213, 16, v213
	v_add3_u32 v214, v115, v214, s22
	v_and_or_b32 v214, v214, s20, v213
	v_bfe_u32 v213, v116, 16, 1
	v_add3_u32 v213, v116, v213, s22
	v_bfe_u32 v215, v117, 16, 1
	v_lshrrev_b32_e32 v213, 16, v213
	v_add3_u32 v215, v117, v215, s22
	v_and_or_b32 v215, v215, s20, v213
	global_store_dwordx2 v[216:217], v[214:215], off offset:-2048
	v_mul_f32_e32 v213, v115, v115
	v_mul_f32_e32 v214, v117, v117
	v_fmac_f32_e32 v213, v114, v114
	v_fmac_f32_e32 v214, v116, v116
	v_add_f32_e32 v213, v213, v214
	v_mov_b32_e32 v214, v232
	v_mov_b32_e32 v215, v234
	v_pk_mul_f32 v[214:215], v[196:197], v[214:215] op_sel_hi:[0,1]
	s_waitcnt vmcnt(7)
	v_pk_fma_f32 v[110:111], v[50:51], v[214:215], v[110:111]
	v_add_f32_e32 v194, v213, v194
	v_mov_b32_e32 v234, v233
	v_bfe_u32 v213, v110, 16, 1
	v_pk_mul_f32 v[218:219], v[196:197], v[234:235] op_sel_hi:[0,1]
	v_add3_u32 v213, v110, v213, s22
	v_bfe_u32 v214, v111, 16, 1
	v_pk_fma_f32 v[112:113], v[52:53], v[218:219], v[112:113]
	v_lshrrev_b32_e32 v213, 16, v213
	v_add3_u32 v214, v111, v214, s22
	v_and_or_b32 v214, v214, s20, v213
	v_bfe_u32 v213, v112, 16, 1
	v_add3_u32 v213, v112, v213, s22
	v_bfe_u32 v215, v113, 16, 1
	v_lshrrev_b32_e32 v213, 16, v213
	v_add3_u32 v215, v113, v215, s22
	v_and_or_b32 v215, v215, s20, v213
	global_store_dwordx2 v[216:217], v[214:215], off offset:-1536
	v_mul_f32_e32 v213, v111, v111
	v_mul_f32_e32 v214, v113, v113
	v_fmac_f32_e32 v213, v110, v110
	v_fmac_f32_e32 v214, v112, v112
	v_add_f32_e32 v213, v213, v214
	v_mov_b32_e32 v214, v204
	v_mov_b32_e32 v215, v202
	v_pk_mul_f32 v[214:215], v[196:197], v[214:215] op_sel_hi:[0,1]
	v_mov_b32_e32 v202, v205
	v_pk_mul_f32 v[202:203], v[196:197], v[202:203] op_sel_hi:[0,1]
	s_waitcnt vmcnt(7)
	v_pk_fma_f32 v[106:107], v[42:43], v[214:215], v[106:107]
	v_pk_mul_f32 v[198:199], v[196:197], v[198:199] op_sel_hi:[0,1]
	v_pk_fma_f32 v[108:109], v[44:45], v[202:203], v[108:109]
	v_bfe_u32 v202, v106, 16, 1
	s_waitcnt vmcnt(6)
	v_pk_fma_f32 v[102:103], v[38:39], v[198:199], v[102:103]
	v_add3_u32 v202, v106, v202, s22
	v_bfe_u32 v203, v107, 16, 1
	v_bfe_u32 v198, v102, 16, 1
	v_lshrrev_b32_e32 v202, 16, v202
	v_add3_u32 v203, v107, v203, s22
	v_pk_mul_f32 v[200:201], v[196:197], v[200:201] op_sel_hi:[0,1]
	v_add3_u32 v198, v102, v198, s22
	v_bfe_u32 v199, v103, 16, 1
	v_and_or_b32 v202, v203, s20, v202
	v_bfe_u32 v203, v108, 16, 1
	v_pk_fma_f32 v[104:105], v[40:41], v[200:201], v[104:105]
	v_lshrrev_b32_e32 v198, 16, v198
	v_add3_u32 v199, v103, v199, s22
	v_add3_u32 v203, v108, v203, s22
	v_bfe_u32 v204, v109, 16, 1
	v_and_or_b32 v198, v199, s20, v198
	v_bfe_u32 v199, v104, 16, 1
	v_lshrrev_b32_e32 v203, 16, v203
	v_add3_u32 v204, v109, v204, s22
	v_add3_u32 v199, v104, v199, s22
	v_bfe_u32 v200, v105, 16, 1
	v_and_or_b32 v203, v204, s20, v203
	v_lshrrev_b32_e32 v199, 16, v199
	v_add3_u32 v200, v105, v200, s22
	global_store_dwordx2 v[216:217], v[202:203], off offset:-1024
	v_mul_f32_e32 v202, v107, v107
	v_mul_f32_e32 v203, v109, v109
	v_and_or_b32 v199, v200, s20, v199
	v_fmac_f32_e32 v202, v106, v106
	v_fmac_f32_e32 v203, v108, v108
	global_store_dwordx2 v[216:217], v[198:199], off offset:-512
	v_mul_f32_e32 v198, v103, v103
	v_mul_f32_e32 v199, v105, v105
	v_add_f32_e32 v194, v213, v194
	v_add_f32_e32 v202, v202, v203
	v_fmac_f32_e32 v198, v102, v102
	v_fmac_f32_e32 v199, v104, v104
	v_add_f32_e32 v194, v202, v194
	v_add_f32_e32 v198, v198, v199
	v_add_f32_e32 v198, v198, v194
	v_mov_b32_e32 v194, v197
	v_pk_mul_f32 v[194:195], v[196:197], v[194:195] op_sel_hi:[0,1]
	v_pk_mul_f32 v[192:193], v[196:197], v[192:193] op_sel_hi:[0,1]
	s_waitcnt vmcnt(7)
	v_pk_fma_f32 v[98:99], v[34:35], v[194:195], v[98:99]
	v_pk_fma_f32 v[100:101], v[36:37], v[192:193], v[100:101]
	v_bfe_u32 v192, v98, 16, 1
	v_add3_u32 v192, v98, v192, s22
	v_bfe_u32 v193, v99, 16, 1
	v_lshrrev_b32_e32 v192, 16, v192
	v_add3_u32 v193, v99, v193, s22
	v_and_or_b32 v192, v193, s20, v192
	v_bfe_u32 v193, v100, 16, 1
	v_add3_u32 v193, v100, v193, s22
	v_bfe_u32 v194, v101, 16, 1
	v_lshrrev_b32_e32 v193, 16, v193
	v_add3_u32 v194, v101, v194, s22
	v_and_or_b32 v193, v194, s20, v193
	global_store_dwordx2 v[216:217], v[192:193], off
	ds_read_b128 v[192:195], v253
	v_mul_f32_e32 v196, v99, v99
	v_mul_f32_e32 v197, v101, v101
	v_fmac_f32_e32 v196, v98, v98
	v_fmac_f32_e32 v197, v100, v100
	v_add_f32_e32 v196, v196, v197
	v_add_f32_e32 v196, v196, v198
	ds_bpermute_b32 v197, v1, v196
	s_waitcnt lgkmcnt(0)
	v_add_f32_e32 v196, v196, v197
	ds_bpermute_b32 v197, v206, v196
	s_waitcnt lgkmcnt(0)
	v_add_f32_e32 v196, v196, v197
	ds_bpermute_b32 v197, v207, v196
	s_waitcnt lgkmcnt(0)
	v_add_f32_e32 v196, v196, v197
	ds_bpermute_b32 v197, v208, v196
	s_waitcnt lgkmcnt(0)
	v_add_f32_e32 v196, v196, v197
	ds_bpermute_b32 v197, v209, v196
	s_waitcnt lgkmcnt(0)
	v_add_f32_e32 v196, v196, v197
	ds_bpermute_b32 v197, v210, v196
	s_waitcnt lgkmcnt(0)
	v_add_f32_e32 v196, v196, v197
	v_fmamk_f32 v196, v196, 0x3a000000, v211
	v_mul_f32_e32 v197, 0x4f800000, v196
	v_cmp_gt_f32_e32 vcc, s21, v196
	s_nop 1
	v_cndmask_b32_e32 v196, v196, v197, vcc
	v_sqrt_f32_e32 v197, v196
	s_nop 0
	v_add_u32_e32 v198, -1, v197
	v_fma_f32 v199, -v198, v197, v196
	v_cmp_ge_f32_e64 s[0:1], 0, v199
	v_add_u32_e32 v199, 1, v197
	s_nop 0
	v_cndmask_b32_e64 v198, v197, v198, s[0:1]
	v_fma_f32 v197, -v199, v197, v196
	v_cmp_lt_f32_e64 s[0:1], 0, v197
	s_nop 1
	v_cndmask_b32_e64 v197, v198, v199, s[0:1]
	v_mul_f32_e32 v198, 0x37800000, v197
	v_cndmask_b32_e32 v197, v197, v198, vcc
	v_cmp_class_f32_e32 vcc, v196, v212
	s_nop 1
	v_cndmask_b32_e32 v196, v197, v196, vcc
	v_div_scale_f32 v197, s[0:1], v196, v196, 1.0
	v_rcp_f32_e32 v198, v197
	s_nop 0
	v_fma_f32 v199, -v197, v198, 1.0
	v_fmac_f32_e32 v198, v199, v198
	v_div_scale_f32 v199, vcc, 1.0, v196, 1.0
	v_mul_f32_e32 v200, v199, v198
	v_fma_f32 v201, -v197, v200, v199
	v_fmac_f32_e32 v200, v201, v198
	v_fma_f32 v197, -v197, v200, v199
	v_div_fmas_f32 v197, v197, v198, v200
	v_div_fixup_f32 v196, v197, v196, 1.0
	v_mul_f32_e32 v126, v126, v196
	s_waitcnt lgkmcnt(0)
	v_mul_f32_e32 v126, v192, v126
	v_mul_f32_e32 v127, v127, v196
	v_mul_f32_e32 v127, v193, v127
	v_bfe_u32 v192, v126, 16, 1
	v_add3_u32 v126, v126, v192, s22
	v_bfe_u32 v192, v127, 16, 1
	v_lshrrev_b32_e32 v126, 16, v126
	v_add3_u32 v127, v127, v192, s22
	v_and_or_b32 v126, v127, s20, v126
	v_mul_f32_e32 v127, v128, v196
	v_mul_f32_e32 v127, v194, v127
	v_mul_f32_e32 v128, v129, v196
	v_mul_f32_e32 v128, v195, v128
	v_bfe_u32 v129, v127, 16, 1
	v_add3_u32 v127, v127, v129, s22
	v_bfe_u32 v129, v128, 16, 1
	v_lshrrev_b32_e32 v127, 16, v127
	v_add3_u32 v128, v128, v129, s22
	v_and_or_b32 v127, v128, s20, v127
	global_store_dwordx2 v[158:159], v[126:127], off offset:-3584
	ds_read_b128 v[126:129], v253 offset:1024
	v_mul_f32_e32 v122, v122, v196
	v_mul_f32_e32 v123, v123, v196
	v_mul_f32_e32 v118, v118, v196
	v_mul_f32_e32 v119, v119, v196
	v_mul_f32_e32 v114, v114, v196
	v_mul_f32_e32 v115, v115, v196
	v_mul_f32_e32 v110, v110, v196
	v_mul_f32_e32 v112, v112, v196
	v_mul_f32_e32 v111, v111, v196
	v_mul_f32_e32 v113, v113, v196
	v_mul_f32_e32 v106, v106, v196
	v_mul_f32_e32 v108, v108, v196
	v_mul_f32_e32 v107, v107, v196
	v_mul_f32_e32 v109, v109, v196
	v_mul_f32_e32 v102, v102, v196
	v_mul_f32_e32 v104, v104, v196
	v_mul_f32_e32 v103, v103, v196
	v_mul_f32_e32 v105, v105, v196
	v_mul_f32_e32 v98, v98, v196
	v_mul_f32_e32 v100, v100, v196
	v_mul_f32_e32 v99, v99, v196
	v_mul_f32_e32 v101, v101, v196
	s_andn2_b64 vcc, exec, s[14:15]
	s_waitcnt lgkmcnt(0)
	v_mul_f32_e32 v122, v126, v122
	v_mul_f32_e32 v123, v127, v123
	v_bfe_u32 v126, v122, 16, 1
	v_add3_u32 v122, v122, v126, s22
	v_bfe_u32 v126, v123, 16, 1
	v_lshrrev_b32_e32 v122, 16, v122
	v_add3_u32 v123, v123, v126, s22
	v_and_or_b32 v122, v123, s20, v122
	v_mul_f32_e32 v123, v124, v196
	v_mul_f32_e32 v123, v128, v123
	v_mul_f32_e32 v124, v125, v196
	v_mul_f32_e32 v124, v129, v124
	v_bfe_u32 v125, v123, 16, 1
	v_add3_u32 v123, v123, v125, s22
	v_bfe_u32 v125, v124, 16, 1
	v_lshrrev_b32_e32 v123, 16, v123
	v_add3_u32 v124, v124, v125, s22
	v_and_or_b32 v123, v124, s20, v123
	global_store_dwordx2 v[158:159], v[122:123], off offset:-3072
	ds_read_b128 v[122:125], v253 offset:2048
	s_waitcnt lgkmcnt(0)
	v_mul_f32_e32 v118, v122, v118
	v_mul_f32_e32 v119, v123, v119
	v_bfe_u32 v122, v118, 16, 1
	v_add3_u32 v118, v118, v122, s22
	v_bfe_u32 v122, v119, 16, 1
	v_lshrrev_b32_e32 v118, 16, v118
	v_add3_u32 v119, v119, v122, s22
	v_and_or_b32 v118, v119, s20, v118
	v_mul_f32_e32 v119, v120, v196
	v_mul_f32_e32 v119, v124, v119
	v_mul_f32_e32 v120, v121, v196
	v_mul_f32_e32 v120, v125, v120
	v_bfe_u32 v121, v119, 16, 1
	v_add3_u32 v119, v119, v121, s22
	v_bfe_u32 v121, v120, 16, 1
	v_lshrrev_b32_e32 v119, 16, v119
	v_add3_u32 v120, v120, v121, s22
	v_and_or_b32 v119, v120, s20, v119
	global_store_dwordx2 v[158:159], v[118:119], off offset:-2560
	ds_read_b128 v[118:121], v253 offset:3072
	s_waitcnt lgkmcnt(0)
	v_mul_f32_e32 v114, v118, v114
	v_mul_f32_e32 v115, v119, v115
	v_bfe_u32 v118, v114, 16, 1
	v_add3_u32 v114, v114, v118, s22
	v_bfe_u32 v118, v115, 16, 1
	v_lshrrev_b32_e32 v114, 16, v114
	v_add3_u32 v115, v115, v118, s22
	v_and_or_b32 v114, v115, s20, v114
	v_mul_f32_e32 v115, v116, v196
	v_mul_f32_e32 v115, v120, v115
	v_mul_f32_e32 v116, v117, v196
	v_mul_f32_e32 v116, v121, v116
	v_bfe_u32 v117, v115, 16, 1
	v_add3_u32 v115, v115, v117, s22
	v_bfe_u32 v117, v116, 16, 1
	v_lshrrev_b32_e32 v115, 16, v115
	v_add3_u32 v116, v116, v117, s22
	v_and_or_b32 v115, v116, s20, v115
	global_store_dwordx2 v[158:159], v[114:115], off offset:-2048
	ds_read_b128 v[114:117], v253 offset:4096
	s_waitcnt lgkmcnt(0)
	v_mul_f32_e32 v110, v114, v110
	v_mul_f32_e32 v112, v116, v112
	v_mul_f32_e32 v111, v115, v111
	v_mul_f32_e32 v113, v117, v113
	v_bfe_u32 v114, v110, 16, 1
	v_bfe_u32 v116, v112, 16, 1
	v_bfe_u32 v115, v111, 16, 1
	v_bfe_u32 v117, v113, 16, 1
	v_add3_u32 v110, v110, v114, s22
	v_add3_u32 v112, v112, v116, s22
	v_add3_u32 v111, v111, v115, s22
	v_add3_u32 v113, v113, v117, s22
	v_lshrrev_b32_e32 v110, 16, v110
	v_lshrrev_b32_e32 v112, 16, v112
	v_and_or_b32 v110, v111, s20, v110
	v_and_or_b32 v111, v113, s20, v112
	global_store_dwordx2 v[158:159], v[110:111], off offset:-1536
	ds_read_b128 v[110:113], v253 offset:5120
	s_waitcnt lgkmcnt(0)
	v_mul_f32_e32 v106, v110, v106
	v_mul_f32_e32 v108, v112, v108
	v_mul_f32_e32 v107, v111, v107
	v_mul_f32_e32 v109, v113, v109
	v_bfe_u32 v110, v106, 16, 1
	v_bfe_u32 v112, v108, 16, 1
	v_bfe_u32 v111, v107, 16, 1
	v_bfe_u32 v113, v109, 16, 1
	v_add3_u32 v106, v106, v110, s22
	v_add3_u32 v108, v108, v112, s22
	v_add3_u32 v107, v107, v111, s22
	v_add3_u32 v109, v109, v113, s22
	v_lshrrev_b32_e32 v106, 16, v106
	v_lshrrev_b32_e32 v108, 16, v108
	v_and_or_b32 v106, v107, s20, v106
	v_and_or_b32 v107, v109, s20, v108
	global_store_dwordx2 v[158:159], v[106:107], off offset:-1024
	ds_read_b128 v[106:109], v253 offset:6144
	s_waitcnt lgkmcnt(0)
	v_mul_f32_e32 v102, v106, v102
	v_mul_f32_e32 v104, v108, v104
	v_mul_f32_e32 v103, v107, v103
	v_mul_f32_e32 v105, v109, v105
	v_bfe_u32 v106, v102, 16, 1
	v_bfe_u32 v108, v104, 16, 1
	v_bfe_u32 v107, v103, 16, 1
	v_bfe_u32 v109, v105, 16, 1
	v_add3_u32 v102, v102, v106, s22
	v_add3_u32 v104, v104, v108, s22
	v_add3_u32 v103, v103, v107, s22
	v_add3_u32 v105, v105, v109, s22
	v_lshrrev_b32_e32 v102, 16, v102
	v_lshrrev_b32_e32 v104, 16, v104
	v_and_or_b32 v102, v103, s20, v102
	v_and_or_b32 v103, v105, s20, v104
	global_store_dwordx2 v[158:159], v[102:103], off offset:-512
	ds_read_b128 v[102:105], v253 offset:7168
	s_waitcnt lgkmcnt(0)
	v_mul_f32_e32 v98, v102, v98
	v_mul_f32_e32 v100, v104, v100
	v_mul_f32_e32 v99, v103, v99
	v_mul_f32_e32 v101, v105, v101
	v_bfe_u32 v102, v98, 16, 1
	v_bfe_u32 v104, v100, 16, 1
	v_bfe_u32 v103, v99, 16, 1
	v_bfe_u32 v105, v101, 16, 1
	v_add3_u32 v98, v98, v102, s22
	v_add3_u32 v100, v100, v104, s22
	v_add3_u32 v99, v99, v103, s22
	v_add3_u32 v101, v101, v105, s22
	v_lshrrev_b32_e32 v98, 16, v98
	v_lshrrev_b32_e32 v100, 16, v100
	v_and_or_b32 v98, v99, s20, v98
	v_and_or_b32 v99, v101, s20, v100
	global_store_dwordx2 v[158:159], v[98:99], off
	s_cbranch_vccnz .LBB0_1065
	v_and_b32_e32 v119, 0xffff0000, v190
	v_and_b32_e32 v118, 0xffff0000, v188
	v_and_b32_e32 v123, 0xffff0000, v191
	v_and_b32_e32 v122, 0xffff0000, v189
	v_lshlrev_b32_e32 v117, 16, v190
	v_lshlrev_b32_e32 v116, 16, v188
	v_lshlrev_b32_e32 v121, 16, v191
	v_lshlrev_b32_e32 v120, 16, v189
	v_pk_mul_f32 v[98:99], v[118:119], v[118:119]
	v_pk_mul_f32 v[100:101], v[122:123], v[122:123]
	v_pk_fma_f32 v[98:99], v[116:117], v[116:117], v[98:99]
	v_pk_fma_f32 v[100:101], v[120:121], v[120:121], v[100:101]
	v_and_b32_e32 v127, 0xffff0000, v187
	v_pk_add_f32 v[98:99], v[98:99], v[100:101]
	v_and_b32_e32 v126, 0xffff0000, v186
	v_pk_add_f32 v[98:99], v[98:99], v[98:99] op_sel_hi:[0,1]
	v_lshlrev_b32_e32 v125, 16, v187
	v_lshlrev_b32_e32 v124, 16, v186
	v_pk_mul_f32 v[100:101], v[126:127], v[126:127]
	v_lshlrev_b32_e32 v128, 16, v184
	v_and_b32_e32 v129, 0xffff0000, v184
	v_lshlrev_b32_e32 v184, 16, v185
	v_lshlrev_b32_e32 v112, 16, v182
	v_pk_fma_f32 v[100:101], v[124:125], v[124:125], v[100:101]
	v_and_b32_e32 v185, 0xffff0000, v185
	v_mul_f32_e32 v113, v128, v128
	v_mul_f32_e32 v103, v129, v129
	v_mul_f32_e32 v98, v184, v184
	v_mov_b32_e32 v102, v112
	v_pk_add_f32 v[100:101], v[100:101], v[100:101] op_sel_hi:[0,1]
	v_pk_fma_f32 v[104:105], v[184:185], v[184:185], v[98:99] op_sel_hi:[1,1,0]
	v_and_b32_e32 v186, 0xffff0000, v182
	v_lshlrev_b32_e32 v114, 16, v183
	v_and_b32_e32 v115, 0xffff0000, v183
	v_pk_add_f32 v[102:103], v[112:113], v[102:103]
	v_mul_f32_e32 v104, v186, v186
	v_mul_f32_e32 v100, v114, v114
	v_mul_f32_e32 v98, v115, v115
	v_mul_f32_e32 v106, v112, v112
	v_mov_b32_e32 v107, v103
	v_pk_add_f32 v[102:103], v[106:107], v[104:105]
	v_pk_add_f32 v[98:99], v[100:101], v[98:99]
	v_and_b32_e32 v109, 0xffff0000, v181
	v_pk_add_f32 v[98:99], v[102:103], v[98:99]
	v_and_b32_e32 v108, 0xffff0000, v180
	v_pk_add_f32 v[106:107], v[98:99], v[98:99] op_sel_hi:[0,1]
	v_lshlrev_b32_e32 v111, 16, v181
	v_lshlrev_b32_e32 v110, 16, v180
	v_pk_mul_f32 v[98:99], v[108:109], v[108:109]
	v_lshlrev_b32_e32 v102, 16, v178
	v_pk_fma_f32 v[98:99], v[110:111], v[110:111], v[98:99]
	v_lshlrev_b32_e32 v104, 16, v179
	v_pk_add_f32 v[180:181], v[98:99], v[98:99] op_sel_hi:[0,1]
	v_and_b32_e32 v105, 0xffff0000, v179
	v_mul_f32_e32 v99, v102, v102
	v_mul_f32_e32 v98, v104, v104
	v_and_b32_e32 v103, 0xffff0000, v178
	v_pk_fma_f32 v[182:183], v[104:105], v[104:105], v[98:99] op_sel_hi:[1,1,0]
	v_lshlrev_b32_e32 v98, 16, v176
	v_mul_f32_e32 v179, v103, v103
	v_mov_b32_e32 v178, v98
	v_and_b32_e32 v187, 0xffff0000, v176
	v_lshlrev_b32_e32 v100, 16, v177
	v_and_b32_e32 v101, 0xffff0000, v177
	v_pk_add_f32 v[178:179], v[98:99], v[178:179]
	v_mul_f32_e32 v182, v187, v187
	v_mul_f32_e32 v180, v100, v100
	v_mul_f32_e32 v106, v101, v101
	v_mul_f32_e32 v176, v98, v98
	v_mov_b32_e32 v177, v179
	v_pk_add_f32 v[176:177], v[176:177], v[182:183]
	v_pk_add_f32 v[106:107], v[180:181], v[106:107]
	v_mov_b32_e32 v180, v121
	v_pk_add_f32 v[106:107], v[176:177], v[106:107]
	v_mov_b32_e32 v181, v123
	v_add_f32_e32 v99, v106, v107
	ds_bpermute_b32 v106, v1, v99
	v_mov_b32_e32 v121, v122
	s_ashr_i32 s13, s12, 31
	s_lshl_b64 s[12:13], s[12:13], 12
	s_waitcnt lgkmcnt(0)
	v_add_f32_e32 v99, v99, v106
	ds_bpermute_b32 v106, v206, v99
	s_waitcnt lgkmcnt(0)
	v_add_f32_e32 v99, v99, v106
	ds_bpermute_b32 v106, v207, v99
	s_waitcnt lgkmcnt(0)
	v_add_f32_e32 v99, v99, v106
	ds_bpermute_b32 v106, v208, v99
	s_waitcnt lgkmcnt(0)
	v_add_f32_e32 v99, v99, v106
	ds_bpermute_b32 v106, v209, v99
	s_waitcnt lgkmcnt(0)
	v_add_f32_e32 v99, v99, v106
	ds_bpermute_b32 v106, v210, v99
	s_waitcnt lgkmcnt(0)
	v_add_f32_e32 v99, v99, v106
	v_fmamk_f32 v99, v99, 0x3a000000, v211
	v_mul_f32_e32 v106, 0x4f800000, v99
	v_cmp_gt_f32_e32 vcc, s21, v99
	s_nop 1
	v_cndmask_b32_e32 v99, v99, v106, vcc
	v_sqrt_f32_e32 v106, v99
	s_nop 0
	v_add_u32_e32 v107, -1, v106
	v_fma_f32 v113, -v107, v106, v99
	v_cmp_ge_f32_e64 s[0:1], 0, v113
	v_add_u32_e32 v113, 1, v106
	s_nop 0
	v_cndmask_b32_e64 v107, v106, v107, s[0:1]
	v_fma_f32 v106, -v113, v106, v99
	v_cmp_lt_f32_e64 s[0:1], 0, v106
	s_nop 1
	v_cndmask_b32_e64 v106, v107, v113, s[0:1]
	v_mul_f32_e32 v107, 0x37800000, v106
	v_cndmask_b32_e32 v106, v106, v107, vcc
	v_cmp_class_f32_e32 vcc, v99, v212
	s_nop 1
	v_cndmask_b32_e32 v99, v106, v99, vcc
	v_div_scale_f32 v113, s[0:1], v99, v99, 1.0
	v_rcp_f32_e32 v176, v113
	v_lshl_add_u64 v[106:107], v[154:155], 0, s[12:13]
	v_fma_f32 v177, -v113, v176, 1.0
	v_fmac_f32_e32 v176, v177, v176
	v_div_scale_f32 v177, vcc, 1.0, v99, 1.0
	v_mul_f32_e32 v178, v177, v176
	v_fma_f32 v179, -v113, v178, v177
	v_fmac_f32_e32 v178, v179, v176
	v_fma_f32 v113, -v113, v178, v177
	v_div_fmas_f32 v113, v113, v176, v178
	v_div_fixup_f32 v176, v113, v99, 1.0
	v_mov_b32_e32 v178, v117
	v_mov_b32_e32 v179, v119
	v_pk_mul_f32 v[178:179], v[176:177], v[178:179] op_sel_hi:[0,1]
	v_pk_fma_f32 v[94:95], v[46:47], v[178:179], v[94:95]
	v_pk_mul_f32 v[180:181], v[176:177], v[180:181] op_sel_hi:[0,1]
	v_bfe_u32 v99, v94, 16, 1
	v_add3_u32 v99, v94, v99, s22
	v_bfe_u32 v113, v95, 16, 1
	v_pk_fma_f32 v[96:97], v[48:49], v[180:181], v[96:97]
	v_lshrrev_b32_e32 v99, 16, v99
	v_add3_u32 v113, v95, v113, s22
	v_and_or_b32 v178, v113, s20, v99
	v_bfe_u32 v99, v96, 16, 1
	v_add3_u32 v99, v96, v99, s22
	v_bfe_u32 v113, v97, 16, 1
	v_lshrrev_b32_e32 v99, 16, v99
	v_add3_u32 v113, v97, v113, s22
	v_mov_b32_e32 v117, v118
	v_and_or_b32 v179, v113, s20, v99
	v_mul_f32_e32 v99, v95, v95
	v_mul_f32_e32 v113, v97, v97
	v_pk_mul_f32 v[116:117], v[176:177], v[116:117] op_sel_hi:[0,1]
	v_fmac_f32_e32 v99, v94, v94
	v_fmac_f32_e32 v113, v96, v96
	v_pk_fma_f32 v[90:91], v[62:63], v[116:117], v[90:91]
	v_add_f32_e32 v99, v99, v113
	v_bfe_u32 v113, v90, 16, 1
	v_pk_mul_f32 v[118:119], v[176:177], v[120:121] op_sel_hi:[0,1]
	v_add3_u32 v113, v90, v113, s22
	v_bfe_u32 v116, v91, 16, 1
	v_pk_fma_f32 v[92:93], v[64:65], v[118:119], v[92:93]
	v_lshrrev_b32_e32 v113, 16, v113
	v_add3_u32 v116, v91, v116, s22
	v_and_or_b32 v116, v116, s20, v113
	v_bfe_u32 v113, v92, 16, 1
	v_add3_u32 v113, v92, v113, s22
	v_bfe_u32 v117, v93, 16, 1
	v_lshrrev_b32_e32 v113, 16, v113
	v_add3_u32 v117, v93, v117, s22
	v_and_or_b32 v117, v117, s20, v113
	global_store_dwordx2 v[106:107], v[116:117], off offset:512
	v_mul_f32_e32 v113, v91, v91
	v_mul_f32_e32 v116, v93, v93
	v_fmac_f32_e32 v113, v90, v90
	v_fmac_f32_e32 v116, v92, v92
	v_add_f32_e32 v113, v113, v116
	v_mov_b32_e32 v116, v124
	v_mov_b32_e32 v117, v126
	v_pk_mul_f32 v[116:117], v[176:177], v[116:117] op_sel_hi:[0,1]
	v_pk_fma_f32 v[86:87], v[58:59], v[116:117], v[86:87]
	v_add_f32_e32 v99, v99, v113
	v_mov_b32_e32 v126, v125
	v_bfe_u32 v113, v86, 16, 1
	v_pk_mul_f32 v[118:119], v[176:177], v[126:127] op_sel_hi:[0,1]
	v_add3_u32 v113, v86, v113, s22
	v_bfe_u32 v116, v87, 16, 1
	v_pk_fma_f32 v[88:89], v[60:61], v[118:119], v[88:89]
	v_lshrrev_b32_e32 v113, 16, v113
	v_add3_u32 v116, v87, v116, s22
	v_and_or_b32 v116, v116, s20, v113
	v_bfe_u32 v113, v88, 16, 1
	v_add3_u32 v113, v88, v113, s22
	v_bfe_u32 v117, v89, 16, 1
	v_lshrrev_b32_e32 v113, 16, v113
	v_add3_u32 v117, v89, v117, s22
	v_and_or_b32 v117, v117, s20, v113
	global_store_dwordx2 v[106:107], v[116:117], off offset:1024
	v_mul_f32_e32 v113, v87, v87
	v_mul_f32_e32 v116, v89, v89
	v_fmac_f32_e32 v113, v86, v86
	v_fmac_f32_e32 v116, v88, v88
	v_add_f32_e32 v113, v113, v116
	v_pk_mul_f32 v[116:117], v[176:177], v[128:129] op_sel_hi:[0,1]
	v_pk_fma_f32 v[82:83], v[54:55], v[116:117], v[82:83]
	v_add_f32_e32 v99, v113, v99
	v_bfe_u32 v113, v82, 16, 1
	v_pk_mul_f32 v[118:119], v[176:177], v[184:185] op_sel_hi:[0,1]
	v_add3_u32 v113, v82, v113, s22
	v_bfe_u32 v116, v83, 16, 1
	v_pk_fma_f32 v[84:85], v[56:57], v[118:119], v[84:85]
	v_lshrrev_b32_e32 v113, 16, v113
	v_add3_u32 v116, v83, v116, s22
	v_and_or_b32 v116, v116, s20, v113
	v_bfe_u32 v113, v84, 16, 1
	v_add3_u32 v113, v84, v113, s22
	v_bfe_u32 v117, v85, 16, 1
	v_lshrrev_b32_e32 v113, 16, v113
	v_add3_u32 v117, v85, v117, s22
	v_and_or_b32 v117, v117, s20, v113
	global_store_dwordx2 v[106:107], v[116:117], off offset:1536
	v_mul_f32_e32 v113, v83, v83
	v_mul_f32_e32 v116, v85, v85
	v_fmac_f32_e32 v113, v82, v82
	v_fmac_f32_e32 v116, v84, v84
	v_add_f32_e32 v113, v113, v116
	v_add_f32_e32 v99, v113, v99
	v_mov_b32_e32 v113, v186
	v_pk_mul_f32 v[112:113], v[176:177], v[112:113] op_sel_hi:[0,1]
	v_pk_fma_f32 v[78:79], v[50:51], v[112:113], v[78:79]
	v_pk_mul_f32 v[114:115], v[176:177], v[114:115] op_sel_hi:[0,1]
	v_bfe_u32 v112, v78, 16, 1
	v_add3_u32 v112, v78, v112, s22
	v_bfe_u32 v113, v79, 16, 1
	v_pk_fma_f32 v[80:81], v[52:53], v[114:115], v[80:81]
	v_lshrrev_b32_e32 v112, 16, v112
	v_add3_u32 v113, v79, v113, s22
	v_and_or_b32 v112, v113, s20, v112
	v_bfe_u32 v113, v80, 16, 1
	v_add3_u32 v113, v80, v113, s22
	v_bfe_u32 v114, v81, 16, 1
	v_lshrrev_b32_e32 v113, 16, v113
	v_add3_u32 v114, v81, v114, s22
	v_and_or_b32 v113, v114, s20, v113
	global_store_dwordx2 v[106:107], v[112:113], off offset:2048
	v_mul_f32_e32 v112, v79, v79
	v_mul_f32_e32 v113, v81, v81
	v_fmac_f32_e32 v112, v78, v78
	v_fmac_f32_e32 v113, v80, v80
	v_add_f32_e32 v112, v112, v113
	v_add_f32_e32 v99, v112, v99
	v_mov_b32_e32 v112, v110
	v_mov_b32_e32 v113, v108
	v_pk_mul_f32 v[112:113], v[176:177], v[112:113] op_sel_hi:[0,1]
	v_mov_b32_e32 v108, v111
	v_pk_mul_f32 v[108:109], v[176:177], v[108:109] op_sel_hi:[0,1]
	v_pk_fma_f32 v[74:75], v[42:43], v[112:113], v[74:75]
	v_pk_mul_f32 v[102:103], v[176:177], v[102:103] op_sel_hi:[0,1]
	v_pk_fma_f32 v[76:77], v[44:45], v[108:109], v[76:77]
	v_bfe_u32 v108, v74, 16, 1
	v_pk_fma_f32 v[70:71], v[38:39], v[102:103], v[70:71]
	v_add3_u32 v108, v74, v108, s22
	v_bfe_u32 v109, v75, 16, 1
	v_bfe_u32 v102, v70, 16, 1
	v_lshrrev_b32_e32 v108, 16, v108
	v_add3_u32 v109, v75, v109, s22
	v_pk_mul_f32 v[104:105], v[176:177], v[104:105] op_sel_hi:[0,1]
	v_add3_u32 v102, v70, v102, s22
	v_bfe_u32 v103, v71, 16, 1
	v_and_or_b32 v108, v109, s20, v108
	v_bfe_u32 v109, v76, 16, 1
	v_pk_fma_f32 v[72:73], v[40:41], v[104:105], v[72:73]
	v_lshrrev_b32_e32 v102, 16, v102
	v_add3_u32 v103, v71, v103, s22
	v_add3_u32 v109, v76, v109, s22
	v_bfe_u32 v110, v77, 16, 1
	v_and_or_b32 v102, v103, s20, v102
	v_bfe_u32 v103, v72, 16, 1
	v_lshrrev_b32_e32 v109, 16, v109
	v_add3_u32 v110, v77, v110, s22
	v_add3_u32 v103, v72, v103, s22
	v_bfe_u32 v104, v73, 16, 1
	v_and_or_b32 v109, v110, s20, v109
	v_lshrrev_b32_e32 v103, 16, v103
	v_add3_u32 v104, v73, v104, s22
	global_store_dwordx2 v[106:107], v[108:109], off offset:2560
	v_mul_f32_e32 v108, v75, v75
	v_mul_f32_e32 v109, v77, v77
	v_and_or_b32 v103, v104, s20, v103
	v_fmac_f32_e32 v108, v74, v74
	v_fmac_f32_e32 v109, v76, v76
	global_store_dwordx2 v[106:107], v[102:103], off offset:3072
	v_mul_f32_e32 v102, v71, v71
	v_mul_f32_e32 v103, v73, v73
	v_add_f32_e32 v108, v108, v109
	v_fmac_f32_e32 v102, v70, v70
	v_fmac_f32_e32 v103, v72, v72
	v_add_f32_e32 v99, v108, v99
	v_add_f32_e32 v102, v102, v103
	v_add_f32_e32 v102, v102, v99
	v_mov_b32_e32 v99, v187
	v_pk_mul_f32 v[98:99], v[176:177], v[98:99] op_sel_hi:[0,1]
	v_pk_fma_f32 v[66:67], v[34:35], v[98:99], v[66:67]
	v_pk_mul_f32 v[100:101], v[176:177], v[100:101] op_sel_hi:[0,1]
	v_bfe_u32 v98, v66, 16, 1
	v_add3_u32 v98, v66, v98, s22
	v_bfe_u32 v99, v67, 16, 1
	v_pk_fma_f32 v[68:69], v[36:37], v[100:101], v[68:69]
	v_lshrrev_b32_e32 v98, 16, v98
	v_add3_u32 v99, v67, v99, s22
	v_and_or_b32 v98, v99, s20, v98
	v_bfe_u32 v99, v68, 16, 1
	v_add3_u32 v99, v68, v99, s22
	v_bfe_u32 v100, v69, 16, 1
	v_lshrrev_b32_e32 v99, 16, v99
	v_add3_u32 v100, v69, v100, s22
	v_and_or_b32 v99, v100, s20, v99
	global_store_dwordx2 v[106:107], v[178:179], off
	global_store_dwordx2 v[106:107], v[98:99], off offset:3584
	ds_read_b128 v[98:101], v253
	v_mul_f32_e32 v103, v67, v67
	v_mul_f32_e32 v104, v69, v69
	v_fmac_f32_e32 v103, v66, v66
	v_fmac_f32_e32 v104, v68, v68
	v_add_f32_e32 v103, v103, v104
	v_add_f32_e32 v102, v103, v102
	ds_bpermute_b32 v103, v1, v102
	s_waitcnt lgkmcnt(0)
	v_add_f32_e32 v102, v102, v103
	ds_bpermute_b32 v103, v206, v102
	s_waitcnt lgkmcnt(0)
	v_add_f32_e32 v102, v102, v103
	ds_bpermute_b32 v103, v207, v102
	s_waitcnt lgkmcnt(0)
	v_add_f32_e32 v102, v102, v103
	ds_bpermute_b32 v103, v208, v102
	s_waitcnt lgkmcnt(0)
	v_add_f32_e32 v102, v102, v103
	ds_bpermute_b32 v103, v209, v102
	s_waitcnt lgkmcnt(0)
	v_add_f32_e32 v102, v102, v103
	ds_bpermute_b32 v103, v210, v102
	s_waitcnt lgkmcnt(0)
	v_add_f32_e32 v102, v102, v103
	v_fmamk_f32 v102, v102, 0x3a000000, v211
	v_mul_f32_e32 v103, 0x4f800000, v102
	v_cmp_gt_f32_e32 vcc, s21, v102
	s_nop 1
	v_cndmask_b32_e32 v102, v102, v103, vcc
	v_sqrt_f32_e32 v103, v102
	s_nop 0
	v_add_u32_e32 v104, -1, v103
	v_fma_f32 v105, -v104, v103, v102
	v_cmp_ge_f32_e64 s[0:1], 0, v105
	v_add_u32_e32 v105, 1, v103
	s_nop 0
	v_cndmask_b32_e64 v104, v103, v104, s[0:1]
	v_fma_f32 v103, -v105, v103, v102
	v_cmp_lt_f32_e64 s[0:1], 0, v103
	s_nop 1
	v_cndmask_b32_e64 v103, v104, v105, s[0:1]
	v_mul_f32_e32 v104, 0x37800000, v103
	v_cndmask_b32_e32 v103, v103, v104, vcc
	v_cmp_class_f32_e32 vcc, v102, v212
	s_nop 1
	v_cndmask_b32_e32 v104, v103, v102, vcc
	v_div_scale_f32 v105, s[0:1], v104, v104, 1.0
	v_rcp_f32_e32 v106, v105
	v_lshl_add_u64 v[102:103], v[156:157], 0, s[12:13]
	v_fma_f32 v107, -v105, v106, 1.0
	v_fmac_f32_e32 v106, v107, v106
	v_div_scale_f32 v107, vcc, 1.0, v104, 1.0
	v_mul_f32_e32 v108, v107, v106
	v_fma_f32 v109, -v105, v108, v107
	v_fmac_f32_e32 v108, v109, v106
	v_fma_f32 v105, -v105, v108, v107
	v_div_fmas_f32 v105, v105, v106, v108
	v_div_fixup_f32 v104, v105, v104, 1.0
	v_mul_f32_e32 v94, v94, v104
	s_waitcnt lgkmcnt(0)
	v_mul_f32_e32 v94, v98, v94
	v_mul_f32_e32 v95, v95, v104
	v_mul_f32_e32 v95, v99, v95
	v_bfe_u32 v98, v94, 16, 1
	v_add3_u32 v94, v94, v98, s22
	v_bfe_u32 v98, v95, 16, 1
	v_lshrrev_b32_e32 v94, 16, v94
	v_add3_u32 v95, v95, v98, s22
	v_and_or_b32 v94, v95, s20, v94
	v_mul_f32_e32 v95, v96, v104
	v_mul_f32_e32 v95, v100, v95
	v_mul_f32_e32 v96, v97, v104
	v_mul_f32_e32 v96, v101, v96
	v_bfe_u32 v97, v95, 16, 1
	v_add3_u32 v95, v95, v97, s22
	v_bfe_u32 v97, v96, 16, 1
	v_lshrrev_b32_e32 v95, 16, v95
	v_add3_u32 v96, v96, v97, s22
	v_and_or_b32 v95, v96, s20, v95
	global_store_dwordx2 v[102:103], v[94:95], off
	ds_read_b128 v[94:97], v253 offset:1024
	v_mul_f32_e32 v90, v90, v104
	v_mul_f32_e32 v91, v91, v104
	v_mul_f32_e32 v86, v86, v104
	v_mul_f32_e32 v87, v87, v104
	v_mul_f32_e32 v82, v82, v104
	v_mul_f32_e32 v83, v83, v104
	v_mul_f32_e32 v78, v78, v104
	v_mul_f32_e32 v80, v80, v104
	v_mul_f32_e32 v79, v79, v104
	v_mul_f32_e32 v81, v81, v104
	v_mul_f32_e32 v74, v74, v104
	v_mul_f32_e32 v76, v76, v104
	v_mul_f32_e32 v75, v75, v104
	v_mul_f32_e32 v77, v77, v104
	v_mul_f32_e32 v70, v70, v104
	v_mul_f32_e32 v72, v72, v104
	v_mul_f32_e32 v71, v71, v104
	v_mul_f32_e32 v73, v73, v104
	v_mul_f32_e32 v66, v66, v104
	v_mul_f32_e32 v68, v68, v104
	v_mul_f32_e32 v67, v67, v104
	v_mul_f32_e32 v69, v69, v104
	s_waitcnt lgkmcnt(0)
	v_mul_f32_e32 v90, v94, v90
	v_mul_f32_e32 v91, v95, v91
	v_bfe_u32 v94, v90, 16, 1
	v_add3_u32 v90, v90, v94, s22
	v_bfe_u32 v94, v91, 16, 1
	v_lshrrev_b32_e32 v90, 16, v90
	v_add3_u32 v91, v91, v94, s22
	v_and_or_b32 v90, v91, s20, v90
	v_mul_f32_e32 v91, v92, v104
	v_mul_f32_e32 v91, v96, v91
	v_mul_f32_e32 v92, v93, v104
	v_mul_f32_e32 v92, v97, v92
	v_bfe_u32 v93, v91, 16, 1
	v_add3_u32 v91, v91, v93, s22
	v_bfe_u32 v93, v92, 16, 1
	v_lshrrev_b32_e32 v91, 16, v91
	v_add3_u32 v92, v92, v93, s22
	v_and_or_b32 v91, v92, s20, v91
	global_store_dwordx2 v[102:103], v[90:91], off offset:512
	ds_read_b128 v[90:93], v253 offset:2048
	s_waitcnt lgkmcnt(0)
	v_mul_f32_e32 v86, v90, v86
	v_mul_f32_e32 v87, v91, v87
	v_bfe_u32 v90, v86, 16, 1
	v_add3_u32 v86, v86, v90, s22
	v_bfe_u32 v90, v87, 16, 1
	v_lshrrev_b32_e32 v86, 16, v86
	v_add3_u32 v87, v87, v90, s22
	v_and_or_b32 v86, v87, s20, v86
	v_mul_f32_e32 v87, v88, v104
	v_mul_f32_e32 v87, v92, v87
	v_mul_f32_e32 v88, v89, v104
	v_mul_f32_e32 v88, v93, v88
	v_bfe_u32 v89, v87, 16, 1
	v_add3_u32 v87, v87, v89, s22
	v_bfe_u32 v89, v88, 16, 1
	v_lshrrev_b32_e32 v87, 16, v87
	v_add3_u32 v88, v88, v89, s22
	v_and_or_b32 v87, v88, s20, v87
	global_store_dwordx2 v[102:103], v[86:87], off offset:1024
	ds_read_b128 v[86:89], v253 offset:3072
	s_waitcnt lgkmcnt(0)
	v_mul_f32_e32 v82, v86, v82
	v_mul_f32_e32 v83, v87, v83
	v_bfe_u32 v86, v82, 16, 1
	v_add3_u32 v82, v82, v86, s22
	v_bfe_u32 v86, v83, 16, 1
	v_lshrrev_b32_e32 v82, 16, v82
	v_add3_u32 v83, v83, v86, s22
	v_and_or_b32 v82, v83, s20, v82
	v_mul_f32_e32 v83, v84, v104
	v_mul_f32_e32 v83, v88, v83
	v_mul_f32_e32 v84, v85, v104
	v_mul_f32_e32 v84, v89, v84
	v_bfe_u32 v85, v83, 16, 1
	v_add3_u32 v83, v83, v85, s22
	v_bfe_u32 v85, v84, 16, 1
	v_lshrrev_b32_e32 v83, 16, v83
	v_add3_u32 v84, v84, v85, s22
	v_and_or_b32 v83, v84, s20, v83
	global_store_dwordx2 v[102:103], v[82:83], off offset:1536
	ds_read_b128 v[82:85], v253 offset:4096
	s_waitcnt lgkmcnt(0)
	v_mul_f32_e32 v78, v82, v78
	v_mul_f32_e32 v80, v84, v80
	v_mul_f32_e32 v79, v83, v79
	v_mul_f32_e32 v81, v85, v81
	v_bfe_u32 v82, v78, 16, 1
	v_bfe_u32 v84, v80, 16, 1
	v_bfe_u32 v83, v79, 16, 1
	v_bfe_u32 v85, v81, 16, 1
	v_add3_u32 v78, v78, v82, s22
	v_add3_u32 v80, v80, v84, s22
	v_add3_u32 v79, v79, v83, s22
	v_add3_u32 v81, v81, v85, s22
	v_lshrrev_b32_e32 v78, 16, v78
	v_lshrrev_b32_e32 v80, 16, v80
	v_and_or_b32 v78, v79, s20, v78
	v_and_or_b32 v79, v81, s20, v80
	global_store_dwordx2 v[102:103], v[78:79], off offset:2048
	ds_read_b128 v[78:81], v253 offset:5120
	s_waitcnt lgkmcnt(0)
	v_mul_f32_e32 v74, v78, v74
	v_mul_f32_e32 v76, v80, v76
	v_mul_f32_e32 v75, v79, v75
	v_mul_f32_e32 v77, v81, v77
	v_bfe_u32 v78, v74, 16, 1
	v_bfe_u32 v80, v76, 16, 1
	v_bfe_u32 v79, v75, 16, 1
	v_bfe_u32 v81, v77, 16, 1
	v_add3_u32 v74, v74, v78, s22
	v_add3_u32 v76, v76, v80, s22
	v_add3_u32 v75, v75, v79, s22
	v_add3_u32 v77, v77, v81, s22
	v_lshrrev_b32_e32 v74, 16, v74
	v_lshrrev_b32_e32 v76, 16, v76
	v_and_or_b32 v74, v75, s20, v74
	v_and_or_b32 v75, v77, s20, v76
	global_store_dwordx2 v[102:103], v[74:75], off offset:2560
	ds_read_b128 v[74:77], v253 offset:6144
	s_waitcnt lgkmcnt(0)
	v_mul_f32_e32 v70, v74, v70
	v_mul_f32_e32 v72, v76, v72
	v_mul_f32_e32 v71, v75, v71
	v_mul_f32_e32 v73, v77, v73
	v_bfe_u32 v74, v70, 16, 1
	v_bfe_u32 v76, v72, 16, 1
	v_bfe_u32 v75, v71, 16, 1
	v_bfe_u32 v77, v73, 16, 1
	v_add3_u32 v70, v70, v74, s22
	v_add3_u32 v72, v72, v76, s22
	v_add3_u32 v71, v71, v75, s22
	v_add3_u32 v73, v73, v77, s22
	v_lshrrev_b32_e32 v70, 16, v70
	v_lshrrev_b32_e32 v72, 16, v72
	v_and_or_b32 v70, v71, s20, v70
	v_and_or_b32 v71, v73, s20, v72
	global_store_dwordx2 v[102:103], v[70:71], off offset:3072
	ds_read_b128 v[70:73], v253 offset:7168
	s_waitcnt lgkmcnt(0)
	v_mul_f32_e32 v66, v70, v66
	v_mul_f32_e32 v68, v72, v68
	v_mul_f32_e32 v67, v71, v67
	v_mul_f32_e32 v69, v73, v69
	v_bfe_u32 v70, v66, 16, 1
	v_bfe_u32 v72, v68, 16, 1
	v_bfe_u32 v71, v67, 16, 1
	v_bfe_u32 v73, v69, 16, 1
	v_add3_u32 v66, v66, v70, s22
	v_add3_u32 v68, v68, v72, s22
	v_add3_u32 v67, v67, v71, s22
	v_add3_u32 v69, v69, v73, s22
	v_lshrrev_b32_e32 v66, 16, v66
	v_lshrrev_b32_e32 v68, 16, v68
	v_and_or_b32 v66, v67, s20, v66
	v_and_or_b32 v67, v69, s20, v68
	global_store_dwordx2 v[102:103], v[66:67], off offset:3584
.LBB0_1065:
	s_andn2_b64 vcc, exec, s[10:11]
	s_cbranch_vccnz .LBB0_1058
	v_and_b32_e32 v83, 0xffff0000, v172
	v_and_b32_e32 v85, 0xffff0000, v173
	v_lshlrev_b32_e32 v82, 16, v172
	v_lshlrev_b32_e32 v84, 16, v173
	v_mul_f32_e32 v66, v85, v85
	v_and_b32_e32 v89, 0xffff0000, v175
	v_and_b32_e32 v88, 0xffff0000, v174
	v_mul_f32_e32 v70, v83, v83
	v_pk_fma_f32 v[66:67], v[84:85], v[84:85], v[66:67] op_sel_hi:[1,1,0]
	v_lshlrev_b32_e32 v87, 16, v175
	v_lshlrev_b32_e32 v86, 16, v174
	v_pk_mul_f32 v[68:69], v[88:89], v[88:89]
	v_lshlrev_b32_e32 v95, 16, v164
	v_pk_fma_f32 v[70:71], v[82:83], v[82:83], v[70:71] op_sel_hi:[1,1,0]
	v_pk_fma_f32 v[68:69], v[86:87], v[86:87], v[68:69]
	v_and_b32_e32 v97, 0xffff0000, v164
	v_mov_b32_e32 v94, v70
	v_mov_b32_e32 v72, v66
	v_mov_b32_e32 v73, v95
	v_mul_f32_e32 v74, v97, v97
	v_pk_add_f32 v[66:67], v[70:71], v[66:67]
	v_pk_mul_f32 v[70:71], v[94:95], v[72:73]
	v_pk_add_f32 v[68:69], v[68:69], v[68:69] op_sel:[0,1] op_sel_hi:[1,0]
	v_and_b32_e32 v91, 0xffff0000, v166
	v_and_b32_e32 v93, 0xffff0000, v167
	v_mov_b32_e32 v67, v71
	v_mov_b32_e32 v69, v74
	v_lshlrev_b32_e32 v90, 16, v166
	v_lshlrev_b32_e32 v92, 16, v167
	v_lshlrev_b32_e32 v98, 16, v165
	v_and_b32_e32 v99, 0xffff0000, v165
	v_pk_add_f32 v[66:67], v[66:67], v[68:69]
	v_mul_f32_e32 v68, v91, v91
	v_mul_f32_e32 v70, v93, v93
	v_mul_f32_e32 v75, v98, v98
	v_mul_f32_e32 v76, v99, v99
	v_pk_fma_f32 v[68:69], v[90:91], v[90:91], v[68:69] op_sel_hi:[1,1,0]
	v_pk_fma_f32 v[70:71], v[92:93], v[92:93], v[70:71] op_sel_hi:[1,1,0]
	v_mov_b32_e32 v69, v75
	v_mov_b32_e32 v71, v76
	v_pk_add_f32 v[68:69], v[68:69], v[70:71]
	v_and_b32_e32 v103, 0xffff0000, v171
	v_and_b32_e32 v102, 0xffff0000, v170
	v_pk_add_f32 v[76:77], v[66:67], v[68:69]
	v_lshlrev_b32_e32 v101, 16, v171
	v_lshlrev_b32_e32 v100, 16, v170
	v_pk_mul_f32 v[66:67], v[102:103], v[102:103]
	v_and_b32_e32 v79, 0xffff0000, v169
	v_pk_fma_f32 v[66:67], v[100:101], v[100:101], v[66:67]
	v_and_b32_e32 v78, 0xffff0000, v168
	v_pk_add_f32 v[104:105], v[66:67], v[66:67] op_sel:[0,1] op_sel_hi:[1,0]
	v_lshlrev_b32_e32 v71, 16, v160
	v_pk_add_f32 v[76:77], v[76:77], v[76:77] op_sel:[0,1] op_sel_hi:[1,0]
	v_lshlrev_b32_e32 v81, 16, v169
	v_lshlrev_b32_e32 v80, 16, v168
	v_pk_mul_f32 v[66:67], v[78:79], v[78:79]
	v_mov_b32_e32 v70, v76
	v_mov_b32_e32 v108, v104
	v_mov_b32_e32 v109, v71
	v_pk_fma_f32 v[106:107], v[80:81], v[80:81], v[66:67]
	v_and_b32_e32 v69, 0xffff0000, v160
	v_pk_add_f32 v[76:77], v[76:77], v[104:105]
	v_pk_mul_f32 v[104:105], v[70:71], v[108:109]
	v_and_b32_e32 v73, 0xffff0000, v162
	v_mul_f32_e32 v68, v69, v69
	v_mov_b32_e32 v77, v105
	v_pk_add_f32 v[104:105], v[106:107], v[106:107] op_sel:[0,1] op_sel_hi:[1,0]
	v_lshlrev_b32_e32 v72, 16, v162
	v_and_b32_e32 v75, 0xffff0000, v163
	v_mov_b32_e32 v105, v68
	v_mul_f32_e32 v68, v73, v73
	v_lshlrev_b32_e32 v74, 16, v163
	v_lshlrev_b32_e32 v66, 16, v161
	v_and_b32_e32 v67, 0xffff0000, v161
	v_pk_add_f32 v[76:77], v[76:77], v[104:105]
	v_pk_fma_f32 v[104:105], v[72:73], v[72:73], v[68:69] op_sel_hi:[1,1,0]
	v_mul_f32_e32 v68, v75, v75
	v_mul_f32_e32 v94, v66, v66
	v_mul_f32_e32 v96, v67, v67
	v_pk_fma_f32 v[106:107], v[74:75], v[74:75], v[68:69] op_sel_hi:[1,1,0]
	v_mov_b32_e32 v105, v94
	v_mov_b32_e32 v107, v96
	v_pk_add_f32 v[104:105], v[104:105], v[106:107]
	s_ashr_i32 s7, s6, 31
	v_pk_add_f32 v[76:77], v[76:77], v[104:105]
	s_lshl_b64 s[6:7], s[6:7], 12
	v_add_f32_e32 v68, v76, v77
	ds_bpermute_b32 v70, v1, v68
	s_waitcnt lgkmcnt(0)
	v_add_f32_e32 v68, v68, v70
	ds_bpermute_b32 v70, v206, v68
	s_waitcnt lgkmcnt(0)
	v_add_f32_e32 v68, v68, v70
	ds_bpermute_b32 v70, v207, v68
	s_waitcnt lgkmcnt(0)
	v_add_f32_e32 v68, v68, v70
	ds_bpermute_b32 v70, v208, v68
	s_waitcnt lgkmcnt(0)
	v_add_f32_e32 v68, v68, v70
	ds_bpermute_b32 v70, v209, v68
	s_waitcnt lgkmcnt(0)
	v_add_f32_e32 v68, v68, v70
	ds_bpermute_b32 v70, v210, v68
	s_waitcnt lgkmcnt(0)
	v_add_f32_e32 v68, v68, v70
	v_fmamk_f32 v68, v68, 0x3a000000, v211
	v_mul_f32_e32 v70, 0x4f800000, v68
	v_cmp_gt_f32_e32 vcc, s21, v68
	s_nop 1
	v_cndmask_b32_e32 v68, v68, v70, vcc
	v_sqrt_f32_e32 v70, v68
	s_nop 0
	v_add_u32_e32 v76, -1, v70
	v_fma_f32 v77, -v76, v70, v68
	v_cmp_ge_f32_e64 s[0:1], 0, v77
	v_add_u32_e32 v77, 1, v70
	s_nop 0
	v_cndmask_b32_e64 v76, v70, v76, s[0:1]
	v_fma_f32 v70, -v77, v70, v68
	v_cmp_lt_f32_e64 s[0:1], 0, v70
	s_nop 1
	v_cndmask_b32_e64 v70, v76, v77, s[0:1]
	v_mul_f32_e32 v76, 0x37800000, v70
	v_cndmask_b32_e32 v70, v70, v76, vcc
	v_cmp_class_f32_e32 vcc, v68, v212
	v_lshl_add_u64 v[76:77], v[154:155], 0, s[6:7]
	s_nop 0
	v_cndmask_b32_e32 v68, v70, v68, vcc
	v_div_scale_f32 v70, s[0:1], v68, v68, 1.0
	v_rcp_f32_e32 v94, v70
	s_nop 0
	v_fma_f32 v96, -v70, v94, 1.0
	v_fmac_f32_e32 v94, v96, v94
	v_div_scale_f32 v96, vcc, 1.0, v68, 1.0
	v_mul_f32_e32 v104, v96, v94
	v_fma_f32 v105, -v70, v104, v96
	v_fmac_f32_e32 v104, v105, v94
	v_fma_f32 v70, -v70, v104, v96
	v_div_fmas_f32 v70, v70, v94, v104
	v_div_fixup_f32 v70, v70, v68, 1.0
	v_pk_mul_f32 v[82:83], v[70:71], v[82:83] op_sel_hi:[0,1]
	v_pk_fma_f32 v[30:31], v[46:47], v[82:83], v[30:31]
	v_pk_mul_f32 v[84:85], v[70:71], v[84:85] op_sel_hi:[0,1]
	v_bfe_u32 v46, v30, 16, 1
	v_add3_u32 v46, v30, v46, s22
	v_bfe_u32 v47, v31, 16, 1
	v_pk_fma_f32 v[32:33], v[48:49], v[84:85], v[32:33]
	v_lshrrev_b32_e32 v46, 16, v46
	v_add3_u32 v47, v31, v47, s22
	v_and_or_b32 v46, v47, s20, v46
	v_bfe_u32 v47, v32, 16, 1
	v_add3_u32 v47, v32, v47, s22
	v_bfe_u32 v48, v33, 16, 1
	v_lshrrev_b32_e32 v47, 16, v47
	v_add3_u32 v48, v33, v48, s22
	v_and_or_b32 v47, v48, s20, v47
	global_store_dwordx2 v[76:77], v[46:47], off
	v_mul_f32_e32 v46, v31, v31
	v_mul_f32_e32 v47, v33, v33
	v_fmac_f32_e32 v46, v30, v30
	v_fmac_f32_e32 v47, v32, v32
	v_add_f32_e32 v68, v46, v47
	v_mov_b32_e32 v46, v86
	v_mov_b32_e32 v47, v88
	v_pk_mul_f32 v[46:47], v[70:71], v[46:47] op_sel_hi:[0,1]
	v_pk_fma_f32 v[26:27], v[62:63], v[46:47], v[26:27]
	v_mov_b32_e32 v88, v87
	v_bfe_u32 v46, v26, 16, 1
	v_pk_mul_f32 v[48:49], v[70:71], v[88:89] op_sel_hi:[0,1]
	v_add3_u32 v46, v26, v46, s22
	v_bfe_u32 v47, v27, 16, 1
	v_pk_fma_f32 v[28:29], v[64:65], v[48:49], v[28:29]
	v_lshrrev_b32_e32 v46, 16, v46
	v_add3_u32 v47, v27, v47, s22
	v_and_or_b32 v46, v47, s20, v46
	v_bfe_u32 v47, v28, 16, 1
	v_add3_u32 v47, v28, v47, s22
	v_bfe_u32 v48, v29, 16, 1
	v_lshrrev_b32_e32 v47, 16, v47
	v_add3_u32 v48, v29, v48, s22
	v_and_or_b32 v47, v48, s20, v47
	global_store_dwordx2 v[76:77], v[46:47], off offset:512
	v_mul_f32_e32 v46, v27, v27
	v_mul_f32_e32 v47, v29, v29
	v_fmac_f32_e32 v46, v26, v26
	v_fmac_f32_e32 v47, v28, v28
	v_add_f32_e32 v46, v46, v47
	v_add_f32_e32 v62, v68, v46
	v_pk_mul_f32 v[46:47], v[70:71], v[90:91] op_sel_hi:[0,1]
	v_pk_fma_f32 v[22:23], v[58:59], v[46:47], v[22:23]
	v_pk_mul_f32 v[48:49], v[70:71], v[92:93] op_sel_hi:[0,1]
	v_bfe_u32 v46, v22, 16, 1
	v_add3_u32 v46, v22, v46, s22
	v_bfe_u32 v47, v23, 16, 1
	v_pk_fma_f32 v[24:25], v[60:61], v[48:49], v[24:25]
	v_lshrrev_b32_e32 v46, 16, v46
	v_add3_u32 v47, v23, v47, s22
	v_and_or_b32 v46, v47, s20, v46
	v_bfe_u32 v47, v24, 16, 1
	v_add3_u32 v47, v24, v47, s22
	v_bfe_u32 v48, v25, 16, 1
	v_lshrrev_b32_e32 v47, 16, v47
	v_add3_u32 v48, v25, v48, s22
	v_and_or_b32 v47, v48, s20, v47
	global_store_dwordx2 v[76:77], v[46:47], off offset:1024
	v_mul_f32_e32 v46, v23, v23
	v_mul_f32_e32 v47, v25, v25
	v_fmac_f32_e32 v46, v22, v22
	v_fmac_f32_e32 v47, v24, v24
	v_add_f32_e32 v46, v46, v47
	v_mov_b32_e32 v96, v95
	v_add_f32_e32 v58, v46, v62
	v_pk_mul_f32 v[46:47], v[70:71], v[96:97] op_sel_hi:[0,1]
	v_pk_fma_f32 v[18:19], v[54:55], v[46:47], v[18:19]
	v_pk_mul_f32 v[48:49], v[70:71], v[98:99] op_sel_hi:[0,1]
	v_bfe_u32 v46, v18, 16, 1
	v_add3_u32 v46, v18, v46, s22
	v_bfe_u32 v47, v19, 16, 1
	v_pk_fma_f32 v[20:21], v[56:57], v[48:49], v[20:21]
	v_lshrrev_b32_e32 v46, 16, v46
	v_add3_u32 v47, v19, v47, s22
	v_and_or_b32 v46, v47, s20, v46
	v_bfe_u32 v47, v20, 16, 1
	v_add3_u32 v47, v20, v47, s22
	v_bfe_u32 v48, v21, 16, 1
	v_lshrrev_b32_e32 v47, 16, v47
	v_add3_u32 v48, v21, v48, s22
	v_and_or_b32 v47, v48, s20, v47
	global_store_dwordx2 v[76:77], v[46:47], off offset:1536
	v_mul_f32_e32 v46, v19, v19
	v_mul_f32_e32 v47, v21, v21
	v_fmac_f32_e32 v46, v18, v18
	v_fmac_f32_e32 v47, v20, v20
	v_add_f32_e32 v46, v46, v47
	v_add_f32_e32 v54, v46, v58
	v_mov_b32_e32 v46, v100
	v_mov_b32_e32 v47, v102
	v_pk_mul_f32 v[46:47], v[70:71], v[46:47] op_sel_hi:[0,1]
	v_pk_fma_f32 v[14:15], v[50:51], v[46:47], v[14:15]
	v_mov_b32_e32 v102, v101
	v_bfe_u32 v46, v14, 16, 1
	v_pk_mul_f32 v[48:49], v[70:71], v[102:103] op_sel_hi:[0,1]
	v_add3_u32 v46, v14, v46, s22
	v_bfe_u32 v47, v15, 16, 1
	v_pk_fma_f32 v[16:17], v[52:53], v[48:49], v[16:17]
	v_lshrrev_b32_e32 v46, 16, v46
	v_add3_u32 v47, v15, v47, s22
	v_and_or_b32 v46, v47, s20, v46
	v_bfe_u32 v47, v16, 16, 1
	v_add3_u32 v47, v16, v47, s22
	v_bfe_u32 v48, v17, 16, 1
	v_lshrrev_b32_e32 v47, 16, v47
	v_add3_u32 v48, v17, v48, s22
	v_and_or_b32 v47, v48, s20, v47
	global_store_dwordx2 v[76:77], v[46:47], off offset:2048
	v_mul_f32_e32 v46, v15, v15
	v_mul_f32_e32 v47, v17, v17
	v_fmac_f32_e32 v46, v14, v14
	v_fmac_f32_e32 v47, v16, v16
	v_add_f32_e32 v46, v46, v47
	v_add_f32_e32 v50, v46, v54
	v_mov_b32_e32 v46, v80
	v_mov_b32_e32 v47, v78
	v_pk_mul_f32 v[46:47], v[70:71], v[46:47] op_sel_hi:[0,1]
	v_pk_fma_f32 v[10:11], v[42:43], v[46:47], v[10:11]
	v_mov_b32_e32 v78, v81
	v_bfe_u32 v42, v10, 16, 1
	v_pk_mul_f32 v[48:49], v[70:71], v[78:79] op_sel_hi:[0,1]
	v_add3_u32 v42, v10, v42, s22
	v_bfe_u32 v43, v11, 16, 1
	v_pk_fma_f32 v[12:13], v[44:45], v[48:49], v[12:13]
	v_lshrrev_b32_e32 v42, 16, v42
	v_add3_u32 v43, v11, v43, s22
	v_and_or_b32 v42, v43, s20, v42
	v_bfe_u32 v43, v12, 16, 1
	v_add3_u32 v43, v12, v43, s22
	v_bfe_u32 v44, v13, 16, 1
	v_lshrrev_b32_e32 v43, 16, v43
	v_add3_u32 v44, v13, v44, s22
	v_and_or_b32 v43, v44, s20, v43
	global_store_dwordx2 v[76:77], v[42:43], off offset:2560
	v_mul_f32_e32 v42, v11, v11
	v_mul_f32_e32 v43, v13, v13
	v_fmac_f32_e32 v42, v10, v10
	v_fmac_f32_e32 v43, v12, v12
	v_add_f32_e32 v42, v42, v43
	v_add_f32_e32 v46, v42, v50
	v_pk_mul_f32 v[42:43], v[70:71], v[72:73] op_sel_hi:[0,1]
	v_pk_fma_f32 v[6:7], v[38:39], v[42:43], v[6:7]
	v_pk_mul_f32 v[44:45], v[70:71], v[74:75] op_sel_hi:[0,1]
	v_bfe_u32 v38, v6, 16, 1
	v_add3_u32 v38, v6, v38, s22
	v_bfe_u32 v39, v7, 16, 1
	v_pk_fma_f32 v[8:9], v[40:41], v[44:45], v[8:9]
	v_lshrrev_b32_e32 v38, 16, v38
	v_add3_u32 v39, v7, v39, s22
	v_and_or_b32 v38, v39, s20, v38
	v_bfe_u32 v39, v8, 16, 1
	v_add3_u32 v39, v8, v39, s22
	v_bfe_u32 v40, v9, 16, 1
	v_lshrrev_b32_e32 v39, 16, v39
	v_add3_u32 v40, v9, v40, s22
	v_and_or_b32 v39, v40, s20, v39
	global_store_dwordx2 v[76:77], v[38:39], off offset:3072
	v_mul_f32_e32 v38, v7, v7
	v_mul_f32_e32 v39, v9, v9
	v_fmac_f32_e32 v38, v6, v6
	v_fmac_f32_e32 v39, v8, v8
	v_add_f32_e32 v38, v38, v39
	v_mov_b32_e32 v68, v71
	v_add_f32_e32 v42, v38, v46
	v_pk_mul_f32 v[38:39], v[70:71], v[68:69] op_sel_hi:[0,1]
	v_pk_fma_f32 v[2:3], v[34:35], v[38:39], v[2:3]
	v_pk_mul_f32 v[40:41], v[70:71], v[66:67] op_sel_hi:[0,1]
	v_bfe_u32 v34, v2, 16, 1
	v_add3_u32 v34, v2, v34, s22
	v_bfe_u32 v35, v3, 16, 1
	v_pk_fma_f32 v[4:5], v[36:37], v[40:41], v[4:5]
	v_lshrrev_b32_e32 v34, 16, v34
	v_add3_u32 v35, v3, v35, s22
	v_and_or_b32 v34, v35, s20, v34
	v_bfe_u32 v35, v4, 16, 1
	v_add3_u32 v35, v4, v35, s22
	v_bfe_u32 v36, v5, 16, 1
	v_lshrrev_b32_e32 v35, 16, v35
	v_add3_u32 v36, v5, v36, s22
	v_and_or_b32 v35, v36, s20, v35
	global_store_dwordx2 v[76:77], v[34:35], off offset:3584
	ds_read_b128 v[34:37], v253
	v_mul_f32_e32 v38, v3, v3
	v_mul_f32_e32 v39, v5, v5
	v_fmac_f32_e32 v38, v2, v2
	v_fmac_f32_e32 v39, v4, v4
	v_add_f32_e32 v38, v38, v39
	v_add_f32_e32 v38, v38, v42
	ds_bpermute_b32 v39, v1, v38
	s_waitcnt lgkmcnt(0)
	v_add_f32_e32 v38, v38, v39
	ds_bpermute_b32 v39, v206, v38
	s_waitcnt lgkmcnt(0)
	v_add_f32_e32 v38, v38, v39
	ds_bpermute_b32 v39, v207, v38
	s_waitcnt lgkmcnt(0)
	v_add_f32_e32 v38, v38, v39
	ds_bpermute_b32 v39, v208, v38
	s_waitcnt lgkmcnt(0)
	v_add_f32_e32 v38, v38, v39
	ds_bpermute_b32 v39, v209, v38
	s_waitcnt lgkmcnt(0)
	v_add_f32_e32 v38, v38, v39
	ds_bpermute_b32 v39, v210, v38
	s_waitcnt lgkmcnt(0)
	v_add_f32_e32 v38, v38, v39
	v_fmamk_f32 v38, v38, 0x3a000000, v211
	v_mul_f32_e32 v39, 0x4f800000, v38
	v_cmp_gt_f32_e32 vcc, s21, v38
	s_nop 1
	v_cndmask_b32_e32 v38, v38, v39, vcc
	v_sqrt_f32_e32 v39, v38
	s_nop 0
	v_add_u32_e32 v40, -1, v39
	v_fma_f32 v41, -v40, v39, v38
	v_cmp_ge_f32_e64 s[0:1], 0, v41
	v_add_u32_e32 v41, 1, v39
	s_nop 0
	v_cndmask_b32_e64 v40, v39, v40, s[0:1]
	v_fma_f32 v39, -v41, v39, v38
	v_cmp_lt_f32_e64 s[0:1], 0, v39
	s_nop 1
	v_cndmask_b32_e64 v39, v40, v41, s[0:1]
	v_mul_f32_e32 v40, 0x37800000, v39
	v_cndmask_b32_e32 v39, v39, v40, vcc
	v_cmp_class_f32_e32 vcc, v38, v212
	s_nop 1
	v_cndmask_b32_e32 v40, v39, v38, vcc
	v_div_scale_f32 v41, s[0:1], v40, v40, 1.0
	v_rcp_f32_e32 v42, v41
	v_lshl_add_u64 v[38:39], v[156:157], 0, s[6:7]
	v_fma_f32 v43, -v41, v42, 1.0
	v_fmac_f32_e32 v42, v43, v42
	v_div_scale_f32 v43, vcc, 1.0, v40, 1.0
	v_mul_f32_e32 v44, v43, v42
	v_fma_f32 v45, -v41, v44, v43
	v_fmac_f32_e32 v44, v45, v42
	v_fma_f32 v41, -v41, v44, v43
	v_div_fmas_f32 v41, v41, v42, v44
	v_div_fixup_f32 v40, v41, v40, 1.0
	v_mul_f32_e32 v30, v30, v40
	s_waitcnt lgkmcnt(0)
	v_mul_f32_e32 v30, v34, v30
	v_mul_f32_e32 v31, v31, v40
	v_mul_f32_e32 v31, v35, v31
	v_bfe_u32 v34, v30, 16, 1
	v_add3_u32 v30, v30, v34, s22
	v_bfe_u32 v34, v31, 16, 1
	v_lshrrev_b32_e32 v30, 16, v30
	v_add3_u32 v31, v31, v34, s22
	v_and_or_b32 v30, v31, s20, v30
	v_mul_f32_e32 v31, v32, v40
	v_mul_f32_e32 v31, v36, v31
	v_mul_f32_e32 v32, v33, v40
	v_mul_f32_e32 v32, v37, v32
	v_bfe_u32 v33, v31, 16, 1
	v_add3_u32 v31, v31, v33, s22
	v_bfe_u32 v33, v32, 16, 1
	v_lshrrev_b32_e32 v31, 16, v31
	v_add3_u32 v32, v32, v33, s22
	v_and_or_b32 v31, v32, s20, v31
	global_store_dwordx2 v[38:39], v[30:31], off
	ds_read_b128 v[30:33], v253 offset:1024
	v_mul_f32_e32 v26, v26, v40
	v_mul_f32_e32 v27, v27, v40
	v_mul_f32_e32 v22, v22, v40
	v_mul_f32_e32 v23, v23, v40
	v_mul_f32_e32 v18, v18, v40
	v_mul_f32_e32 v19, v19, v40
	v_mul_f32_e32 v14, v14, v40
	v_mul_f32_e32 v16, v16, v40
	v_mul_f32_e32 v15, v15, v40
	v_mul_f32_e32 v17, v17, v40
	v_mul_f32_e32 v10, v10, v40
	v_mul_f32_e32 v12, v12, v40
	v_mul_f32_e32 v11, v11, v40
	v_mul_f32_e32 v13, v13, v40
	v_mul_f32_e32 v6, v6, v40
	v_mul_f32_e32 v8, v8, v40
	v_mul_f32_e32 v7, v7, v40
	v_mul_f32_e32 v9, v9, v40
	v_mul_f32_e32 v2, v2, v40
	v_mul_f32_e32 v4, v4, v40
	v_mul_f32_e32 v3, v3, v40
	v_mul_f32_e32 v5, v5, v40
	s_waitcnt lgkmcnt(0)
	v_mul_f32_e32 v26, v30, v26
	v_mul_f32_e32 v27, v31, v27
	v_bfe_u32 v30, v26, 16, 1
	v_add3_u32 v26, v26, v30, s22
	v_bfe_u32 v30, v27, 16, 1
	v_lshrrev_b32_e32 v26, 16, v26
	v_add3_u32 v27, v27, v30, s22
	v_and_or_b32 v26, v27, s20, v26
	v_mul_f32_e32 v27, v28, v40
	v_mul_f32_e32 v27, v32, v27
	v_mul_f32_e32 v28, v29, v40
	v_mul_f32_e32 v28, v33, v28
	v_bfe_u32 v29, v27, 16, 1
	v_add3_u32 v27, v27, v29, s22
	v_bfe_u32 v29, v28, 16, 1
	v_lshrrev_b32_e32 v27, 16, v27
	v_add3_u32 v28, v28, v29, s22
	v_and_or_b32 v27, v28, s20, v27
	global_store_dwordx2 v[38:39], v[26:27], off offset:512
	ds_read_b128 v[26:29], v253 offset:2048
	s_waitcnt lgkmcnt(0)
	v_mul_f32_e32 v22, v26, v22
	v_mul_f32_e32 v23, v27, v23
	v_bfe_u32 v26, v22, 16, 1
	v_add3_u32 v22, v22, v26, s22
	v_bfe_u32 v26, v23, 16, 1
	v_lshrrev_b32_e32 v22, 16, v22
	v_add3_u32 v23, v23, v26, s22
	v_and_or_b32 v22, v23, s20, v22
	v_mul_f32_e32 v23, v24, v40
	v_mul_f32_e32 v23, v28, v23
	v_mul_f32_e32 v24, v25, v40
	v_mul_f32_e32 v24, v29, v24
	v_bfe_u32 v25, v23, 16, 1
	v_add3_u32 v23, v23, v25, s22
	v_bfe_u32 v25, v24, 16, 1
	v_lshrrev_b32_e32 v23, 16, v23
	v_add3_u32 v24, v24, v25, s22
	v_and_or_b32 v23, v24, s20, v23
	global_store_dwordx2 v[38:39], v[22:23], off offset:1024
	ds_read_b128 v[22:25], v253 offset:3072
	s_waitcnt lgkmcnt(0)
	v_mul_f32_e32 v18, v22, v18
	v_mul_f32_e32 v19, v23, v19
	v_bfe_u32 v22, v18, 16, 1
	v_add3_u32 v18, v18, v22, s22
	v_bfe_u32 v22, v19, 16, 1
	v_lshrrev_b32_e32 v18, 16, v18
	v_add3_u32 v19, v19, v22, s22
	v_and_or_b32 v18, v19, s20, v18
	v_mul_f32_e32 v19, v20, v40
	v_mul_f32_e32 v19, v24, v19
	v_mul_f32_e32 v20, v21, v40
	v_mul_f32_e32 v20, v25, v20
	v_bfe_u32 v21, v19, 16, 1
	v_add3_u32 v19, v19, v21, s22
	v_bfe_u32 v21, v20, 16, 1
	v_lshrrev_b32_e32 v19, 16, v19
	v_add3_u32 v20, v20, v21, s22
	v_and_or_b32 v19, v20, s20, v19
	global_store_dwordx2 v[38:39], v[18:19], off offset:1536
	ds_read_b128 v[18:21], v253 offset:4096
	s_waitcnt lgkmcnt(0)
	v_mul_f32_e32 v14, v18, v14
	v_mul_f32_e32 v16, v20, v16
	v_mul_f32_e32 v15, v19, v15
	v_mul_f32_e32 v17, v21, v17
	v_bfe_u32 v18, v14, 16, 1
	v_bfe_u32 v20, v16, 16, 1
	v_bfe_u32 v19, v15, 16, 1
	v_bfe_u32 v21, v17, 16, 1
	v_add3_u32 v14, v14, v18, s22
	v_add3_u32 v16, v16, v20, s22
	v_add3_u32 v15, v15, v19, s22
	v_add3_u32 v17, v17, v21, s22
	v_lshrrev_b32_e32 v14, 16, v14
	v_lshrrev_b32_e32 v16, 16, v16
	v_and_or_b32 v14, v15, s20, v14
	v_and_or_b32 v15, v17, s20, v16
	global_store_dwordx2 v[38:39], v[14:15], off offset:2048
	ds_read_b128 v[14:17], v253 offset:5120
	s_waitcnt lgkmcnt(0)
	v_mul_f32_e32 v10, v14, v10
	v_mul_f32_e32 v12, v16, v12
	v_mul_f32_e32 v11, v15, v11
	v_mul_f32_e32 v13, v17, v13
	v_bfe_u32 v14, v10, 16, 1
	v_bfe_u32 v16, v12, 16, 1
	v_bfe_u32 v15, v11, 16, 1
	v_bfe_u32 v17, v13, 16, 1
	v_add3_u32 v10, v10, v14, s22
	v_add3_u32 v12, v12, v16, s22
	v_add3_u32 v11, v11, v15, s22
	v_add3_u32 v13, v13, v17, s22
	v_lshrrev_b32_e32 v10, 16, v10
	v_lshrrev_b32_e32 v12, 16, v12
	v_and_or_b32 v10, v11, s20, v10
	v_and_or_b32 v11, v13, s20, v12
	global_store_dwordx2 v[38:39], v[10:11], off offset:2560
	ds_read_b128 v[10:13], v253 offset:6144
	s_waitcnt lgkmcnt(0)
	v_mul_f32_e32 v6, v10, v6
	v_mul_f32_e32 v8, v12, v8
	v_mul_f32_e32 v7, v11, v7
	v_mul_f32_e32 v9, v13, v9
	v_bfe_u32 v10, v6, 16, 1
	v_bfe_u32 v12, v8, 16, 1
	v_bfe_u32 v11, v7, 16, 1
	v_bfe_u32 v13, v9, 16, 1
	v_add3_u32 v6, v6, v10, s22
	v_add3_u32 v8, v8, v12, s22
	v_add3_u32 v7, v7, v11, s22
	v_add3_u32 v9, v9, v13, s22
	v_lshrrev_b32_e32 v6, 16, v6
	v_lshrrev_b32_e32 v8, 16, v8
	v_and_or_b32 v6, v7, s20, v6
	v_and_or_b32 v7, v9, s20, v8
	global_store_dwordx2 v[38:39], v[6:7], off offset:3072
	ds_read_b128 v[6:9], v253 offset:7168
	s_waitcnt lgkmcnt(0)
	v_mul_f32_e32 v2, v6, v2
	v_mul_f32_e32 v4, v8, v4
	v_mul_f32_e32 v3, v7, v3
	v_mul_f32_e32 v5, v9, v5
	v_bfe_u32 v6, v2, 16, 1
	v_bfe_u32 v8, v4, 16, 1
	v_bfe_u32 v7, v3, 16, 1
	v_bfe_u32 v9, v5, 16, 1
	v_add3_u32 v2, v2, v6, s22
	v_add3_u32 v4, v4, v8, s22
	v_add3_u32 v3, v3, v7, s22
	v_add3_u32 v5, v5, v9, s22
	v_lshrrev_b32_e32 v2, 16, v2
	v_lshrrev_b32_e32 v4, 16, v4
	v_and_or_b32 v2, v3, s20, v2
	v_and_or_b32 v3, v5, s20, v4
	global_store_dwordx2 v[38:39], v[2:3], off offset:3584
	s_branch .LBB0_1058
